# K-loops: removed the compiler's redundant s_waitcnt lgkmcnt(0) at the head of each 32-MFMA block (28 sites; the asm lgkmcnt(0) before the barrier already drained LDS), on top of v23
# speedup vs baseline: 1.0136x; 1.0032x over previous
.LBB0_131:
	s_add_u32 s60, s57, 0xffffff80
	s_addc_u32 s61, s58, -1
	s_cmp_eq_u32 s59, 60
	s_cselect_b32 s36, s17, s57
	s_cselect_b32 s37, s7, s58
	s_cselect_b32 s39, s21, s56
	s_cselect_b32 s38, s33, s55
	s_add_u32 s30, s36, 0x80
	s_addc_u32 s31, s37, 0
	s_add_u32 s34, s38, 0x80
	s_addc_u32 s35, s39, 0
	s_add_i32 s62, 0, 0x10000
	s_add_i32 s63, 0, 0x14000
	v_add_u32_e32 v152, s62, v1
	v_add_u32_e32 v168, s63, v1
	ds_read_b128 v[140:143], v152
	ds_read_b128 v[144:147], v152 offset:1024
	ds_read_b128 v[148:151], v152 offset:2048
	ds_read_b128 v[152:155], v152 offset:3072
	ds_read_b128 v[156:159], v168
	ds_read_b128 v[160:163], v168 offset:1024
	ds_read_b128 v[164:167], v168 offset:2048
	ds_read_b128 v[168:171], v168 offset:3072
	s_add_u32 s60, s60, 0x100000
	s_addc_u32 s61, s61, 0
	v_lshl_add_u64 v[204:205], s[60:61], 0, v[2:3]
	s_add_i32 m0, s29, 0xc000
	ds_read_b128 v[172:175], v5
	ds_read_b128 v[176:179], v5 offset:1024
	ds_read_b128 v[180:183], v5 offset:2048
	ds_read_b128 v[184:187], v5 offset:3072
	ds_read_b128 v[188:191], v5 offset:4096
	ds_read_b128 v[192:195], v5 offset:5120
	ds_read_b128 v[196:199], v5 offset:6144
	ds_read_b128 v[200:203], v5 offset:7168
	global_load_lds_dwordx4 v[204:205], off
	v_lshl_add_u64 v[204:205], s[60:61], 0, v[136:137]
	s_add_i32 m0, s29, 0xe000
	s_nop 0
	global_load_lds_dwordx4 v[204:205], off
	s_waitcnt vmcnt(8)
	s_waitcnt lgkmcnt(0)
	s_barrier
	s_setprio 1
	v_mfma_f32_16x16x32_bf16 v[130:133], v[140:143], v[172:175], v[130:133]
	v_mfma_f32_16x16x32_bf16 v[126:129], v[148:151], v[172:175], v[126:129]
	v_mfma_f32_16x16x32_bf16 v[114:117], v[140:143], v[180:183], v[114:117]
	v_mfma_f32_16x16x32_bf16 v[110:113], v[148:151], v[180:183], v[110:113]
	v_mfma_f32_16x16x32_bf16 v[98:101], v[140:143], v[188:191], v[98:101]
	v_mfma_f32_16x16x32_bf16 v[94:97], v[148:151], v[188:191], v[94:97]
	v_mfma_f32_16x16x32_bf16 v[82:85], v[140:143], v[196:199], v[82:85]
	v_mfma_f32_16x16x32_bf16 v[78:81], v[148:151], v[196:199], v[78:81]
	v_mfma_f32_16x16x32_bf16 v[130:133], v[144:147], v[176:179], v[130:133]
	v_mfma_f32_16x16x32_bf16 v[126:129], v[152:155], v[176:179], v[126:129]
	v_mfma_f32_16x16x32_bf16 v[114:117], v[144:147], v[184:187], v[114:117]
	v_mfma_f32_16x16x32_bf16 v[110:113], v[152:155], v[184:187], v[110:113]
	v_mfma_f32_16x16x32_bf16 v[98:101], v[144:147], v[192:195], v[98:101]
	v_mfma_f32_16x16x32_bf16 v[94:97], v[152:155], v[192:195], v[94:97]
	v_mfma_f32_16x16x32_bf16 v[82:85], v[144:147], v[200:203], v[82:85]
	v_mfma_f32_16x16x32_bf16 v[78:81], v[152:155], v[200:203], v[78:81]
	s_setprio 0
	s_setprio 1
	v_mfma_f32_16x16x32_bf16 v[122:125], v[156:159], v[172:175], v[122:125]
	v_mfma_f32_16x16x32_bf16 v[118:121], v[164:167], v[172:175], v[118:121]
	v_mfma_f32_16x16x32_bf16 v[106:109], v[156:159], v[180:183], v[106:109]
	v_mfma_f32_16x16x32_bf16 v[102:105], v[164:167], v[180:183], v[102:105]
	v_mfma_f32_16x16x32_bf16 v[90:93], v[156:159], v[188:191], v[90:93]
	v_mfma_f32_16x16x32_bf16 v[86:89], v[164:167], v[188:191], v[86:89]
	v_mfma_f32_16x16x32_bf16 v[74:77], v[156:159], v[196:199], v[74:77]
	v_mfma_f32_16x16x32_bf16 v[70:73], v[164:167], v[196:199], v[70:73]
	v_mfma_f32_16x16x32_bf16 v[122:125], v[160:163], v[176:179], v[122:125]
	v_mfma_f32_16x16x32_bf16 v[118:121], v[168:171], v[176:179], v[118:121]
	v_mfma_f32_16x16x32_bf16 v[106:109], v[160:163], v[184:187], v[106:109]
	v_mfma_f32_16x16x32_bf16 v[102:105], v[168:171], v[184:187], v[102:105]
	v_mfma_f32_16x16x32_bf16 v[90:93], v[160:163], v[192:195], v[90:93]
	v_mfma_f32_16x16x32_bf16 v[86:89], v[168:171], v[192:195], v[86:89]
	v_mfma_f32_16x16x32_bf16 v[74:77], v[160:163], v[200:203], v[74:77]
	v_mfma_f32_16x16x32_bf16 v[70:73], v[168:171], v[200:203], v[70:73]
	s_setprio 0
	s_barrier
	s_add_i32 s60, s62, s42
	v_lshl_add_u64 v[204:205], s[38:39], 0, v[134:135]
	s_mov_b32 m0, s60
	ds_read_b128 v[172:175], v5 offset:16384
	ds_read_b128 v[176:179], v5 offset:17408
	ds_read_b128 v[180:183], v5 offset:18432
	ds_read_b128 v[184:187], v5 offset:19456
	ds_read_b128 v[188:191], v5 offset:20480
	ds_read_b128 v[192:195], v5 offset:21504
	ds_read_b128 v[196:199], v5 offset:22528
	ds_read_b128 v[200:203], v5 offset:23552
	global_load_lds_dwordx4 v[204:205], off
	s_add_i32 m0, s60, 0x2000
	v_lshl_add_u64 v[204:205], s[38:39], 0, v[138:139]
	s_add_u32 s38, s38, 0x100000
	s_addc_u32 s39, s39, 0
	s_add_i32 s60, s63, s42
	global_load_lds_dwordx4 v[204:205], off
	v_lshl_add_u64 v[204:205], s[38:39], 0, v[134:135]
	s_mov_b32 m0, s60
	s_nop 0
	global_load_lds_dwordx4 v[204:205], off
	v_lshl_add_u64 v[204:205], s[38:39], 0, v[138:139]
	s_add_i32 m0, s60, 0x2000
	s_nop 0
	global_load_lds_dwordx4 v[204:205], off
	v_lshl_add_u64 v[204:205], s[36:37], 0, v[2:3]
	s_mov_b32 m0, s29
	s_nop 0
	global_load_lds_dwordx4 v[204:205], off
	v_lshl_add_u64 v[204:205], s[36:37], 0, v[136:137]
	s_mov_b32 m0, s43
	s_nop 0
	global_load_lds_dwordx4 v[204:205], off
	s_waitcnt vmcnt(8)
	s_waitcnt lgkmcnt(0)
	s_barrier
	s_setprio 1
	v_mfma_f32_16x16x32_bf16 v[66:69], v[140:143], v[172:175], v[66:69]
	v_mfma_f32_16x16x32_bf16 v[62:65], v[148:151], v[172:175], v[62:65]
	v_mfma_f32_16x16x32_bf16 v[50:53], v[140:143], v[180:183], v[50:53]
	v_mfma_f32_16x16x32_bf16 v[46:49], v[148:151], v[180:183], v[46:49]
	v_mfma_f32_16x16x32_bf16 v[34:37], v[140:143], v[188:191], v[34:37]
	v_mfma_f32_16x16x32_bf16 v[30:33], v[148:151], v[188:191], v[30:33]
	v_mfma_f32_16x16x32_bf16 v[18:21], v[140:143], v[196:199], v[18:21]
	v_mfma_f32_16x16x32_bf16 v[14:17], v[148:151], v[196:199], v[14:17]
	v_mfma_f32_16x16x32_bf16 v[66:69], v[144:147], v[176:179], v[66:69]
	v_mfma_f32_16x16x32_bf16 v[62:65], v[152:155], v[176:179], v[62:65]
	v_mfma_f32_16x16x32_bf16 v[50:53], v[144:147], v[184:187], v[50:53]
	v_mfma_f32_16x16x32_bf16 v[46:49], v[152:155], v[184:187], v[46:49]
	v_mfma_f32_16x16x32_bf16 v[34:37], v[144:147], v[192:195], v[34:37]
	v_mfma_f32_16x16x32_bf16 v[30:33], v[152:155], v[192:195], v[30:33]
	v_mfma_f32_16x16x32_bf16 v[18:21], v[144:147], v[200:203], v[18:21]
	v_mfma_f32_16x16x32_bf16 v[14:17], v[152:155], v[200:203], v[14:17]
	s_setprio 0
	s_setprio 1
	v_mfma_f32_16x16x32_bf16 v[58:61], v[156:159], v[172:175], v[58:61]
	v_mfma_f32_16x16x32_bf16 v[54:57], v[164:167], v[172:175], v[54:57]
	v_mfma_f32_16x16x32_bf16 v[42:45], v[156:159], v[180:183], v[42:45]
	v_mfma_f32_16x16x32_bf16 v[38:41], v[164:167], v[180:183], v[38:41]
	v_mfma_f32_16x16x32_bf16 v[26:29], v[156:159], v[188:191], v[26:29]
	v_mfma_f32_16x16x32_bf16 v[22:25], v[164:167], v[188:191], v[22:25]
	v_mfma_f32_16x16x32_bf16 v[10:13], v[156:159], v[196:199], v[10:13]
	v_mfma_f32_16x16x32_bf16 v[6:9], v[164:167], v[196:199], v[6:9]
	v_mfma_f32_16x16x32_bf16 v[58:61], v[160:163], v[176:179], v[58:61]
	v_mfma_f32_16x16x32_bf16 v[54:57], v[168:171], v[176:179], v[54:57]
	v_mfma_f32_16x16x32_bf16 v[42:45], v[160:163], v[184:187], v[42:45]
	v_mfma_f32_16x16x32_bf16 v[38:41], v[168:171], v[184:187], v[38:41]
	v_mfma_f32_16x16x32_bf16 v[26:29], v[160:163], v[192:195], v[26:29]
	v_mfma_f32_16x16x32_bf16 v[22:25], v[168:171], v[192:195], v[22:25]
	v_mfma_f32_16x16x32_bf16 v[10:13], v[160:163], v[200:203], v[10:13]
	v_mfma_f32_16x16x32_bf16 v[6:9], v[168:171], v[200:203], v[6:9]
	s_setprio 0
	s_barrier
	s_add_i32 s38, 0, 0x18000
	s_add_i32 s39, 0, 0x1c000
	v_add_u32_e32 v152, s38, v1
	v_add_u32_e32 v168, s39, v1
	ds_read_b128 v[140:143], v152
	ds_read_b128 v[144:147], v152 offset:1024
	ds_read_b128 v[148:151], v152 offset:2048
	ds_read_b128 v[152:155], v152 offset:3072
	ds_read_b128 v[156:159], v168
	ds_read_b128 v[160:163], v168 offset:1024
	ds_read_b128 v[164:167], v168 offset:2048
	ds_read_b128 v[168:171], v168 offset:3072
	s_add_u32 s36, s36, 0x100000
	s_addc_u32 s37, s37, 0
	s_mov_b32 m0, s48
	v_lshl_add_u64 v[204:205], s[36:37], 0, v[2:3]
	ds_read_b128 v[172:175], v5 offset:32768
	ds_read_b128 v[176:179], v5 offset:33792
	ds_read_b128 v[180:183], v5 offset:34816
	ds_read_b128 v[184:187], v5 offset:35840
	ds_read_b128 v[188:191], v5 offset:36864
	ds_read_b128 v[192:195], v5 offset:37888
	ds_read_b128 v[196:199], v5 offset:38912
	ds_read_b128 v[200:203], v5 offset:39936
	global_load_lds_dwordx4 v[204:205], off
	v_lshl_add_u64 v[204:205], s[36:37], 0, v[136:137]
	s_mov_b32 m0, s49
	s_nop 0
	global_load_lds_dwordx4 v[204:205], off
	s_waitcnt vmcnt(8)
	s_waitcnt lgkmcnt(0)
	s_barrier
	s_setprio 1
	v_mfma_f32_16x16x32_bf16 v[130:133], v[140:143], v[172:175], v[130:133]
	v_mfma_f32_16x16x32_bf16 v[126:129], v[148:151], v[172:175], v[126:129]
	v_mfma_f32_16x16x32_bf16 v[114:117], v[140:143], v[180:183], v[114:117]
	v_mfma_f32_16x16x32_bf16 v[110:113], v[148:151], v[180:183], v[110:113]
	v_mfma_f32_16x16x32_bf16 v[98:101], v[140:143], v[188:191], v[98:101]
	v_mfma_f32_16x16x32_bf16 v[94:97], v[148:151], v[188:191], v[94:97]
	v_mfma_f32_16x16x32_bf16 v[82:85], v[140:143], v[196:199], v[82:85]
	v_mfma_f32_16x16x32_bf16 v[78:81], v[148:151], v[196:199], v[78:81]
	v_mfma_f32_16x16x32_bf16 v[130:133], v[144:147], v[176:179], v[130:133]
	v_mfma_f32_16x16x32_bf16 v[126:129], v[152:155], v[176:179], v[126:129]
	v_mfma_f32_16x16x32_bf16 v[114:117], v[144:147], v[184:187], v[114:117]
	v_mfma_f32_16x16x32_bf16 v[110:113], v[152:155], v[184:187], v[110:113]
	v_mfma_f32_16x16x32_bf16 v[98:101], v[144:147], v[192:195], v[98:101]
	v_mfma_f32_16x16x32_bf16 v[94:97], v[152:155], v[192:195], v[94:97]
	v_mfma_f32_16x16x32_bf16 v[82:85], v[144:147], v[200:203], v[82:85]
	v_mfma_f32_16x16x32_bf16 v[78:81], v[152:155], v[200:203], v[78:81]
	s_setprio 0
	s_setprio 1
	v_mfma_f32_16x16x32_bf16 v[122:125], v[156:159], v[172:175], v[122:125]
	v_mfma_f32_16x16x32_bf16 v[118:121], v[164:167], v[172:175], v[118:121]
	v_mfma_f32_16x16x32_bf16 v[106:109], v[156:159], v[180:183], v[106:109]
	v_mfma_f32_16x16x32_bf16 v[102:105], v[164:167], v[180:183], v[102:105]
	v_mfma_f32_16x16x32_bf16 v[90:93], v[156:159], v[188:191], v[90:93]
	v_mfma_f32_16x16x32_bf16 v[86:89], v[164:167], v[188:191], v[86:89]
	v_mfma_f32_16x16x32_bf16 v[74:77], v[156:159], v[196:199], v[74:77]
	v_mfma_f32_16x16x32_bf16 v[70:73], v[164:167], v[196:199], v[70:73]
	v_mfma_f32_16x16x32_bf16 v[122:125], v[160:163], v[176:179], v[122:125]
	v_mfma_f32_16x16x32_bf16 v[118:121], v[168:171], v[176:179], v[118:121]
	v_mfma_f32_16x16x32_bf16 v[106:109], v[160:163], v[184:187], v[106:109]
	v_mfma_f32_16x16x32_bf16 v[102:105], v[168:171], v[184:187], v[102:105]
	v_mfma_f32_16x16x32_bf16 v[90:93], v[160:163], v[192:195], v[90:93]
	v_mfma_f32_16x16x32_bf16 v[86:89], v[168:171], v[192:195], v[86:89]
	v_mfma_f32_16x16x32_bf16 v[74:77], v[160:163], v[200:203], v[74:77]
	v_mfma_f32_16x16x32_bf16 v[70:73], v[168:171], v[200:203], v[70:73]
	s_setprio 0
	s_barrier
	s_add_i32 s36, s38, s42
	v_lshl_add_u64 v[204:205], s[34:35], 0, v[134:135]
	s_mov_b32 m0, s36
	ds_read_b128 v[172:175], v5 offset:49152
	ds_read_b128 v[176:179], v5 offset:50176
	ds_read_b128 v[180:183], v5 offset:51200
	ds_read_b128 v[184:187], v5 offset:52224
	ds_read_b128 v[188:191], v5 offset:53248
	ds_read_b128 v[192:195], v5 offset:54272
	ds_read_b128 v[196:199], v5 offset:55296
	ds_read_b128 v[200:203], v5 offset:56320
	global_load_lds_dwordx4 v[204:205], off
	s_add_i32 m0, s36, 0x2000
	v_lshl_add_u64 v[204:205], s[34:35], 0, v[138:139]
	s_add_u32 s34, s34, 0x100000
	s_addc_u32 s35, s35, 0
	s_add_i32 s36, s39, s42
	global_load_lds_dwordx4 v[204:205], off
	v_lshl_add_u64 v[204:205], s[34:35], 0, v[134:135]
	s_mov_b32 m0, s36
	s_nop 0
	global_load_lds_dwordx4 v[204:205], off
	v_lshl_add_u64 v[204:205], s[34:35], 0, v[138:139]
	s_add_i32 m0, s36, 0x2000
	s_nop 0
	global_load_lds_dwordx4 v[204:205], off
	v_lshl_add_u64 v[204:205], s[30:31], 0, v[2:3]
	s_mov_b32 m0, s52
	s_nop 0
	global_load_lds_dwordx4 v[204:205], off
	v_lshl_add_u64 v[204:205], s[30:31], 0, v[136:137]
	s_mov_b32 m0, s53
	s_nop 0
	global_load_lds_dwordx4 v[204:205], off
	s_waitcnt vmcnt(8)
	s_waitcnt lgkmcnt(0)
	s_barrier
	s_setprio 1
	v_mfma_f32_16x16x32_bf16 v[66:69], v[140:143], v[172:175], v[66:69]
	v_mfma_f32_16x16x32_bf16 v[62:65], v[148:151], v[172:175], v[62:65]
	v_mfma_f32_16x16x32_bf16 v[50:53], v[140:143], v[180:183], v[50:53]
	v_mfma_f32_16x16x32_bf16 v[46:49], v[148:151], v[180:183], v[46:49]
	v_mfma_f32_16x16x32_bf16 v[34:37], v[140:143], v[188:191], v[34:37]
	v_mfma_f32_16x16x32_bf16 v[30:33], v[148:151], v[188:191], v[30:33]
	v_mfma_f32_16x16x32_bf16 v[18:21], v[140:143], v[196:199], v[18:21]
	v_mfma_f32_16x16x32_bf16 v[14:17], v[148:151], v[196:199], v[14:17]
	v_mfma_f32_16x16x32_bf16 v[66:69], v[144:147], v[176:179], v[66:69]
	v_mfma_f32_16x16x32_bf16 v[62:65], v[152:155], v[176:179], v[62:65]
	v_mfma_f32_16x16x32_bf16 v[50:53], v[144:147], v[184:187], v[50:53]
	v_mfma_f32_16x16x32_bf16 v[46:49], v[152:155], v[184:187], v[46:49]
	v_mfma_f32_16x16x32_bf16 v[34:37], v[144:147], v[192:195], v[34:37]
	v_mfma_f32_16x16x32_bf16 v[30:33], v[152:155], v[192:195], v[30:33]
	v_mfma_f32_16x16x32_bf16 v[18:21], v[144:147], v[200:203], v[18:21]
	v_mfma_f32_16x16x32_bf16 v[14:17], v[152:155], v[200:203], v[14:17]
	s_setprio 0
	s_setprio 1
	v_mfma_f32_16x16x32_bf16 v[58:61], v[156:159], v[172:175], v[58:61]
	v_mfma_f32_16x16x32_bf16 v[54:57], v[164:167], v[172:175], v[54:57]
	v_mfma_f32_16x16x32_bf16 v[42:45], v[156:159], v[180:183], v[42:45]
	v_mfma_f32_16x16x32_bf16 v[38:41], v[164:167], v[180:183], v[38:41]
	v_mfma_f32_16x16x32_bf16 v[26:29], v[156:159], v[188:191], v[26:29]
	v_mfma_f32_16x16x32_bf16 v[22:25], v[164:167], v[188:191], v[22:25]
	v_mfma_f32_16x16x32_bf16 v[10:13], v[156:159], v[196:199], v[10:13]
	v_mfma_f32_16x16x32_bf16 v[6:9], v[164:167], v[196:199], v[6:9]
	v_mfma_f32_16x16x32_bf16 v[58:61], v[160:163], v[176:179], v[58:61]
	v_mfma_f32_16x16x32_bf16 v[54:57], v[168:171], v[176:179], v[54:57]
	v_mfma_f32_16x16x32_bf16 v[42:45], v[160:163], v[184:187], v[42:45]
	v_mfma_f32_16x16x32_bf16 v[38:41], v[168:171], v[184:187], v[38:41]
	v_mfma_f32_16x16x32_bf16 v[26:29], v[160:163], v[192:195], v[26:29]
	v_mfma_f32_16x16x32_bf16 v[22:25], v[168:171], v[192:195], v[22:25]
	v_mfma_f32_16x16x32_bf16 v[10:13], v[160:163], v[200:203], v[10:13]
	v_mfma_f32_16x16x32_bf16 v[6:9], v[168:171], v[200:203], v[6:9]
	s_setprio 0
	s_barrier
	s_add_i32 s59, s59, 2
	s_add_u32 s55, s55, 0x100
	s_addc_u32 s56, s56, 0
	s_add_u32 s57, s57, 0x100
	s_addc_u32 s58, s58, 0
	s_cmp_gt_u32 s59, 61
	s_cbranch_scc0 .LBB0_131
	s_and_b64 vcc, exec, s[8:9]
	s_cbranch_vccz .LBB0_134
	s_barrier

.LBB0_251:
	s_add_u32 s56, s52, 0xffffff80
	s_addc_u32 s57, s53, -1
	s_cmp_eq_u32 s54, 60
	s_cselect_b32 s28, s2, s52
	s_cselect_b32 s29, s1, s53
	s_cselect_b32 s31, s11, s33
	s_cselect_b32 s30, s15, s19
	s_add_u32 s24, s28, 0x80
	s_addc_u32 s25, s29, 0
	s_add_u32 s26, s30, 0x80
	s_addc_u32 s27, s31, 0
	s_add_i32 s55, 0, 0x10000
	s_add_i32 s58, 0, 0x14000
	v_add_u32_e32 v152, s55, v1
	v_add_u32_e32 v168, s58, v1
	ds_read_b128 v[140:143], v152
	ds_read_b128 v[144:147], v152 offset:1024
	ds_read_b128 v[148:151], v152 offset:2048
	ds_read_b128 v[152:155], v152 offset:3072
	ds_read_b128 v[156:159], v168
	ds_read_b128 v[160:163], v168 offset:1024
	ds_read_b128 v[164:167], v168 offset:2048
	ds_read_b128 v[168:171], v168 offset:3072
	s_add_u32 s56, s56, 0x100000
	s_addc_u32 s57, s57, 0
	v_lshl_add_u64 v[204:205], s[56:57], 0, v[138:139]
	s_add_i32 m0, s23, 0xc000
	ds_read_b128 v[172:175], v5
	ds_read_b128 v[176:179], v5 offset:1024
	ds_read_b128 v[180:183], v5 offset:2048
	ds_read_b128 v[184:187], v5 offset:3072
	ds_read_b128 v[188:191], v5 offset:4096
	ds_read_b128 v[192:195], v5 offset:5120
	ds_read_b128 v[196:199], v5 offset:6144
	ds_read_b128 v[200:203], v5 offset:7168
	global_load_lds_dwordx4 v[204:205], off
	v_lshl_add_u64 v[204:205], s[56:57], 0, v[134:135]
	s_add_i32 m0, s23, 0xe000
	s_nop 0
	global_load_lds_dwordx4 v[204:205], off
	s_waitcnt vmcnt(8)
	s_waitcnt lgkmcnt(0)
	s_barrier
	s_setprio 1
	v_mfma_f32_16x16x32_bf16 v[6:9], v[140:143], v[172:175], v[6:9]
	v_mfma_f32_16x16x32_bf16 v[10:13], v[148:151], v[172:175], v[10:13]
	v_mfma_f32_16x16x32_bf16 v[22:25], v[140:143], v[180:183], v[22:25]
	v_mfma_f32_16x16x32_bf16 v[26:29], v[148:151], v[180:183], v[26:29]
	v_mfma_f32_16x16x32_bf16 v[38:41], v[140:143], v[188:191], v[38:41]
	v_mfma_f32_16x16x32_bf16 v[42:45], v[148:151], v[188:191], v[42:45]
	v_mfma_f32_16x16x32_bf16 v[54:57], v[140:143], v[196:199], v[54:57]
	v_mfma_f32_16x16x32_bf16 v[58:61], v[148:151], v[196:199], v[58:61]
	v_mfma_f32_16x16x32_bf16 v[6:9], v[144:147], v[176:179], v[6:9]
	v_mfma_f32_16x16x32_bf16 v[10:13], v[152:155], v[176:179], v[10:13]
	v_mfma_f32_16x16x32_bf16 v[22:25], v[144:147], v[184:187], v[22:25]
	v_mfma_f32_16x16x32_bf16 v[26:29], v[152:155], v[184:187], v[26:29]
	v_mfma_f32_16x16x32_bf16 v[38:41], v[144:147], v[192:195], v[38:41]
	v_mfma_f32_16x16x32_bf16 v[42:45], v[152:155], v[192:195], v[42:45]
	v_mfma_f32_16x16x32_bf16 v[54:57], v[144:147], v[200:203], v[54:57]
	v_mfma_f32_16x16x32_bf16 v[58:61], v[152:155], v[200:203], v[58:61]
	s_setprio 0
	s_setprio 1
	v_mfma_f32_16x16x32_bf16 v[14:17], v[156:159], v[172:175], v[14:17]
	v_mfma_f32_16x16x32_bf16 v[18:21], v[164:167], v[172:175], v[18:21]
	v_mfma_f32_16x16x32_bf16 v[30:33], v[156:159], v[180:183], v[30:33]
	v_mfma_f32_16x16x32_bf16 v[34:37], v[164:167], v[180:183], v[34:37]
	v_mfma_f32_16x16x32_bf16 v[46:49], v[156:159], v[188:191], v[46:49]
	v_mfma_f32_16x16x32_bf16 v[50:53], v[164:167], v[188:191], v[50:53]
	v_mfma_f32_16x16x32_bf16 v[62:65], v[156:159], v[196:199], v[62:65]
	v_mfma_f32_16x16x32_bf16 v[66:69], v[164:167], v[196:199], v[66:69]
	v_mfma_f32_16x16x32_bf16 v[14:17], v[160:163], v[176:179], v[14:17]
	v_mfma_f32_16x16x32_bf16 v[18:21], v[168:171], v[176:179], v[18:21]
	v_mfma_f32_16x16x32_bf16 v[30:33], v[160:163], v[184:187], v[30:33]
	v_mfma_f32_16x16x32_bf16 v[34:37], v[168:171], v[184:187], v[34:37]
	v_mfma_f32_16x16x32_bf16 v[46:49], v[160:163], v[192:195], v[46:49]
	v_mfma_f32_16x16x32_bf16 v[50:53], v[168:171], v[192:195], v[50:53]
	v_mfma_f32_16x16x32_bf16 v[62:65], v[160:163], v[200:203], v[62:65]
	v_mfma_f32_16x16x32_bf16 v[66:69], v[168:171], v[200:203], v[66:69]
	s_setprio 0
	s_barrier
	s_add_i32 s55, s55, s37
	v_lshl_add_u64 v[204:205], s[30:31], 0, v[136:137]
	s_mov_b32 m0, s55
	ds_read_b128 v[172:175], v5 offset:16384
	ds_read_b128 v[176:179], v5 offset:17408
	ds_read_b128 v[180:183], v5 offset:18432
	ds_read_b128 v[184:187], v5 offset:19456
	ds_read_b128 v[188:191], v5 offset:20480
	ds_read_b128 v[192:195], v5 offset:21504
	ds_read_b128 v[196:199], v5 offset:22528
	ds_read_b128 v[200:203], v5 offset:23552
	global_load_lds_dwordx4 v[204:205], off
	s_add_i32 m0, s55, 0x2000
	v_lshl_add_u64 v[204:205], s[30:31], 0, v[2:3]
	s_add_u32 s30, s30, 0x100000
	s_addc_u32 s31, s31, 0
	s_add_i32 s55, s58, s37
	global_load_lds_dwordx4 v[204:205], off
	v_lshl_add_u64 v[204:205], s[30:31], 0, v[136:137]
	s_mov_b32 m0, s55
	s_nop 0
	global_load_lds_dwordx4 v[204:205], off
	v_lshl_add_u64 v[204:205], s[30:31], 0, v[2:3]
	s_add_i32 m0, s55, 0x2000
	s_nop 0
	global_load_lds_dwordx4 v[204:205], off
	v_lshl_add_u64 v[204:205], s[28:29], 0, v[138:139]
	s_mov_b32 m0, s23
	s_nop 0
	global_load_lds_dwordx4 v[204:205], off
	v_lshl_add_u64 v[204:205], s[28:29], 0, v[134:135]
	s_mov_b32 m0, s40
	s_nop 0
	global_load_lds_dwordx4 v[204:205], off
	s_waitcnt vmcnt(8)
	s_waitcnt lgkmcnt(0)
	s_barrier
	s_setprio 1
	v_mfma_f32_16x16x32_bf16 v[70:73], v[140:143], v[172:175], v[70:73]
	v_mfma_f32_16x16x32_bf16 v[74:77], v[148:151], v[172:175], v[74:77]
	v_mfma_f32_16x16x32_bf16 v[86:89], v[140:143], v[180:183], v[86:89]
	v_mfma_f32_16x16x32_bf16 v[90:93], v[148:151], v[180:183], v[90:93]
	v_mfma_f32_16x16x32_bf16 v[102:105], v[140:143], v[188:191], v[102:105]
	v_mfma_f32_16x16x32_bf16 v[106:109], v[148:151], v[188:191], v[106:109]
	v_mfma_f32_16x16x32_bf16 v[130:133], v[140:143], v[196:199], v[130:133]
	v_mfma_f32_16x16x32_bf16 v[126:129], v[148:151], v[196:199], v[126:129]
	v_mfma_f32_16x16x32_bf16 v[70:73], v[144:147], v[176:179], v[70:73]
	v_mfma_f32_16x16x32_bf16 v[74:77], v[152:155], v[176:179], v[74:77]
	v_mfma_f32_16x16x32_bf16 v[86:89], v[144:147], v[184:187], v[86:89]
	v_mfma_f32_16x16x32_bf16 v[90:93], v[152:155], v[184:187], v[90:93]
	v_mfma_f32_16x16x32_bf16 v[102:105], v[144:147], v[192:195], v[102:105]
	v_mfma_f32_16x16x32_bf16 v[106:109], v[152:155], v[192:195], v[106:109]
	v_mfma_f32_16x16x32_bf16 v[130:133], v[144:147], v[200:203], v[130:133]
	v_mfma_f32_16x16x32_bf16 v[126:129], v[152:155], v[200:203], v[126:129]
	s_setprio 0
	s_setprio 1
	v_mfma_f32_16x16x32_bf16 v[78:81], v[156:159], v[172:175], v[78:81]
	v_mfma_f32_16x16x32_bf16 v[82:85], v[164:167], v[172:175], v[82:85]
	v_mfma_f32_16x16x32_bf16 v[94:97], v[156:159], v[180:183], v[94:97]
	v_mfma_f32_16x16x32_bf16 v[98:101], v[164:167], v[180:183], v[98:101]
	v_mfma_f32_16x16x32_bf16 v[110:113], v[156:159], v[188:191], v[110:113]
	v_mfma_f32_16x16x32_bf16 v[114:117], v[164:167], v[188:191], v[114:117]
	v_mfma_f32_16x16x32_bf16 v[122:125], v[156:159], v[196:199], v[122:125]
	v_mfma_f32_16x16x32_bf16 v[118:121], v[164:167], v[196:199], v[118:121]
	v_mfma_f32_16x16x32_bf16 v[78:81], v[160:163], v[176:179], v[78:81]
	v_mfma_f32_16x16x32_bf16 v[82:85], v[168:171], v[176:179], v[82:85]
	v_mfma_f32_16x16x32_bf16 v[94:97], v[160:163], v[184:187], v[94:97]
	v_mfma_f32_16x16x32_bf16 v[98:101], v[168:171], v[184:187], v[98:101]
	v_mfma_f32_16x16x32_bf16 v[110:113], v[160:163], v[192:195], v[110:113]
	v_mfma_f32_16x16x32_bf16 v[114:117], v[168:171], v[192:195], v[114:117]
	v_mfma_f32_16x16x32_bf16 v[122:125], v[160:163], v[200:203], v[122:125]
	v_mfma_f32_16x16x32_bf16 v[118:121], v[168:171], v[200:203], v[118:121]
	s_setprio 0
	s_barrier
	s_add_i32 s30, 0, 0x18000
	s_add_i32 s31, 0, 0x1c000
	v_add_u32_e32 v152, s30, v1
	v_add_u32_e32 v168, s31, v1
	ds_read_b128 v[140:143], v152
	ds_read_b128 v[144:147], v152 offset:1024
	ds_read_b128 v[148:151], v152 offset:2048
	ds_read_b128 v[152:155], v152 offset:3072
	ds_read_b128 v[156:159], v168
	ds_read_b128 v[160:163], v168 offset:1024
	ds_read_b128 v[164:167], v168 offset:2048
	ds_read_b128 v[168:171], v168 offset:3072
	s_add_u32 s28, s28, 0x100000
	s_addc_u32 s29, s29, 0
	s_mov_b32 m0, s41
	v_lshl_add_u64 v[204:205], s[28:29], 0, v[138:139]
	ds_read_b128 v[172:175], v5 offset:32768
	ds_read_b128 v[176:179], v5 offset:33792
	ds_read_b128 v[180:183], v5 offset:34816
	ds_read_b128 v[184:187], v5 offset:35840
	ds_read_b128 v[188:191], v5 offset:36864
	ds_read_b128 v[192:195], v5 offset:37888
	ds_read_b128 v[196:199], v5 offset:38912
	ds_read_b128 v[200:203], v5 offset:39936
	global_load_lds_dwordx4 v[204:205], off
	v_lshl_add_u64 v[204:205], s[28:29], 0, v[134:135]
	s_mov_b32 m0, s42
	s_nop 0
	global_load_lds_dwordx4 v[204:205], off
	s_waitcnt vmcnt(8)
	s_waitcnt lgkmcnt(0)
	s_barrier
	s_setprio 1
	v_mfma_f32_16x16x32_bf16 v[6:9], v[140:143], v[172:175], v[6:9]
	v_mfma_f32_16x16x32_bf16 v[10:13], v[148:151], v[172:175], v[10:13]
	v_mfma_f32_16x16x32_bf16 v[22:25], v[140:143], v[180:183], v[22:25]
	v_mfma_f32_16x16x32_bf16 v[26:29], v[148:151], v[180:183], v[26:29]
	v_mfma_f32_16x16x32_bf16 v[38:41], v[140:143], v[188:191], v[38:41]
	v_mfma_f32_16x16x32_bf16 v[42:45], v[148:151], v[188:191], v[42:45]
	v_mfma_f32_16x16x32_bf16 v[54:57], v[140:143], v[196:199], v[54:57]
	v_mfma_f32_16x16x32_bf16 v[58:61], v[148:151], v[196:199], v[58:61]
	v_mfma_f32_16x16x32_bf16 v[6:9], v[144:147], v[176:179], v[6:9]
	v_mfma_f32_16x16x32_bf16 v[10:13], v[152:155], v[176:179], v[10:13]
	v_mfma_f32_16x16x32_bf16 v[22:25], v[144:147], v[184:187], v[22:25]
	v_mfma_f32_16x16x32_bf16 v[26:29], v[152:155], v[184:187], v[26:29]
	v_mfma_f32_16x16x32_bf16 v[38:41], v[144:147], v[192:195], v[38:41]
	v_mfma_f32_16x16x32_bf16 v[42:45], v[152:155], v[192:195], v[42:45]
	v_mfma_f32_16x16x32_bf16 v[54:57], v[144:147], v[200:203], v[54:57]
	v_mfma_f32_16x16x32_bf16 v[58:61], v[152:155], v[200:203], v[58:61]
	s_setprio 0
	s_setprio 1
	v_mfma_f32_16x16x32_bf16 v[14:17], v[156:159], v[172:175], v[14:17]
	v_mfma_f32_16x16x32_bf16 v[18:21], v[164:167], v[172:175], v[18:21]
	v_mfma_f32_16x16x32_bf16 v[30:33], v[156:159], v[180:183], v[30:33]
	v_mfma_f32_16x16x32_bf16 v[34:37], v[164:167], v[180:183], v[34:37]
	v_mfma_f32_16x16x32_bf16 v[46:49], v[156:159], v[188:191], v[46:49]
	v_mfma_f32_16x16x32_bf16 v[50:53], v[164:167], v[188:191], v[50:53]
	v_mfma_f32_16x16x32_bf16 v[62:65], v[156:159], v[196:199], v[62:65]
	v_mfma_f32_16x16x32_bf16 v[66:69], v[164:167], v[196:199], v[66:69]
	v_mfma_f32_16x16x32_bf16 v[14:17], v[160:163], v[176:179], v[14:17]
	v_mfma_f32_16x16x32_bf16 v[18:21], v[168:171], v[176:179], v[18:21]
	v_mfma_f32_16x16x32_bf16 v[30:33], v[160:163], v[184:187], v[30:33]
	v_mfma_f32_16x16x32_bf16 v[34:37], v[168:171], v[184:187], v[34:37]
	v_mfma_f32_16x16x32_bf16 v[46:49], v[160:163], v[192:195], v[46:49]
	v_mfma_f32_16x16x32_bf16 v[50:53], v[168:171], v[192:195], v[50:53]
	v_mfma_f32_16x16x32_bf16 v[62:65], v[160:163], v[200:203], v[62:65]
	v_mfma_f32_16x16x32_bf16 v[66:69], v[168:171], v[200:203], v[66:69]
	s_setprio 0
	s_barrier
	s_add_i32 s28, s30, s37
	v_lshl_add_u64 v[204:205], s[26:27], 0, v[136:137]
	s_mov_b32 m0, s28
	ds_read_b128 v[172:175], v5 offset:49152
	ds_read_b128 v[176:179], v5 offset:50176
	ds_read_b128 v[180:183], v5 offset:51200
	ds_read_b128 v[184:187], v5 offset:52224
	ds_read_b128 v[188:191], v5 offset:53248
	ds_read_b128 v[192:195], v5 offset:54272
	ds_read_b128 v[196:199], v5 offset:55296
	ds_read_b128 v[200:203], v5 offset:56320
	global_load_lds_dwordx4 v[204:205], off
	s_add_i32 m0, s28, 0x2000
	v_lshl_add_u64 v[204:205], s[26:27], 0, v[2:3]
	s_add_u32 s26, s26, 0x100000
	s_addc_u32 s27, s27, 0
	s_add_i32 s28, s31, s37
	global_load_lds_dwordx4 v[204:205], off
	v_lshl_add_u64 v[204:205], s[26:27], 0, v[136:137]
	s_mov_b32 m0, s28
	s_nop 0
	global_load_lds_dwordx4 v[204:205], off
	v_lshl_add_u64 v[204:205], s[26:27], 0, v[2:3]
	s_add_i32 m0, s28, 0x2000
	s_nop 0
	global_load_lds_dwordx4 v[204:205], off
	v_lshl_add_u64 v[204:205], s[24:25], 0, v[138:139]
	s_mov_b32 m0, s49
	s_nop 0
	global_load_lds_dwordx4 v[204:205], off
	v_lshl_add_u64 v[204:205], s[24:25], 0, v[134:135]
	s_mov_b32 m0, s50
	s_nop 0
	global_load_lds_dwordx4 v[204:205], off
	s_waitcnt vmcnt(8)
	s_waitcnt lgkmcnt(0)
	s_barrier
	s_setprio 1
	v_mfma_f32_16x16x32_bf16 v[70:73], v[140:143], v[172:175], v[70:73]
	v_mfma_f32_16x16x32_bf16 v[74:77], v[148:151], v[172:175], v[74:77]
	v_mfma_f32_16x16x32_bf16 v[86:89], v[140:143], v[180:183], v[86:89]
	v_mfma_f32_16x16x32_bf16 v[90:93], v[148:151], v[180:183], v[90:93]
	v_mfma_f32_16x16x32_bf16 v[102:105], v[140:143], v[188:191], v[102:105]
	v_mfma_f32_16x16x32_bf16 v[106:109], v[148:151], v[188:191], v[106:109]
	v_mfma_f32_16x16x32_bf16 v[130:133], v[140:143], v[196:199], v[130:133]
	v_mfma_f32_16x16x32_bf16 v[126:129], v[148:151], v[196:199], v[126:129]
	v_mfma_f32_16x16x32_bf16 v[70:73], v[144:147], v[176:179], v[70:73]
	v_mfma_f32_16x16x32_bf16 v[74:77], v[152:155], v[176:179], v[74:77]
	v_mfma_f32_16x16x32_bf16 v[86:89], v[144:147], v[184:187], v[86:89]
	v_mfma_f32_16x16x32_bf16 v[90:93], v[152:155], v[184:187], v[90:93]
	v_mfma_f32_16x16x32_bf16 v[102:105], v[144:147], v[192:195], v[102:105]
	v_mfma_f32_16x16x32_bf16 v[106:109], v[152:155], v[192:195], v[106:109]
	v_mfma_f32_16x16x32_bf16 v[130:133], v[144:147], v[200:203], v[130:133]
	v_mfma_f32_16x16x32_bf16 v[126:129], v[152:155], v[200:203], v[126:129]
	s_setprio 0
	s_setprio 1
	v_mfma_f32_16x16x32_bf16 v[78:81], v[156:159], v[172:175], v[78:81]
	v_mfma_f32_16x16x32_bf16 v[82:85], v[164:167], v[172:175], v[82:85]
	v_mfma_f32_16x16x32_bf16 v[94:97], v[156:159], v[180:183], v[94:97]
	v_mfma_f32_16x16x32_bf16 v[98:101], v[164:167], v[180:183], v[98:101]
	v_mfma_f32_16x16x32_bf16 v[110:113], v[156:159], v[188:191], v[110:113]
	v_mfma_f32_16x16x32_bf16 v[114:117], v[164:167], v[188:191], v[114:117]
	v_mfma_f32_16x16x32_bf16 v[122:125], v[156:159], v[196:199], v[122:125]
	v_mfma_f32_16x16x32_bf16 v[118:121], v[164:167], v[196:199], v[118:121]
	v_mfma_f32_16x16x32_bf16 v[78:81], v[160:163], v[176:179], v[78:81]
	v_mfma_f32_16x16x32_bf16 v[82:85], v[168:171], v[176:179], v[82:85]
	v_mfma_f32_16x16x32_bf16 v[94:97], v[160:163], v[184:187], v[94:97]
	v_mfma_f32_16x16x32_bf16 v[98:101], v[168:171], v[184:187], v[98:101]
	v_mfma_f32_16x16x32_bf16 v[110:113], v[160:163], v[192:195], v[110:113]
	v_mfma_f32_16x16x32_bf16 v[114:117], v[168:171], v[192:195], v[114:117]
	v_mfma_f32_16x16x32_bf16 v[122:125], v[160:163], v[200:203], v[122:125]
	v_mfma_f32_16x16x32_bf16 v[118:121], v[168:171], v[200:203], v[118:121]
	s_setprio 0
	s_barrier
	s_add_i32 s54, s54, 2
	s_add_u32 s19, s19, 0x100
	s_addc_u32 s33, s33, 0
	s_add_u32 s52, s52, 0x100
	s_addc_u32 s53, s53, 0
	s_cmp_gt_u32 s54, 61
	s_cbranch_scc0 .LBB0_251
	v_mov_b32_e32 v141, v0
	s_lshl_b32 s1, s0, 8
	s_mov_b64 s[24:25], s[84:85]
	s_add_i32 s1, s1, s43
	v_and_or_b32 v140, v141, 15, s1
	v_lshrrev_b32_e32 v141, 1, v141
	s_add_u32 s26, s24, s6
	v_and_or_b32 v148, v141, 24, s48
	s_addc_u32 s27, s25, s7
	v_ashrrev_i32_e32 v141, 31, v140
	v_lshl_add_u64 v[142:143], v[140:141], 2, s[26:27]
	s_mov_b64 s[26:27], 0x10000
	v_lshl_add_u64 v[144:145], v[142:143], 0, s[26:27]
	v_add_co_u32_e32 v142, vcc, s91, v142
	global_load_dword v146, v[144:145], off offset:512
	s_nop 0
	v_addc_co_u32_e32 v143, vcc, 0, v143, vcc
	global_load_dword v142, v[142:143], off
	s_cmp_lt_i32 s22, 8
	s_mov_b64 s[26:27], -1
	global_load_dword v205, v[144:145], off offset:64
	global_load_dword v204, v[144:145], off offset:128
	global_load_dword v203, v[144:145], off offset:192
	global_load_dword v202, v[144:145], off offset:576
	global_load_dword v201, v[144:145], off offset:640
	global_load_dword v200, v[144:145], off offset:704
	s_waitcnt vmcnt(0)
	v_fmamk_f32 v146, v146, 0x39800000, v246
	v_mul_f32_e32 v147, 0x4b800000, v146
	v_fmamk_f32 v142, v142, 0x39800000, v246
	v_cmp_gt_f32_e32 vcc, s95, v142
	v_mul_f32_e32 v143, 0x4b800000, v142
	s_nop 0
	v_cndmask_b32_e32 v142, v142, v143, vcc
	v_rsq_f32_e32 v142, v142
	s_nop 0
	v_mul_f32_e32 v143, 0x45800000, v142
	v_cndmask_b32_e32 v142, v142, v143, vcc
	v_pk_mul_f32 v[8:9], v[8:9], v[142:143] op_sel_hi:[1,0]
	v_pk_mul_f32 v[6:7], v[6:7], v[142:143] op_sel_hi:[1,0]
	v_pk_mul_f32 v[12:13], v[12:13], v[142:143] op_sel_hi:[1,0]
	v_pk_mul_f32 v[10:11], v[10:11], v[142:143] op_sel_hi:[1,0]
	v_pk_mul_f32 v[16:17], v[16:17], v[142:143] op_sel_hi:[1,0]
	v_pk_mul_f32 v[14:15], v[14:15], v[142:143] op_sel_hi:[1,0]
	v_pk_mul_f32 v[20:21], v[20:21], v[142:143] op_sel_hi:[1,0]
	v_pk_mul_f32 v[18:19], v[18:19], v[142:143] op_sel_hi:[1,0]
	s_waitcnt vmcnt(0)
	v_fmamk_f32 v142, v205, 0x39800000, v246
	v_cmp_gt_f32_e32 vcc, s95, v142
	v_mul_f32_e32 v143, 0x4b800000, v142
	s_nop 0
	v_cndmask_b32_e32 v142, v142, v143, vcc
	v_rsq_f32_e32 v142, v142
	s_nop 0
	v_mul_f32_e32 v143, 0x45800000, v142
	v_cndmask_b32_e32 v142, v142, v143, vcc
	v_pk_mul_f32 v[24:25], v[24:25], v[142:143] op_sel_hi:[1,0]
	v_pk_mul_f32 v[22:23], v[22:23], v[142:143] op_sel_hi:[1,0]
	v_pk_mul_f32 v[28:29], v[28:29], v[142:143] op_sel_hi:[1,0]
	v_pk_mul_f32 v[26:27], v[26:27], v[142:143] op_sel_hi:[1,0]
	v_pk_mul_f32 v[32:33], v[32:33], v[142:143] op_sel_hi:[1,0]
	v_pk_mul_f32 v[30:31], v[30:31], v[142:143] op_sel_hi:[1,0]
	v_pk_mul_f32 v[36:37], v[36:37], v[142:143] op_sel_hi:[1,0]
	v_pk_mul_f32 v[34:35], v[34:35], v[142:143] op_sel_hi:[1,0]
	s_waitcnt vmcnt(0)
	v_fmamk_f32 v142, v204, 0x39800000, v246
	v_cmp_gt_f32_e32 vcc, s95, v142
	v_mul_f32_e32 v143, 0x4b800000, v142
	s_nop 0
	v_cndmask_b32_e32 v142, v142, v143, vcc
	v_rsq_f32_e32 v142, v142
	s_nop 0
	v_mul_f32_e32 v143, 0x45800000, v142
	v_cndmask_b32_e32 v142, v142, v143, vcc
	v_pk_mul_f32 v[40:41], v[40:41], v[142:143] op_sel_hi:[1,0]
	v_pk_mul_f32 v[38:39], v[38:39], v[142:143] op_sel_hi:[1,0]
	v_pk_mul_f32 v[44:45], v[44:45], v[142:143] op_sel_hi:[1,0]
	v_pk_mul_f32 v[42:43], v[42:43], v[142:143] op_sel_hi:[1,0]
	v_pk_mul_f32 v[48:49], v[48:49], v[142:143] op_sel_hi:[1,0]
	v_pk_mul_f32 v[46:47], v[46:47], v[142:143] op_sel_hi:[1,0]
	v_pk_mul_f32 v[52:53], v[52:53], v[142:143] op_sel_hi:[1,0]
	v_pk_mul_f32 v[50:51], v[50:51], v[142:143] op_sel_hi:[1,0]
	s_waitcnt vmcnt(0)
	v_fmamk_f32 v142, v203, 0x39800000, v246
	v_cmp_gt_f32_e32 vcc, s95, v142
	v_mul_f32_e32 v143, 0x4b800000, v142
	s_nop 0
	v_cndmask_b32_e32 v142, v142, v143, vcc
	v_rsq_f32_e32 v142, v142
	s_nop 0
	v_mul_f32_e32 v143, 0x45800000, v142
	v_cndmask_b32_e32 v142, v142, v143, vcc
	v_cmp_gt_f32_e32 vcc, s95, v146
	v_pk_mul_f32 v[56:57], v[56:57], v[142:143] op_sel_hi:[1,0]
	v_pk_mul_f32 v[54:55], v[54:55], v[142:143] op_sel_hi:[1,0]
	v_cndmask_b32_e32 v146, v146, v147, vcc
	v_rsq_f32_e32 v146, v146
	v_pk_mul_f32 v[60:61], v[60:61], v[142:143] op_sel_hi:[1,0]
	v_pk_mul_f32 v[58:59], v[58:59], v[142:143] op_sel_hi:[1,0]
	v_pk_mul_f32 v[64:65], v[64:65], v[142:143] op_sel_hi:[1,0]
	v_mul_f32_e32 v147, 0x45800000, v146
	v_cndmask_b32_e32 v146, v146, v147, vcc
	v_pk_mul_f32 v[72:73], v[72:73], v[146:147] op_sel_hi:[1,0]
	v_pk_mul_f32 v[70:71], v[70:71], v[146:147] op_sel_hi:[1,0]
	v_pk_mul_f32 v[76:77], v[76:77], v[146:147] op_sel_hi:[1,0]
	v_pk_mul_f32 v[74:75], v[74:75], v[146:147] op_sel_hi:[1,0]
	v_pk_mul_f32 v[80:81], v[80:81], v[146:147] op_sel_hi:[1,0]
	v_pk_mul_f32 v[78:79], v[78:79], v[146:147] op_sel_hi:[1,0]
	v_pk_mul_f32 v[84:85], v[84:85], v[146:147] op_sel_hi:[1,0]
	v_pk_mul_f32 v[82:83], v[82:83], v[146:147] op_sel_hi:[1,0]
	v_pk_mul_f32 v[62:63], v[62:63], v[142:143] op_sel_hi:[1,0]
	v_pk_mul_f32 v[68:69], v[68:69], v[142:143] op_sel_hi:[1,0]
	v_pk_mul_f32 v[66:67], v[66:67], v[142:143] op_sel_hi:[1,0]
	v_add_u32_e32 v142, 0x80, v140
	v_ashrrev_i32_e32 v143, 31, v142
	s_waitcnt vmcnt(0)
	v_fmamk_f32 v146, v202, 0x39800000, v246
	v_cmp_gt_f32_e32 vcc, s95, v146
	v_mul_f32_e32 v147, 0x4b800000, v146
	s_nop 0
	v_cndmask_b32_e32 v146, v146, v147, vcc
	v_rsq_f32_e32 v146, v146
	s_nop 0
	v_mul_f32_e32 v147, 0x45800000, v146
	v_cndmask_b32_e32 v146, v146, v147, vcc
	v_pk_mul_f32 v[88:89], v[88:89], v[146:147] op_sel_hi:[1,0]
	v_pk_mul_f32 v[86:87], v[86:87], v[146:147] op_sel_hi:[1,0]
	v_pk_mul_f32 v[92:93], v[92:93], v[146:147] op_sel_hi:[1,0]
	v_pk_mul_f32 v[90:91], v[90:91], v[146:147] op_sel_hi:[1,0]
	v_pk_mul_f32 v[96:97], v[96:97], v[146:147] op_sel_hi:[1,0]
	v_pk_mul_f32 v[94:95], v[94:95], v[146:147] op_sel_hi:[1,0]
	v_pk_mul_f32 v[100:101], v[100:101], v[146:147] op_sel_hi:[1,0]
	v_pk_mul_f32 v[98:99], v[98:99], v[146:147] op_sel_hi:[1,0]
	s_waitcnt vmcnt(0)
	v_fmamk_f32 v146, v201, 0x39800000, v246
	v_cmp_gt_f32_e32 vcc, s95, v146
	v_mul_f32_e32 v147, 0x4b800000, v146
	s_waitcnt vmcnt(0)
	v_fmamk_f32 v144, v200, 0x39800000, v246
	v_cndmask_b32_e32 v146, v146, v147, vcc
	v_rsq_f32_e32 v146, v146
	v_mul_f32_e32 v145, 0x4b800000, v144
	v_mul_f32_e32 v147, 0x45800000, v146
	v_cndmask_b32_e32 v146, v146, v147, vcc
	v_cmp_gt_f32_e32 vcc, s95, v144
	v_pk_mul_f32 v[104:105], v[104:105], v[146:147] op_sel_hi:[1,0]
	v_pk_mul_f32 v[102:103], v[102:103], v[146:147] op_sel_hi:[1,0]
	v_cndmask_b32_e32 v144, v144, v145, vcc
	v_rsq_f32_e32 v144, v144
	v_pk_mul_f32 v[108:109], v[108:109], v[146:147] op_sel_hi:[1,0]
	v_pk_mul_f32 v[106:107], v[106:107], v[146:147] op_sel_hi:[1,0]
	v_pk_mul_f32 v[112:113], v[112:113], v[146:147] op_sel_hi:[1,0]
	v_mul_f32_e32 v145, 0x45800000, v144
	v_cndmask_b32_e32 v144, v144, v145, vcc
	v_pk_mul_f32 v[110:111], v[110:111], v[146:147] op_sel_hi:[1,0]
	v_pk_mul_f32 v[116:117], v[116:117], v[146:147] op_sel_hi:[1,0]
	v_pk_mul_f32 v[114:115], v[114:115], v[146:147] op_sel_hi:[1,0]
	v_pk_mul_f32 v[132:133], v[132:133], v[144:145] op_sel_hi:[1,0]
	v_pk_mul_f32 v[130:131], v[130:131], v[144:145] op_sel_hi:[1,0]
	v_pk_mul_f32 v[128:129], v[128:129], v[144:145] op_sel_hi:[1,0]
	v_pk_mul_f32 v[126:127], v[126:127], v[144:145] op_sel_hi:[1,0]
	v_pk_mul_f32 v[124:125], v[124:125], v[144:145] op_sel_hi:[1,0]
	v_pk_mul_f32 v[122:123], v[122:123], v[144:145] op_sel_hi:[1,0]
	v_pk_mul_f32 v[120:121], v[120:121], v[144:145] op_sel_hi:[1,0]
	v_pk_mul_f32 v[118:119], v[118:119], v[144:145] op_sel_hi:[1,0]
	s_cbranch_scc1 .LBB0_254
	v_mul_f32_e32 v145, 0xbfb8aa3b, v7
	v_mul_f32_e32 v146, 0xbfb8aa3b, v8
	v_exp_f32_e32 v145, v145
	v_exp_f32_e32 v146, v146
	v_mul_f32_e32 v144, 0xbfb8aa3b, v6
	v_exp_f32_e32 v144, v144
	v_add_f32_e32 v145, 1.0, v145
	v_add_f32_e32 v146, 1.0, v146
	v_rcp_f32_e32 v145, v145
	v_rcp_f32_e32 v149, v146
	v_add_f32_e32 v144, 1.0, v144
	v_mul_f32_e32 v146, 0xbfb8aa3b, v9
	v_mul_f32_e32 v147, v7, v145
	v_mul_f32_e32 v195, v8, v149
	v_mul_f32_e32 v145, 0xbfb8aa3b, v10
	v_mul_f32_e32 v149, 0xbfb8aa3b, v11
	v_rcp_f32_e32 v144, v144
	v_exp_f32_e32 v150, v146
	v_exp_f32_e32 v145, v145
	v_exp_f32_e32 v149, v149
	v_mul_f32_e32 v146, v6, v144
	v_add_f32_e32 v144, 1.0, v150
	v_add_f32_e32 v145, 1.0, v145
	v_add_f32_e32 v149, 1.0, v149
	v_mul_f32_e32 v150, 0xbfb8aa3b, v12
	v_rcp_f32_e32 v144, v144
	v_rcp_f32_e32 v145, v145
	v_rcp_f32_e32 v149, v149
	v_exp_f32_e32 v150, v150
	v_mul_f32_e32 v209, v9, v144
	v_mul_f32_e32 v144, v10, v145
	v_mul_f32_e32 v145, v11, v149
	v_add_f32_e32 v149, 1.0, v150
	v_mul_f32_e32 v150, 0xbfb8aa3b, v13
	v_exp_f32_e32 v150, v150
	v_mul_f32_e32 v151, 0xbfb8aa3b, v14
	v_exp_f32_e32 v151, v151
	v_mul_f32_e32 v240, 0xbfb8aa3b, v99
	v_add_f32_e32 v150, 1.0, v150
	v_rcp_f32_e32 v150, v150
	v_add_f32_e32 v151, 1.0, v151
	v_rcp_f32_e32 v151, v151
	v_exp_f32_e32 v240, v240
	v_mul_f32_e32 v206, v13, v150
	v_mul_f32_e32 v150, 0xbfb8aa3b, v16
	v_mul_f32_e32 v194, v14, v151
	v_exp_f32_e32 v150, v150
	v_mul_f32_e32 v151, 0xbfb8aa3b, v17
	v_exp_f32_e32 v151, v151
	v_mul_f32_e32 v152, 0xbfb8aa3b, v15
	v_rcp_f32_e32 v149, v149
	v_exp_f32_e32 v152, v152
	v_add_f32_e32 v150, 1.0, v150
	v_rcp_f32_e32 v150, v150
	v_add_f32_e32 v151, 1.0, v151
	v_add_f32_e32 v242, 1.0, v240
	v_cvt_pk_bf16_f32 v240, v146, v147
	v_mul_f32_e32 v146, 0xbfb8aa3b, v100
	v_rcp_f32_e32 v151, v151
	v_exp_f32_e32 v146, v146
	v_mul_f32_e32 v147, 0xbfb8aa3b, v101
	v_exp_f32_e32 v147, v147
	v_mul_f32_e32 v205, v12, v149
	v_add_f32_e32 v149, 1.0, v152
	v_mul_f32_e32 v152, 0xbfb8aa3b, v18
	s_lshl_b32 s1, s22, 8
	v_rcp_f32_e32 v149, v149
	v_exp_f32_e32 v152, v152
	v_mul_f32_e32 v203, v16, v150
	v_mul_f32_e32 v150, 0xbfb8aa3b, v19
	v_cvt_pk_bf16_f32 v241, v195, v209
	v_rcp_f32_e32 v195, v242
	s_addk_i32 s1, 0xf800
	v_cvt_pk_bf16_f32 v242, v144, v145
	v_cvt_pk_bf16_f32 v243, v205, v206
	v_mul_f32_e32 v205, 0xbfb8aa3b, v102
	v_mul_f32_e32 v204, v17, v151
	v_exp_f32_e32 v150, v150
	v_mul_f32_e32 v151, 0xbfb8aa3b, v20
	v_add_f32_e32 v146, 1.0, v146
	v_or_b32_e32 v144, s1, v148
	v_mov_b32_e32 v145, v4
	v_exp_f32_e32 v205, v205
	v_exp_f32_e32 v151, v151
	v_rcp_f32_e32 v209, v146
	v_add_f32_e32 v146, 1.0, v147
	v_lshl_add_u64 v[144:145], v[144:145], 1, s[24:25]
	s_mov_b64 s[26:27], 0x1b480000
	v_rcp_f32_e32 v244, v146
	v_lshl_add_u64 v[146:147], v[144:145], 0, s[26:27]
	v_lshlrev_b64 v[144:145], 13, v[140:141]
	v_mul_f32_e32 v202, v15, v149
	v_add_f32_e32 v149, 1.0, v152
	v_lshl_add_u64 v[144:145], v[146:147], 0, v[144:145]
	v_rcp_f32_e32 v149, v149
	v_add_f32_e32 v150, 1.0, v150
	global_store_dwordx4 v[144:145], v[240:243], off nt
	v_add_f32_e32 v205, 1.0, v205
	v_rcp_f32_e32 v150, v150
	v_mul_f32_e32 v240, 0xbfb8aa3b, v103
	v_add_f32_e32 v151, 1.0, v151
	v_exp_f32_e32 v240, v240
	v_cvt_pk_bf16_f32 v202, v194, v202
	v_cvt_pk_bf16_f32 v203, v203, v204
	v_rcp_f32_e32 v204, v205
	v_rcp_f32_e32 v151, v151
	v_mul_f32_e32 v152, 0xbfb8aa3b, v21
	v_mul_f32_e32 v200, v18, v149
	v_exp_f32_e32 v152, v152
	v_mul_f32_e32 v201, v19, v150
	v_add_f32_e32 v205, 1.0, v240
	v_mul_f32_e32 v240, 0xbfb8aa3b, v105
	v_mul_f32_e32 v241, v102, v204
	v_cvt_pk_bf16_f32 v204, v200, v201
	v_mul_f32_e32 v200, 0xbfb8aa3b, v106
	v_mul_f32_e32 v192, v20, v151
	v_mul_f32_e32 v151, 0xbfb8aa3b, v23
	v_rcp_f32_e32 v205, v205
	v_exp_f32_e32 v240, v240
	v_exp_f32_e32 v200, v200
	v_exp_f32_e32 v151, v151
	v_mul_f32_e32 v150, 0xbfb8aa3b, v22
	v_add_f32_e32 v149, 1.0, v152
	v_exp_f32_e32 v150, v150
	v_rcp_f32_e32 v149, v149
	v_mul_f32_e32 v242, v103, v205
	v_add_f32_e32 v205, 1.0, v240
	v_mul_f32_e32 v201, 0xbfb8aa3b, v107
	v_add_f32_e32 v200, 1.0, v200
	v_add_f32_e32 v151, 1.0, v151
	v_exp_f32_e32 v201, v201
	v_rcp_f32_e32 v240, v205
	v_rcp_f32_e32 v200, v200
	v_rcp_f32_e32 v151, v151
	v_add_f32_e32 v150, 1.0, v150
	v_rcp_f32_e32 v150, v150
	v_mul_f32_e32 v197, v21, v149
	v_mul_f32_e32 v152, 0xbfb8aa3b, v24
	v_add_f32_e32 v201, 1.0, v201
	v_cvt_pk_bf16_f32 v205, v192, v197
	v_mul_f32_e32 v197, v105, v240
	v_mul_f32_e32 v240, v106, v200
	v_mul_f32_e32 v200, 0xbfb8aa3b, v109
	v_exp_f32_e32 v152, v152
	v_mul_f32_e32 v181, v23, v151
	v_mul_f32_e32 v151, 0xbfb8aa3b, v26
	v_rcp_f32_e32 v201, v201
	v_exp_f32_e32 v200, v200
	v_exp_f32_e32 v151, v151
	v_mul_f32_e32 v179, v22, v150
	v_mul_f32_e32 v150, 0xbfb8aa3b, v25
	v_exp_f32_e32 v150, v150
	v_add_f32_e32 v149, 1.0, v152
	v_mul_f32_e32 v152, 0xbfb8aa3b, v27
	v_mul_f32_e32 v243, v107, v201
	v_mul_f32_e32 v201, 0xbfb8aa3b, v110
	v_add_f32_e32 v200, 1.0, v200
	v_rcp_f32_e32 v149, v149
	v_add_f32_e32 v151, 1.0, v151
	v_exp_f32_e32 v152, v152
	v_exp_f32_e32 v201, v201
	v_rcp_f32_e32 v200, v200
	v_rcp_f32_e32 v151, v151
	v_add_f32_e32 v150, 1.0, v150
	v_rcp_f32_e32 v150, v150
	global_store_dwordx4 v[144:145], v[202:205], off offset:256 nt
	v_mul_f32_e32 v188, v24, v149
	v_add_f32_e32 v149, 1.0, v152
	v_mul_f32_e32 v202, 0xbfb8aa3b, v111
	v_add_f32_e32 v201, 1.0, v201
	v_exp_f32_e32 v202, v202
	v_mul_f32_e32 v204, v109, v200
	v_cvt_pk_bf16_f32 v200, v179, v181
	v_mul_f32_e32 v181, 0xbfb8aa3b, v113
	v_mul_f32_e32 v178, v26, v151
	v_mul_f32_e32 v151, 0xbfb8aa3b, v29
	v_rcp_f32_e32 v149, v149
	v_rcp_f32_e32 v201, v201
	v_exp_f32_e32 v181, v181
	v_exp_f32_e32 v151, v151
	v_mul_f32_e32 v179, 0xbfb8aa3b, v112
	v_mul_f32_e32 v189, v25, v150
	v_mul_f32_e32 v150, 0xbfb8aa3b, v28
	v_exp_f32_e32 v179, v179
	v_exp_f32_e32 v150, v150
	v_add_f32_e32 v202, 1.0, v202
	v_mul_f32_e32 v187, v27, v149
	v_mul_f32_e32 v205, v110, v201
	v_cvt_pk_bf16_f32 v201, v188, v189
	v_rcp_f32_e32 v188, v202
	v_add_f32_e32 v181, 1.0, v181
	v_cvt_pk_bf16_f32 v202, v178, v187
	v_mul_f32_e32 v178, 0xbfb8aa3b, v114
	v_add_f32_e32 v151, 1.0, v151
	v_rcp_f32_e32 v181, v181
	v_exp_f32_e32 v178, v178
	v_rcp_f32_e32 v151, v151
	v_add_f32_e32 v179, 1.0, v179
	v_add_f32_e32 v150, 1.0, v150
	v_rcp_f32_e32 v179, v179
	v_rcp_f32_e32 v150, v150
	v_mul_f32_e32 v245, v113, v181
	v_add_f32_e32 v181, 1.0, v178
	v_mul_f32_e32 v178, 0xbfb8aa3b, v115
	v_mul_f32_e32 v182, v29, v151
	v_mul_f32_e32 v151, 0xbfb8aa3b, v32
	v_exp_f32_e32 v248, v178
	v_or_b32_e32 v178, 16, v140
	v_exp_f32_e32 v151, v151
	v_mul_f32_e32 v206, v100, v209
	v_mul_f32_e32 v209, v101, v244
	v_mul_f32_e32 v244, v112, v179
	v_ashrrev_i32_e32 v179, 31, v178
	v_mul_f32_e32 v152, 0xbfb8aa3b, v30
	v_mul_f32_e32 v180, v28, v150
	v_mul_f32_e32 v150, 0xbfb8aa3b, v31
	v_lshlrev_b64 v[178:179], 13, v[178:179]
	v_exp_f32_e32 v152, v152
	v_exp_f32_e32 v150, v150
	v_mul_f32_e32 v187, v111, v188
	v_lshl_add_u64 v[188:189], v[146:147], 0, v[178:179]
	v_mul_f32_e32 v178, 0xbfb8aa3b, v116
	v_exp_f32_e32 v178, v178
	v_add_f32_e32 v151, 1.0, v151
	v_rcp_f32_e32 v151, v151
	v_add_f32_e32 v149, 1.0, v152
	v_add_f32_e32 v150, 1.0, v150
	v_rcp_f32_e32 v149, v149
	v_rcp_f32_e32 v150, v150
	v_add_f32_e32 v178, 1.0, v178
	v_rcp_f32_e32 v178, v178
	v_mul_f32_e32 v173, v32, v151
	v_mul_f32_e32 v151, 0xbfb8aa3b, v35
	v_exp_f32_e32 v151, v151
	v_mul_f32_e32 v152, 0xbfb8aa3b, v33
	v_mul_f32_e32 v170, v30, v149
	v_mul_f32_e32 v172, v31, v150
	v_mul_f32_e32 v150, 0xbfb8aa3b, v34
	v_exp_f32_e32 v152, v152
	v_exp_f32_e32 v150, v150
	v_cvt_pk_bf16_f32 v203, v180, v182
	global_store_dwordx4 v[188:189], v[200:203], off nt
	v_add_f32_e32 v151, 1.0, v151
	v_rcp_f32_e32 v151, v151
	v_mul_f32_e32 v201, v116, v178
	v_cvt_pk_bf16_f32 v178, v170, v172
	v_mul_f32_e32 v170, 0xbfb8aa3b, v130
	v_exp_f32_e32 v170, v170
	v_add_f32_e32 v149, 1.0, v152
	v_add_f32_e32 v150, 1.0, v150
	v_rcp_f32_e32 v149, v149
	v_rcp_f32_e32 v150, v150
	v_add_f32_e32 v170, 1.0, v170
	v_rcp_f32_e32 v179, v181
	v_rcp_f32_e32 v170, v170
	v_mul_f32_e32 v152, 0xbfb8aa3b, v36
	v_mul_f32_e32 v169, v35, v151
	v_mul_f32_e32 v151, 0xbfb8aa3b, v38
	v_exp_f32_e32 v152, v152
	v_exp_f32_e32 v151, v151
	v_add_f32_e32 v180, 1.0, v248
	v_mul_f32_e32 v181, 0xbfb8aa3b, v117
	v_mul_f32_e32 v183, v33, v149
	v_mul_f32_e32 v168, v34, v150
	v_mul_f32_e32 v150, 0xbfb8aa3b, v37
	v_rcp_f32_e32 v180, v180
	v_exp_f32_e32 v181, v181
	v_exp_f32_e32 v150, v150
	v_mul_f32_e32 v182, v114, v179
	v_cvt_pk_bf16_f32 v179, v173, v183
	v_mul_f32_e32 v183, v130, v170
	v_mul_f32_e32 v170, 0xbfb8aa3b, v126
	v_exp_f32_e32 v170, v170
	v_add_f32_e32 v149, 1.0, v152
	v_add_f32_e32 v151, 1.0, v151
	v_rcp_f32_e32 v149, v149
	v_rcp_f32_e32 v151, v151
	v_mul_f32_e32 v200, v115, v180
	v_add_f32_e32 v180, 1.0, v181
	v_add_f32_e32 v150, 1.0, v150
	v_rcp_f32_e32 v173, v180
	v_cvt_pk_bf16_f32 v180, v168, v169
	v_mul_f32_e32 v168, 0xbfb8aa3b, v132
	v_mul_f32_e32 v169, 0xbfb8aa3b, v133
	v_rcp_f32_e32 v150, v150
	v_exp_f32_e32 v168, v168
	v_exp_f32_e32 v169, v169
	v_add_f32_e32 v170, 1.0, v170
	v_rcp_f32_e32 v170, v170
	v_mul_f32_e32 v171, v36, v149
	v_mul_f32_e32 v149, v38, v151
	v_mul_f32_e32 v151, 0xbfb8aa3b, v40
	v_mul_f32_e32 v152, 0xbfb8aa3b, v39
	v_exp_f32_e32 v151, v151
	v_exp_f32_e32 v152, v152
	v_mul_f32_e32 v174, v37, v150
	v_add_f32_e32 v168, 1.0, v168
	v_cvt_pk_bf16_f32 v181, v171, v174
	v_add_f32_e32 v169, 1.0, v169
	v_mul_f32_e32 v171, 0xbfb8aa3b, v127
	v_rcp_f32_e32 v168, v168
	v_rcp_f32_e32 v169, v169
	v_exp_f32_e32 v171, v171
	v_mul_f32_e32 v203, v126, v170
	v_mul_f32_e32 v170, 0xbfb8aa3b, v129
	v_exp_f32_e32 v170, v170
	v_add_f32_e32 v151, 1.0, v151
	v_add_f32_e32 v150, 1.0, v152
	v_mul_f32_e32 v152, 0xbfb8aa3b, v41
	v_rcp_f32_e32 v151, v151
	v_exp_f32_e32 v152, v152
	v_mul_f32_e32 v174, v132, v168
	v_mul_f32_e32 v202, v133, v169
	v_add_f32_e32 v168, 1.0, v171
	v_mul_f32_e32 v169, 0xbfb8aa3b, v128
	v_exp_f32_e32 v169, v169
	v_rcp_f32_e32 v168, v168
	v_add_f32_e32 v170, 1.0, v170
	v_mul_f32_e32 v171, 0xbfb8aa3b, v122
	v_rcp_f32_e32 v170, v170
	v_exp_f32_e32 v171, v171
	v_mul_f32_e32 v153, 0xbfb8aa3b, v42
	v_mul_f32_e32 v154, v40, v151
	v_mul_f32_e32 v151, 0xbfb8aa3b, v43
	v_rcp_f32_e32 v150, v150
	v_add_f32_e32 v152, 1.0, v152
	v_exp_f32_e32 v156, v153
	v_exp_f32_e32 v151, v151
	v_rcp_f32_e32 v152, v152
	global_store_dwordx4 v[188:189], v[178:181], off offset:256 nt
	v_add_f32_e32 v169, 1.0, v169
	v_rcp_f32_e32 v169, v169
	v_mul_f32_e32 v178, v127, v168
	v_mul_f32_e32 v168, 0xbfb8aa3b, v123
	v_mul_f32_e32 v180, v129, v170
	v_add_f32_e32 v170, 1.0, v171
	v_exp_f32_e32 v171, v168
	v_mul_f32_e32 v153, v39, v150
	v_add_f32_e32 v150, 1.0, v156
	v_add_f32_e32 v151, 1.0, v151
	v_mul_f32_e32 v156, 0xbfb8aa3b, v45
	v_mul_f32_e32 v155, v41, v152
	v_mul_f32_e32 v152, 0xbfb8aa3b, v44
	v_rcp_f32_e32 v150, v150
	v_rcp_f32_e32 v151, v151
	v_exp_f32_e32 v158, v156
	v_exp_f32_e32 v152, v152
	v_mul_f32_e32 v179, v128, v169
	v_cvt_pk_bf16_f32 v168, v149, v153
	v_cvt_pk_bf16_f32 v169, v154, v155
	v_add_f32_e32 v154, 1.0, v171
	v_mul_f32_e32 v155, 0xbfb8aa3b, v125
	v_rcp_f32_e32 v153, v170
	v_rcp_f32_e32 v154, v154
	v_exp_f32_e32 v155, v155
	v_mul_f32_e32 v156, v42, v150
	v_mul_f32_e32 v157, v43, v151
	v_add_f32_e32 v150, 1.0, v158
	v_mul_f32_e32 v151, 0xbfb8aa3b, v46
	v_mul_f32_e32 v158, 0xbfb8aa3b, v47
	v_add_f32_e32 v152, 1.0, v152
	v_exp_f32_e32 v151, v151
	v_exp_f32_e32 v158, v158
	v_rcp_f32_e32 v152, v152
	v_mul_f32_e32 v185, 0xbfb8aa3b, v61
	v_mul_f32_e32 v181, v122, v153
	v_mul_f32_e32 v188, v123, v154
	v_add_f32_e32 v153, 1.0, v155
	v_mul_f32_e32 v154, 0xbfb8aa3b, v118
	v_rcp_f32_e32 v150, v150
	v_exp_f32_e32 v185, v185
	v_mul_f32_e32 v186, 0xbfb8aa3b, v62
	v_rcp_f32_e32 v153, v153
	v_exp_f32_e32 v154, v154
	v_mul_f32_e32 v184, 0xbfb8aa3b, v60
	v_exp_f32_e32 v186, v186
	v_add_f32_e32 v151, 1.0, v151
	v_add_f32_e32 v158, 1.0, v158
	v_mul_f32_e32 v159, 0xbfb8aa3b, v48
	v_exp_f32_e32 v184, v184
	v_mul_f32_e32 v210, 0xbfb8aa3b, v71
	v_mul_f32_e32 v155, 0xbfb8aa3b, v119
	v_mul_f32_e32 v152, v44, v152
	v_rcp_f32_e32 v151, v151
	v_rcp_f32_e32 v158, v158
	v_exp_f32_e32 v159, v159
	v_mul_f32_e32 v207, 0xbfb8aa3b, v69
	v_mul_f32_e32 v208, 0xbfb8aa3b, v70
	v_exp_f32_e32 v210, v210
	v_mul_f32_e32 v226, 0xbfb8aa3b, v85
	v_exp_f32_e32 v155, v155
	v_mul_f32_e32 v161, v45, v150
	v_add_f32_e32 v185, 1.0, v185
	v_exp_f32_e32 v207, v207
	v_exp_f32_e32 v208, v208
	v_exp_f32_e32 v226, v226
	v_mul_f32_e32 v227, 0xbfb8aa3b, v86
	v_cvt_pk_bf16_f32 v170, v156, v157
	v_mul_f32_e32 v156, v125, v153
	v_add_f32_e32 v153, 1.0, v154
	v_cvt_pk_bf16_f32 v171, v152, v161
	v_or_b32_e32 v152, 32, v140
	v_rcp_f32_e32 v190, v185
	v_add_f32_e32 v185, 1.0, v186
	v_mul_f32_e32 v225, 0xbfb8aa3b, v84
	v_exp_f32_e32 v227, v227
	v_mul_f32_e32 v236, 0xbfb8aa3b, v95
	v_rcp_f32_e32 v157, v153
	v_ashrrev_i32_e32 v153, 31, v152
	v_add_f32_e32 v184, 1.0, v184
	v_rcp_f32_e32 v191, v185
	v_mul_f32_e32 v185, 0xbfb8aa3b, v63
	v_exp_f32_e32 v225, v225
	v_mul_f32_e32 v234, 0xbfb8aa3b, v93
	v_mul_f32_e32 v235, 0xbfb8aa3b, v94
	v_exp_f32_e32 v236, v236
	v_lshlrev_b64 v[152:153], 13, v[152:153]
	v_mul_f32_e32 v150, v46, v151
	v_mul_f32_e32 v151, v47, v158
	v_add_f32_e32 v158, 1.0, v159
	v_mul_f32_e32 v159, 0xbfb8aa3b, v49
	v_mul_f32_e32 v160, 0xbfb8aa3b, v50
	v_mul_f32_e32 v162, 0xbfb8aa3b, v51
	v_mul_f32_e32 v163, 0xbfb8aa3b, v52
	v_mul_f32_e32 v164, 0xbfb8aa3b, v53
	v_rcp_f32_e32 v184, v184
	v_exp_f32_e32 v193, v185
	v_add_f32_e32 v210, 1.0, v210
	v_exp_f32_e32 v234, v234
	v_exp_f32_e32 v235, v235
	v_add_f32_e32 v189, 1.0, v155
	v_lshl_add_u64 v[154:155], v[146:147], 0, v[152:153]
	v_mul_f32_e32 v152, 0xbfb8aa3b, v120
	v_mul_f32_e32 v153, 0xbfb8aa3b, v121
	v_exp_f32_e32 v159, v159
	v_exp_f32_e32 v160, v160
	v_exp_f32_e32 v162, v162
	v_exp_f32_e32 v163, v163
	v_exp_f32_e32 v164, v164
	v_add_f32_e32 v207, 1.0, v207
	v_add_f32_e32 v208, 1.0, v208
	v_rcp_f32_e32 v211, v210
	v_mul_f32_e32 v210, 0xbfb8aa3b, v72
	v_add_f32_e32 v226, 1.0, v226
	v_exp_f32_e32 v152, v152
	v_exp_f32_e32 v153, v153
	v_rcp_f32_e32 v207, v207
	v_rcp_f32_e32 v208, v208
	v_exp_f32_e32 v212, v210
	v_rcp_f32_e32 v228, v226
	v_add_f32_e32 v226, 1.0, v227
	v_mul_f32_e32 v165, 0xbfb8aa3b, v54
	v_mul_f32_e32 v166, 0xbfb8aa3b, v55
	v_mul_f32_e32 v167, 0xbfb8aa3b, v56
	v_mul_f32_e32 v175, 0xbfb8aa3b, v57
	v_add_f32_e32 v225, 1.0, v225
	v_rcp_f32_e32 v229, v226
	v_mul_f32_e32 v226, 0xbfb8aa3b, v87
	v_add_f32_e32 v236, 1.0, v236
	v_exp_f32_e32 v165, v165
	v_exp_f32_e32 v166, v166
	v_exp_f32_e32 v167, v167
	v_exp_f32_e32 v175, v175
	v_mul_f32_e32 v176, 0xbfb8aa3b, v58
	v_mul_f32_e32 v177, 0xbfb8aa3b, v59
	v_mul_f32_e32 v185, v60, v184
	v_mul_f32_e32 v186, v61, v190
	v_mul_f32_e32 v184, v62, v191
	v_add_f32_e32 v190, 1.0, v193
	v_mul_f32_e32 v191, 0xbfb8aa3b, v64
	v_mul_f32_e32 v193, 0xbfb8aa3b, v65
	v_rcp_f32_e32 v225, v225
	v_exp_f32_e32 v230, v226
	v_add_f32_e32 v234, 1.0, v234
	v_add_f32_e32 v235, 1.0, v235
	v_rcp_f32_e32 v237, v236
	v_mul_f32_e32 v236, 0xbfb8aa3b, v96
	v_add_f32_e32 v159, 1.0, v159
	v_add_f32_e32 v160, 1.0, v160
	v_add_f32_e32 v162, 1.0, v162
	v_add_f32_e32 v163, 1.0, v163
	v_add_f32_e32 v164, 1.0, v164
	v_exp_f32_e32 v176, v176
	v_exp_f32_e32 v177, v177
	v_exp_f32_e32 v191, v191
	v_exp_f32_e32 v193, v193
	v_mul_f32_e32 v196, 0xbfb8aa3b, v66
	v_mul_f32_e32 v198, 0xbfb8aa3b, v67
	v_mul_f32_e32 v199, 0xbfb8aa3b, v68
	v_rcp_f32_e32 v234, v234
	v_rcp_f32_e32 v235, v235
	v_exp_f32_e32 v238, v236
	v_add_f32_e32 v152, 1.0, v152
	v_add_f32_e32 v153, 1.0, v153
	v_rcp_f32_e32 v158, v158
	v_rcp_f32_e32 v159, v159
	v_rcp_f32_e32 v160, v160
	v_rcp_f32_e32 v162, v162
	v_rcp_f32_e32 v163, v163
	v_rcp_f32_e32 v164, v164
	v_exp_f32_e32 v196, v196
	v_exp_f32_e32 v198, v198
	v_exp_f32_e32 v199, v199
	v_mul_f32_e32 v210, v69, v207
	v_mul_f32_e32 v207, v70, v208
	v_mul_f32_e32 v208, v71, v211
	v_add_f32_e32 v211, 1.0, v212
	v_mul_f32_e32 v212, 0xbfb8aa3b, v73
	v_mul_f32_e32 v213, 0xbfb8aa3b, v74
	v_mul_f32_e32 v216, 0xbfb8aa3b, v75
	v_mul_f32_e32 v217, 0xbfb8aa3b, v76
	v_mul_f32_e32 v218, 0xbfb8aa3b, v77
	v_rcp_f32_e32 v152, v152
	v_rcp_f32_e32 v153, v153
	v_exp_f32_e32 v212, v212
	v_exp_f32_e32 v213, v213
	v_exp_f32_e32 v216, v216
	v_exp_f32_e32 v217, v217
	v_exp_f32_e32 v218, v218
	v_mul_f32_e32 v219, 0xbfb8aa3b, v78
	v_mul_f32_e32 v220, 0xbfb8aa3b, v79
	v_mul_f32_e32 v221, 0xbfb8aa3b, v80
	v_mul_f32_e32 v222, 0xbfb8aa3b, v81
	v_mul_f32_e32 v223, 0xbfb8aa3b, v82
	v_mul_f32_e32 v224, 0xbfb8aa3b, v83
	v_add_f32_e32 v165, 1.0, v165
	v_add_f32_e32 v166, 1.0, v166
	v_add_f32_e32 v167, 1.0, v167
	v_add_f32_e32 v175, 1.0, v175
	v_exp_f32_e32 v219, v219
	v_exp_f32_e32 v220, v220
	v_exp_f32_e32 v221, v221
	v_exp_f32_e32 v222, v222
	v_exp_f32_e32 v223, v223
	v_exp_f32_e32 v224, v224
	v_mul_f32_e32 v226, v84, v225
	v_mul_f32_e32 v227, v85, v228
	v_mul_f32_e32 v225, v86, v229
	v_add_f32_e32 v228, 1.0, v230
	v_mul_f32_e32 v229, 0xbfb8aa3b, v88
	v_mul_f32_e32 v230, 0xbfb8aa3b, v89
	v_mul_f32_e32 v231, 0xbfb8aa3b, v90
	v_mul_f32_e32 v232, 0xbfb8aa3b, v91
	v_mul_f32_e32 v233, 0xbfb8aa3b, v92
	v_rcp_f32_e32 v165, v165
	v_rcp_f32_e32 v166, v166
	v_rcp_f32_e32 v167, v167
	v_rcp_f32_e32 v175, v175
	v_add_f32_e32 v176, 1.0, v176
	v_add_f32_e32 v177, 1.0, v177
	v_add_f32_e32 v191, 1.0, v191
	v_add_f32_e32 v193, 1.0, v193
	v_exp_f32_e32 v229, v229
	v_exp_f32_e32 v230, v230
	v_exp_f32_e32 v231, v231
	v_exp_f32_e32 v232, v232
	v_exp_f32_e32 v233, v233
	v_mul_f32_e32 v236, v93, v234
	v_mul_f32_e32 v234, v94, v235
	v_mul_f32_e32 v235, v95, v237
	v_add_f32_e32 v237, 1.0, v238
	v_mul_f32_e32 v238, 0xbfb8aa3b, v97
	v_mul_f32_e32 v239, 0xbfb8aa3b, v98
	global_store_dwordx4 v[154:155], v[168:171], off nt
	v_cvt_pk_bf16_f32 v150, v150, v151
	v_mul_f32_e32 v158, v48, v158
	v_mul_f32_e32 v159, v49, v159
	v_mul_f32_e32 v160, v50, v160
	v_mul_f32_e32 v162, v51, v162
	v_mul_f32_e32 v163, v52, v163
	v_mul_f32_e32 v164, v53, v164
	v_rcp_f32_e32 v176, v176
	v_rcp_f32_e32 v177, v177
	v_rcp_f32_e32 v190, v190
	v_rcp_f32_e32 v191, v191
	v_rcp_f32_e32 v193, v193
	v_add_f32_e32 v196, 1.0, v196
	v_add_f32_e32 v198, 1.0, v198
	v_add_f32_e32 v199, 1.0, v199
	v_exp_f32_e32 v238, v238
	v_exp_f32_e32 v239, v239
	v_mul_f32_e32 v194, 0xbfb8aa3b, v104
	v_mul_f32_e32 v192, 0xbfb8aa3b, v108
	v_mul_f32_e32 v168, v120, v152
	v_mul_f32_e32 v169, v121, v153
	v_cvt_pk_bf16_f32 v151, v158, v159
	v_cvt_pk_bf16_f32 v152, v160, v162
	v_cvt_pk_bf16_f32 v153, v163, v164
	global_store_dwordx4 v[154:155], v[150:153], off offset:256 nt
	v_rcp_f32_e32 v196, v196
	v_rcp_f32_e32 v198, v198
	v_or_b32_e32 v150, 48, v140
	v_rcp_f32_e32 v199, v199
	v_add_f32_e32 v212, 1.0, v212
	v_add_f32_e32 v213, 1.0, v213
	v_add_f32_e32 v216, 1.0, v216
	v_add_f32_e32 v217, 1.0, v217
	v_add_f32_e32 v218, 1.0, v218
	v_exp_f32_e32 v194, v194
	v_exp_f32_e32 v192, v192
	v_ashrrev_i32_e32 v151, 31, v150
	v_rcp_f32_e32 v211, v211
	v_rcp_f32_e32 v212, v212
	v_rcp_f32_e32 v213, v213
	v_rcp_f32_e32 v216, v216
	v_rcp_f32_e32 v217, v217
	v_rcp_f32_e32 v218, v218
	v_add_f32_e32 v219, 1.0, v219
	v_add_f32_e32 v220, 1.0, v220
	v_add_f32_e32 v221, 1.0, v221
	v_add_f32_e32 v222, 1.0, v222
	v_add_f32_e32 v223, 1.0, v223
	v_add_f32_e32 v224, 1.0, v224
	v_mul_f32_e32 v172, 0xbfb8aa3b, v131
	v_mul_f32_e32 v149, 0xbfb8aa3b, v124
	v_lshlrev_b64 v[150:151], 13, v[150:151]
	v_mul_f32_e32 v165, v54, v165
	v_mul_f32_e32 v166, v55, v166
	v_mul_f32_e32 v167, v56, v167
	v_mul_f32_e32 v175, v57, v175
	v_rcp_f32_e32 v219, v219
	v_rcp_f32_e32 v220, v220
	v_rcp_f32_e32 v221, v221
	v_rcp_f32_e32 v222, v222
	v_rcp_f32_e32 v223, v223
	v_rcp_f32_e32 v224, v224
	v_add_f32_e32 v229, 1.0, v229
	v_add_f32_e32 v230, 1.0, v230
	v_add_f32_e32 v231, 1.0, v231
	v_add_f32_e32 v232, 1.0, v232
	v_add_f32_e32 v233, 1.0, v233
	v_exp_f32_e32 v172, v172
	v_exp_f32_e32 v149, v149
	v_lshl_add_u64 v[154:155], v[146:147], 0, v[150:151]
	v_cvt_pk_bf16_f32 v150, v165, v166
	v_cvt_pk_bf16_f32 v151, v167, v175
	v_mul_f32_e32 v176, v58, v176
	v_mul_f32_e32 v177, v59, v177
	v_mul_f32_e32 v190, v63, v190
	v_mul_f32_e32 v191, v64, v191
	v_mul_f32_e32 v193, v65, v193
	v_rcp_f32_e32 v228, v228
	v_rcp_f32_e32 v229, v229
	v_rcp_f32_e32 v230, v230
	v_rcp_f32_e32 v231, v231
	v_rcp_f32_e32 v232, v232
	v_rcp_f32_e32 v233, v233
	v_add_f32_e32 v238, 1.0, v238
	v_add_f32_e32 v239, 1.0, v239
	v_cvt_pk_bf16_f32 v152, v176, v177
	v_cvt_pk_bf16_f32 v153, v185, v186
	global_store_dwordx4 v[154:155], v[150:153], off nt
	v_mul_f32_e32 v196, v66, v196
	v_mul_f32_e32 v198, v67, v198
	v_cvt_pk_bf16_f32 v150, v184, v190
	v_cvt_pk_bf16_f32 v151, v191, v193
	v_mul_f32_e32 v199, v68, v199
	v_rcp_f32_e32 v237, v237
	v_rcp_f32_e32 v238, v238
	v_rcp_f32_e32 v239, v239
	v_add_f32_e32 v194, 1.0, v194
	v_add_f32_e32 v192, 1.0, v192
	v_cvt_pk_bf16_f32 v152, v196, v198
	v_cvt_pk_bf16_f32 v153, v199, v210
	global_store_dwordx4 v[154:155], v[150:153], off offset:256 nt
	v_mul_f32_e32 v211, v72, v211
	v_mul_f32_e32 v212, v73, v212
	v_lshlrev_b64 v[150:151], 13, v[142:143]
	v_mul_f32_e32 v213, v74, v213
	v_mul_f32_e32 v216, v75, v216
	v_mul_f32_e32 v217, v76, v217
	v_mul_f32_e32 v218, v77, v218
	v_rcp_f32_e32 v194, v194
	v_rcp_f32_e32 v192, v192
	v_lshl_add_u64 v[146:147], v[146:147], 0, v[150:151]
	v_cvt_pk_bf16_f32 v150, v207, v208
	v_cvt_pk_bf16_f32 v151, v211, v212
	v_cvt_pk_bf16_f32 v152, v213, v216
	v_cvt_pk_bf16_f32 v153, v217, v218
	v_add_co_u32_e32 v154, vcc, s72, v144
	v_mul_f32_e32 v219, v78, v219
	v_mul_f32_e32 v220, v79, v220
	v_mul_f32_e32 v221, v80, v221
	v_mul_f32_e32 v222, v81, v222
	v_mul_f32_e32 v223, v82, v223
	v_mul_f32_e32 v224, v83, v224
	v_add_f32_e32 v172, 1.0, v172
	v_add_f32_e32 v149, 1.0, v149
	global_store_dwordx4 v[146:147], v[150:153], off nt
	s_mov_b64 s[26:27], 0x120000
	v_addc_co_u32_e32 v155, vcc, 0, v145, vcc
	v_cvt_pk_bf16_f32 v150, v219, v220
	v_cvt_pk_bf16_f32 v151, v221, v222
	v_cvt_pk_bf16_f32 v152, v223, v224
	v_cvt_pk_bf16_f32 v153, v226, v227
	global_store_dwordx4 v[146:147], v[150:153], off offset:256 nt
	v_mul_f32_e32 v228, v87, v228
	v_mul_f32_e32 v229, v88, v229
	v_mul_f32_e32 v230, v89, v230
	v_mul_f32_e32 v231, v90, v231
	v_mul_f32_e32 v232, v91, v232
	v_mul_f32_e32 v233, v92, v233
	v_rcp_f32_e32 v172, v172
	v_rcp_f32_e32 v149, v149
	v_rcp_f32_e32 v161, v189
	v_lshl_add_u64 v[146:147], v[144:145], 0, s[26:27]
	v_cvt_pk_bf16_f32 v150, v225, v228
	v_cvt_pk_bf16_f32 v151, v229, v230
	v_cvt_pk_bf16_f32 v152, v231, v232
	v_cvt_pk_bf16_f32 v153, v233, v236
	global_store_dwordx4 v[154:155], v[150:153], off nt
	s_mov_b64 s[26:27], 0x140000
	v_add_co_u32_e32 v154, vcc, s73, v144
	v_mul_f32_e32 v237, v96, v237
	v_mul_f32_e32 v238, v97, v238
	v_mul_f32_e32 v239, v98, v239
	v_mul_f32_e32 v195, v99, v195
	v_cvt_pk_bf16_f32 v150, v234, v235
	v_cvt_pk_bf16_f32 v151, v237, v238
	v_cvt_pk_bf16_f32 v152, v239, v195
	v_cvt_pk_bf16_f32 v153, v206, v209
	global_store_dwordx4 v[146:147], v[150:153], off offset:256 nt
	v_lshl_add_u64 v[146:147], v[144:145], 0, s[26:27]
	v_addc_co_u32_e32 v155, vcc, 0, v145, vcc
	s_mov_b64 s[26:27], 0x160000
	v_mul_f32_e32 v194, v104, v194
	v_mul_f32_e32 v192, v108, v192
	v_cvt_pk_bf16_f32 v150, v241, v242
	v_cvt_pk_bf16_f32 v151, v194, v197
	v_cvt_pk_bf16_f32 v152, v240, v243
	v_cvt_pk_bf16_f32 v153, v192, v204
	global_store_dwordx4 v[154:155], v[150:153], off nt
	v_lshl_add_u64 v[154:155], v[144:145], 0, s[26:27]
	v_add_co_u32_e32 v144, vcc, 0x160000, v144
	v_mul_f32_e32 v173, v117, v173
	v_cvt_pk_bf16_f32 v150, v205, v187
	v_cvt_pk_bf16_f32 v151, v244, v245
	v_cvt_pk_bf16_f32 v152, v182, v200
	v_cvt_pk_bf16_f32 v153, v201, v173
	global_store_dwordx4 v[146:147], v[150:153], off offset:256 nt
	v_addc_co_u32_e32 v145, vcc, 0, v145, vcc
	v_mul_f32_e32 v172, v131, v172
	v_mul_f32_e32 v149, v124, v149
	v_mul_f32_e32 v157, v118, v157
	v_mul_f32_e32 v161, v119, v161
	v_cvt_pk_bf16_f32 v150, v183, v172
	v_cvt_pk_bf16_f32 v151, v174, v202
	v_cvt_pk_bf16_f32 v152, v203, v178
	v_cvt_pk_bf16_f32 v153, v179, v180
	global_store_dwordx4 v[144:145], v[150:153], off nt
	v_cvt_pk_bf16_f32 v144, v181, v188
	v_cvt_pk_bf16_f32 v145, v149, v156
	v_cvt_pk_bf16_f32 v146, v157, v161
	v_cvt_pk_bf16_f32 v147, v168, v169
	global_store_dwordx4 v[154:155], v[144:147], off offset:256 nt
	s_mov_b64 s[26:27], 0

.LBB0_346:
	s_add_u32 s54, s33, 0xffffff80
	s_addc_u32 s55, s52, -1
	s_cmp_eq_u32 s53, 60
	s_cselect_b32 s28, s2, s33
	s_cselect_b32 s29, s1, s52
	s_cselect_b32 s31, s11, s23
	s_cselect_b32 s30, s15, s19
	s_add_u32 s24, s28, 0x80
	s_addc_u32 s25, s29, 0
	s_add_u32 s26, s30, 0x80
	s_addc_u32 s27, s31, 0
	s_add_i32 s56, 0, 0x10000
	s_add_i32 s57, 0, 0x14000
	v_add_u32_e32 v152, s56, v1
	v_add_u32_e32 v168, s57, v1
	ds_read_b128 v[140:143], v152
	ds_read_b128 v[144:147], v152 offset:1024
	ds_read_b128 v[148:151], v152 offset:2048
	ds_read_b128 v[152:155], v152 offset:3072
	ds_read_b128 v[156:159], v168
	ds_read_b128 v[160:163], v168 offset:1024
	ds_read_b128 v[164:167], v168 offset:2048
	ds_read_b128 v[168:171], v168 offset:3072
	s_add_u32 s54, s54, 0x100000
	s_addc_u32 s55, s55, 0
	v_lshl_add_u64 v[204:205], s[54:55], 0, v[2:3]
	s_add_i32 m0, s41, 0xc000
	ds_read_b128 v[172:175], v5
	ds_read_b128 v[176:179], v5 offset:1024
	ds_read_b128 v[180:183], v5 offset:2048
	ds_read_b128 v[184:187], v5 offset:3072
	ds_read_b128 v[188:191], v5 offset:4096
	ds_read_b128 v[192:195], v5 offset:5120
	ds_read_b128 v[196:199], v5 offset:6144
	ds_read_b128 v[200:203], v5 offset:7168
	global_load_lds_dwordx4 v[204:205], off
	v_lshl_add_u64 v[204:205], s[54:55], 0, v[136:137]
	s_add_i32 m0, s41, 0xe000
	s_nop 0
	global_load_lds_dwordx4 v[204:205], off
	s_waitcnt vmcnt(8)
	s_waitcnt lgkmcnt(0)
	s_barrier
	s_setprio 1
	v_mfma_f32_16x16x32_bf16 v[130:133], v[140:143], v[172:175], v[130:133]
	v_mfma_f32_16x16x32_bf16 v[126:129], v[148:151], v[172:175], v[126:129]
	v_mfma_f32_16x16x32_bf16 v[114:117], v[140:143], v[180:183], v[114:117]
	v_mfma_f32_16x16x32_bf16 v[110:113], v[148:151], v[180:183], v[110:113]
	v_mfma_f32_16x16x32_bf16 v[98:101], v[140:143], v[188:191], v[98:101]
	v_mfma_f32_16x16x32_bf16 v[94:97], v[148:151], v[188:191], v[94:97]
	v_mfma_f32_16x16x32_bf16 v[82:85], v[140:143], v[196:199], v[82:85]
	v_mfma_f32_16x16x32_bf16 v[78:81], v[148:151], v[196:199], v[78:81]
	v_mfma_f32_16x16x32_bf16 v[130:133], v[144:147], v[176:179], v[130:133]
	v_mfma_f32_16x16x32_bf16 v[126:129], v[152:155], v[176:179], v[126:129]
	v_mfma_f32_16x16x32_bf16 v[114:117], v[144:147], v[184:187], v[114:117]
	v_mfma_f32_16x16x32_bf16 v[110:113], v[152:155], v[184:187], v[110:113]
	v_mfma_f32_16x16x32_bf16 v[98:101], v[144:147], v[192:195], v[98:101]
	v_mfma_f32_16x16x32_bf16 v[94:97], v[152:155], v[192:195], v[94:97]
	v_mfma_f32_16x16x32_bf16 v[82:85], v[144:147], v[200:203], v[82:85]
	v_mfma_f32_16x16x32_bf16 v[78:81], v[152:155], v[200:203], v[78:81]
	s_setprio 0
	s_setprio 1
	v_mfma_f32_16x16x32_bf16 v[122:125], v[156:159], v[172:175], v[122:125]
	v_mfma_f32_16x16x32_bf16 v[118:121], v[164:167], v[172:175], v[118:121]
	v_mfma_f32_16x16x32_bf16 v[106:109], v[156:159], v[180:183], v[106:109]
	v_mfma_f32_16x16x32_bf16 v[102:105], v[164:167], v[180:183], v[102:105]
	v_mfma_f32_16x16x32_bf16 v[90:93], v[156:159], v[188:191], v[90:93]
	v_mfma_f32_16x16x32_bf16 v[86:89], v[164:167], v[188:191], v[86:89]
	v_mfma_f32_16x16x32_bf16 v[74:77], v[156:159], v[196:199], v[74:77]
	v_mfma_f32_16x16x32_bf16 v[70:73], v[164:167], v[196:199], v[70:73]
	v_mfma_f32_16x16x32_bf16 v[122:125], v[160:163], v[176:179], v[122:125]
	v_mfma_f32_16x16x32_bf16 v[118:121], v[168:171], v[176:179], v[118:121]
	v_mfma_f32_16x16x32_bf16 v[106:109], v[160:163], v[184:187], v[106:109]
	v_mfma_f32_16x16x32_bf16 v[102:105], v[168:171], v[184:187], v[102:105]
	v_mfma_f32_16x16x32_bf16 v[90:93], v[160:163], v[192:195], v[90:93]
	v_mfma_f32_16x16x32_bf16 v[86:89], v[168:171], v[192:195], v[86:89]
	v_mfma_f32_16x16x32_bf16 v[74:77], v[160:163], v[200:203], v[74:77]
	v_mfma_f32_16x16x32_bf16 v[70:73], v[168:171], v[200:203], v[70:73]
	s_setprio 0
	s_barrier
	s_add_i32 s54, s56, s38
	v_lshl_add_u64 v[204:205], s[30:31], 0, v[134:135]
	s_mov_b32 m0, s54
	ds_read_b128 v[172:175], v5 offset:16384
	ds_read_b128 v[176:179], v5 offset:17408
	ds_read_b128 v[180:183], v5 offset:18432
	ds_read_b128 v[184:187], v5 offset:19456
	ds_read_b128 v[188:191], v5 offset:20480
	ds_read_b128 v[192:195], v5 offset:21504
	ds_read_b128 v[196:199], v5 offset:22528
	ds_read_b128 v[200:203], v5 offset:23552
	global_load_lds_dwordx4 v[204:205], off
	s_add_i32 m0, s54, 0x2000
	v_lshl_add_u64 v[204:205], s[30:31], 0, v[138:139]
	s_add_u32 s30, s30, 0x100000
	s_addc_u32 s31, s31, 0
	s_add_i32 s54, s57, s38
	global_load_lds_dwordx4 v[204:205], off
	v_lshl_add_u64 v[204:205], s[30:31], 0, v[134:135]
	s_mov_b32 m0, s54
	s_nop 0
	global_load_lds_dwordx4 v[204:205], off
	v_lshl_add_u64 v[204:205], s[30:31], 0, v[138:139]
	s_add_i32 m0, s54, 0x2000
	s_nop 0
	global_load_lds_dwordx4 v[204:205], off
	v_lshl_add_u64 v[204:205], s[28:29], 0, v[2:3]
	s_mov_b32 m0, s41
	s_nop 0
	global_load_lds_dwordx4 v[204:205], off
	v_lshl_add_u64 v[204:205], s[28:29], 0, v[136:137]
	s_mov_b32 m0, s3
	s_nop 0
	global_load_lds_dwordx4 v[204:205], off
	s_waitcnt vmcnt(8)
	s_waitcnt lgkmcnt(0)
	s_barrier
	s_setprio 1
	v_mfma_f32_16x16x32_bf16 v[66:69], v[140:143], v[172:175], v[66:69]
	v_mfma_f32_16x16x32_bf16 v[62:65], v[148:151], v[172:175], v[62:65]
	v_mfma_f32_16x16x32_bf16 v[50:53], v[140:143], v[180:183], v[50:53]
	v_mfma_f32_16x16x32_bf16 v[46:49], v[148:151], v[180:183], v[46:49]
	v_mfma_f32_16x16x32_bf16 v[34:37], v[140:143], v[188:191], v[34:37]
	v_mfma_f32_16x16x32_bf16 v[30:33], v[148:151], v[188:191], v[30:33]
	v_mfma_f32_16x16x32_bf16 v[18:21], v[140:143], v[196:199], v[18:21]
	v_mfma_f32_16x16x32_bf16 v[14:17], v[148:151], v[196:199], v[14:17]
	v_mfma_f32_16x16x32_bf16 v[66:69], v[144:147], v[176:179], v[66:69]
	v_mfma_f32_16x16x32_bf16 v[62:65], v[152:155], v[176:179], v[62:65]
	v_mfma_f32_16x16x32_bf16 v[50:53], v[144:147], v[184:187], v[50:53]
	v_mfma_f32_16x16x32_bf16 v[46:49], v[152:155], v[184:187], v[46:49]
	v_mfma_f32_16x16x32_bf16 v[34:37], v[144:147], v[192:195], v[34:37]
	v_mfma_f32_16x16x32_bf16 v[30:33], v[152:155], v[192:195], v[30:33]
	v_mfma_f32_16x16x32_bf16 v[18:21], v[144:147], v[200:203], v[18:21]
	v_mfma_f32_16x16x32_bf16 v[14:17], v[152:155], v[200:203], v[14:17]
	s_setprio 0
	s_setprio 1
	v_mfma_f32_16x16x32_bf16 v[58:61], v[156:159], v[172:175], v[58:61]
	v_mfma_f32_16x16x32_bf16 v[54:57], v[164:167], v[172:175], v[54:57]
	v_mfma_f32_16x16x32_bf16 v[42:45], v[156:159], v[180:183], v[42:45]
	v_mfma_f32_16x16x32_bf16 v[38:41], v[164:167], v[180:183], v[38:41]
	v_mfma_f32_16x16x32_bf16 v[26:29], v[156:159], v[188:191], v[26:29]
	v_mfma_f32_16x16x32_bf16 v[22:25], v[164:167], v[188:191], v[22:25]
	v_mfma_f32_16x16x32_bf16 v[10:13], v[156:159], v[196:199], v[10:13]
	v_mfma_f32_16x16x32_bf16 v[6:9], v[164:167], v[196:199], v[6:9]
	v_mfma_f32_16x16x32_bf16 v[58:61], v[160:163], v[176:179], v[58:61]
	v_mfma_f32_16x16x32_bf16 v[54:57], v[168:171], v[176:179], v[54:57]
	v_mfma_f32_16x16x32_bf16 v[42:45], v[160:163], v[184:187], v[42:45]
	v_mfma_f32_16x16x32_bf16 v[38:41], v[168:171], v[184:187], v[38:41]
	v_mfma_f32_16x16x32_bf16 v[26:29], v[160:163], v[192:195], v[26:29]
	v_mfma_f32_16x16x32_bf16 v[22:25], v[168:171], v[192:195], v[22:25]
	v_mfma_f32_16x16x32_bf16 v[10:13], v[160:163], v[200:203], v[10:13]
	v_mfma_f32_16x16x32_bf16 v[6:9], v[168:171], v[200:203], v[6:9]
	s_setprio 0
	s_barrier
	s_add_i32 s30, 0, 0x18000
	s_add_i32 s31, 0, 0x1c000
	v_add_u32_e32 v152, s30, v1
	v_add_u32_e32 v168, s31, v1
	ds_read_b128 v[140:143], v152
	ds_read_b128 v[144:147], v152 offset:1024
	ds_read_b128 v[148:151], v152 offset:2048
	ds_read_b128 v[152:155], v152 offset:3072
	ds_read_b128 v[156:159], v168
	ds_read_b128 v[160:163], v168 offset:1024
	ds_read_b128 v[164:167], v168 offset:2048
	ds_read_b128 v[168:171], v168 offset:3072
	s_add_u32 s28, s28, 0x100000
	s_addc_u32 s29, s29, 0
	s_mov_b32 m0, s43
	v_lshl_add_u64 v[204:205], s[28:29], 0, v[2:3]
	ds_read_b128 v[172:175], v5 offset:32768
	ds_read_b128 v[176:179], v5 offset:33792
	ds_read_b128 v[180:183], v5 offset:34816
	ds_read_b128 v[184:187], v5 offset:35840
	ds_read_b128 v[188:191], v5 offset:36864
	ds_read_b128 v[192:195], v5 offset:37888
	ds_read_b128 v[196:199], v5 offset:38912
	ds_read_b128 v[200:203], v5 offset:39936
	global_load_lds_dwordx4 v[204:205], off
	v_lshl_add_u64 v[204:205], s[28:29], 0, v[136:137]
	s_mov_b32 m0, s46
	s_nop 0
	global_load_lds_dwordx4 v[204:205], off
	s_waitcnt vmcnt(8)
	s_waitcnt lgkmcnt(0)
	s_barrier
	s_setprio 1
	v_mfma_f32_16x16x32_bf16 v[130:133], v[140:143], v[172:175], v[130:133]
	v_mfma_f32_16x16x32_bf16 v[126:129], v[148:151], v[172:175], v[126:129]
	v_mfma_f32_16x16x32_bf16 v[114:117], v[140:143], v[180:183], v[114:117]
	v_mfma_f32_16x16x32_bf16 v[110:113], v[148:151], v[180:183], v[110:113]
	v_mfma_f32_16x16x32_bf16 v[98:101], v[140:143], v[188:191], v[98:101]
	v_mfma_f32_16x16x32_bf16 v[94:97], v[148:151], v[188:191], v[94:97]
	v_mfma_f32_16x16x32_bf16 v[82:85], v[140:143], v[196:199], v[82:85]
	v_mfma_f32_16x16x32_bf16 v[78:81], v[148:151], v[196:199], v[78:81]
	v_mfma_f32_16x16x32_bf16 v[130:133], v[144:147], v[176:179], v[130:133]
	v_mfma_f32_16x16x32_bf16 v[126:129], v[152:155], v[176:179], v[126:129]
	v_mfma_f32_16x16x32_bf16 v[114:117], v[144:147], v[184:187], v[114:117]
	v_mfma_f32_16x16x32_bf16 v[110:113], v[152:155], v[184:187], v[110:113]
	v_mfma_f32_16x16x32_bf16 v[98:101], v[144:147], v[192:195], v[98:101]
	v_mfma_f32_16x16x32_bf16 v[94:97], v[152:155], v[192:195], v[94:97]
	v_mfma_f32_16x16x32_bf16 v[82:85], v[144:147], v[200:203], v[82:85]
	v_mfma_f32_16x16x32_bf16 v[78:81], v[152:155], v[200:203], v[78:81]
	s_setprio 0
	s_setprio 1
	v_mfma_f32_16x16x32_bf16 v[122:125], v[156:159], v[172:175], v[122:125]
	v_mfma_f32_16x16x32_bf16 v[118:121], v[164:167], v[172:175], v[118:121]
	v_mfma_f32_16x16x32_bf16 v[106:109], v[156:159], v[180:183], v[106:109]
	v_mfma_f32_16x16x32_bf16 v[102:105], v[164:167], v[180:183], v[102:105]
	v_mfma_f32_16x16x32_bf16 v[90:93], v[156:159], v[188:191], v[90:93]
	v_mfma_f32_16x16x32_bf16 v[86:89], v[164:167], v[188:191], v[86:89]
	v_mfma_f32_16x16x32_bf16 v[74:77], v[156:159], v[196:199], v[74:77]
	v_mfma_f32_16x16x32_bf16 v[70:73], v[164:167], v[196:199], v[70:73]
	v_mfma_f32_16x16x32_bf16 v[122:125], v[160:163], v[176:179], v[122:125]
	v_mfma_f32_16x16x32_bf16 v[118:121], v[168:171], v[176:179], v[118:121]
	v_mfma_f32_16x16x32_bf16 v[106:109], v[160:163], v[184:187], v[106:109]
	v_mfma_f32_16x16x32_bf16 v[102:105], v[168:171], v[184:187], v[102:105]
	v_mfma_f32_16x16x32_bf16 v[90:93], v[160:163], v[192:195], v[90:93]
	v_mfma_f32_16x16x32_bf16 v[86:89], v[168:171], v[192:195], v[86:89]
	v_mfma_f32_16x16x32_bf16 v[74:77], v[160:163], v[200:203], v[74:77]
	v_mfma_f32_16x16x32_bf16 v[70:73], v[168:171], v[200:203], v[70:73]
	s_setprio 0
	s_barrier
	s_add_i32 s28, s30, s38
	v_lshl_add_u64 v[204:205], s[26:27], 0, v[134:135]
	s_mov_b32 m0, s28
	ds_read_b128 v[172:175], v5 offset:49152
	ds_read_b128 v[176:179], v5 offset:50176
	ds_read_b128 v[180:183], v5 offset:51200
	ds_read_b128 v[184:187], v5 offset:52224
	ds_read_b128 v[188:191], v5 offset:53248
	ds_read_b128 v[192:195], v5 offset:54272
	ds_read_b128 v[196:199], v5 offset:55296
	ds_read_b128 v[200:203], v5 offset:56320
	global_load_lds_dwordx4 v[204:205], off
	s_add_i32 m0, s28, 0x2000
	v_lshl_add_u64 v[204:205], s[26:27], 0, v[138:139]
	s_add_u32 s26, s26, 0x100000
	s_addc_u32 s27, s27, 0
	s_add_i32 s28, s31, s38
	global_load_lds_dwordx4 v[204:205], off
	v_lshl_add_u64 v[204:205], s[26:27], 0, v[134:135]
	s_mov_b32 m0, s28
	s_nop 0
	global_load_lds_dwordx4 v[204:205], off
	v_lshl_add_u64 v[204:205], s[26:27], 0, v[138:139]
	s_add_i32 m0, s28, 0x2000
	s_nop 0
	global_load_lds_dwordx4 v[204:205], off
	v_lshl_add_u64 v[204:205], s[24:25], 0, v[2:3]
	s_mov_b32 m0, s49
	s_nop 0
	global_load_lds_dwordx4 v[204:205], off
	v_lshl_add_u64 v[204:205], s[24:25], 0, v[136:137]
	s_mov_b32 m0, s50
	s_nop 0
	global_load_lds_dwordx4 v[204:205], off
	s_waitcnt vmcnt(8)
	s_waitcnt lgkmcnt(0)
	s_barrier
	s_setprio 1
	v_mfma_f32_16x16x32_bf16 v[66:69], v[140:143], v[172:175], v[66:69]
	v_mfma_f32_16x16x32_bf16 v[62:65], v[148:151], v[172:175], v[62:65]
	v_mfma_f32_16x16x32_bf16 v[50:53], v[140:143], v[180:183], v[50:53]
	v_mfma_f32_16x16x32_bf16 v[46:49], v[148:151], v[180:183], v[46:49]
	v_mfma_f32_16x16x32_bf16 v[34:37], v[140:143], v[188:191], v[34:37]
	v_mfma_f32_16x16x32_bf16 v[30:33], v[148:151], v[188:191], v[30:33]
	v_mfma_f32_16x16x32_bf16 v[18:21], v[140:143], v[196:199], v[18:21]
	v_mfma_f32_16x16x32_bf16 v[14:17], v[148:151], v[196:199], v[14:17]
	v_mfma_f32_16x16x32_bf16 v[66:69], v[144:147], v[176:179], v[66:69]
	v_mfma_f32_16x16x32_bf16 v[62:65], v[152:155], v[176:179], v[62:65]
	v_mfma_f32_16x16x32_bf16 v[50:53], v[144:147], v[184:187], v[50:53]
	v_mfma_f32_16x16x32_bf16 v[46:49], v[152:155], v[184:187], v[46:49]
	v_mfma_f32_16x16x32_bf16 v[34:37], v[144:147], v[192:195], v[34:37]
	v_mfma_f32_16x16x32_bf16 v[30:33], v[152:155], v[192:195], v[30:33]
	v_mfma_f32_16x16x32_bf16 v[18:21], v[144:147], v[200:203], v[18:21]
	v_mfma_f32_16x16x32_bf16 v[14:17], v[152:155], v[200:203], v[14:17]
	s_setprio 0
	s_setprio 1
	v_mfma_f32_16x16x32_bf16 v[58:61], v[156:159], v[172:175], v[58:61]
	v_mfma_f32_16x16x32_bf16 v[54:57], v[164:167], v[172:175], v[54:57]
	v_mfma_f32_16x16x32_bf16 v[42:45], v[156:159], v[180:183], v[42:45]
	v_mfma_f32_16x16x32_bf16 v[38:41], v[164:167], v[180:183], v[38:41]
	v_mfma_f32_16x16x32_bf16 v[26:29], v[156:159], v[188:191], v[26:29]
	v_mfma_f32_16x16x32_bf16 v[22:25], v[164:167], v[188:191], v[22:25]
	v_mfma_f32_16x16x32_bf16 v[10:13], v[156:159], v[196:199], v[10:13]
	v_mfma_f32_16x16x32_bf16 v[6:9], v[164:167], v[196:199], v[6:9]
	v_mfma_f32_16x16x32_bf16 v[58:61], v[160:163], v[176:179], v[58:61]
	v_mfma_f32_16x16x32_bf16 v[54:57], v[168:171], v[176:179], v[54:57]
	v_mfma_f32_16x16x32_bf16 v[42:45], v[160:163], v[184:187], v[42:45]
	v_mfma_f32_16x16x32_bf16 v[38:41], v[168:171], v[184:187], v[38:41]
	v_mfma_f32_16x16x32_bf16 v[26:29], v[160:163], v[192:195], v[26:29]
	v_mfma_f32_16x16x32_bf16 v[22:25], v[168:171], v[192:195], v[22:25]
	v_mfma_f32_16x16x32_bf16 v[10:13], v[160:163], v[200:203], v[10:13]
	v_mfma_f32_16x16x32_bf16 v[6:9], v[168:171], v[200:203], v[6:9]
	s_setprio 0
	s_barrier
	s_add_i32 s53, s53, 2
	s_add_u32 s19, s19, 0x100
	s_addc_u32 s23, s23, 0
	s_add_u32 s33, s33, 0x100
	s_addc_u32 s52, s52, 0
	s_cmp_gt_u32 s53, 61
	s_cbranch_scc0 .LBB0_346
	v_mov_b32_e32 v140, v0
	s_lshl_b32 s1, s0, 8
	s_mov_b64 s[24:25], s[84:85]
	s_add_i32 s1, s1, s47
	v_bfe_u32 v210, v140, 4, 2
	v_and_or_b32 v140, v140, 15, s1
	s_add_u32 s26, s24, s6
	s_addc_u32 s27, s25, s7
	v_ashrrev_i32_e32 v141, 31, v140
	v_lshl_add_u64 v[142:143], v[140:141], 2, s[26:27]
	s_mov_b64 s[26:27], 0x10000
	v_lshl_add_u64 v[154:155], v[142:143], 0, s[26:27]
	v_add_co_u32_e32 v142, vcc, s91, v142
	s_cmp_gt_i32 s22, 3
	s_nop 0
	v_addc_co_u32_e32 v143, vcc, 0, v143, vcc
	global_load_dword v142, v[142:143], off
	s_cselect_b64 s[28:29], -1, 0
	s_cmp_lt_i32 s22, 4
	s_cselect_b64 s[26:27], -1, 0
	global_load_dword v205, v[154:155], off offset:64
	global_load_dword v204, v[154:155], off offset:128
	global_load_dword v203, v[154:155], off offset:192
	global_load_dword v202, v[154:155], off offset:512
	global_load_dword v201, v[154:155], off offset:576
	global_load_dword v200, v[154:155], off offset:640
	global_load_dword v199, v[154:155], off offset:704
	s_waitcnt vmcnt(0)
	v_fmamk_f32 v142, v142, 0x39800000, v246
	v_cmp_gt_f32_e32 vcc, s95, v142
	v_mul_f32_e32 v143, 0x4b800000, v142
	s_nop 0
	v_cndmask_b32_e32 v142, v142, v143, vcc
	v_rsq_f32_e32 v142, v142
	s_nop 0
	v_mul_f32_e32 v143, 0x45800000, v142
	v_cndmask_b32_e32 v142, v142, v143, vcc
	v_pk_mul_f32 v[132:133], v[132:133], v[142:143] op_sel_hi:[1,0]
	v_pk_mul_f32 v[130:131], v[130:131], v[142:143] op_sel_hi:[1,0]
	v_pk_mul_f32 v[128:129], v[128:129], v[142:143] op_sel_hi:[1,0]
	v_pk_mul_f32 v[126:127], v[126:127], v[142:143] op_sel_hi:[1,0]
	v_pk_mul_f32 v[124:125], v[124:125], v[142:143] op_sel_hi:[1,0]
	v_pk_mul_f32 v[122:123], v[122:123], v[142:143] op_sel_hi:[1,0]
	v_pk_mul_f32 v[120:121], v[120:121], v[142:143] op_sel_hi:[1,0]
	v_pk_mul_f32 v[118:119], v[118:119], v[142:143] op_sel_hi:[1,0]
	s_waitcnt vmcnt(0)
	v_fmamk_f32 v142, v205, 0x39800000, v246
	v_cmp_gt_f32_e32 vcc, s95, v142
	v_mul_f32_e32 v143, 0x4b800000, v142
	s_nop 0
	v_cndmask_b32_e32 v142, v142, v143, vcc
	v_rsq_f32_e32 v142, v142
	s_nop 0
	v_mul_f32_e32 v143, 0x45800000, v142
	v_cndmask_b32_e32 v142, v142, v143, vcc
	v_pk_mul_f32 v[116:117], v[116:117], v[142:143] op_sel_hi:[1,0]
	v_pk_mul_f32 v[114:115], v[114:115], v[142:143] op_sel_hi:[1,0]
	v_pk_mul_f32 v[112:113], v[112:113], v[142:143] op_sel_hi:[1,0]
	v_pk_mul_f32 v[110:111], v[110:111], v[142:143] op_sel_hi:[1,0]
	v_pk_mul_f32 v[108:109], v[108:109], v[142:143] op_sel_hi:[1,0]
	v_pk_mul_f32 v[106:107], v[106:107], v[142:143] op_sel_hi:[1,0]
	v_pk_mul_f32 v[104:105], v[104:105], v[142:143] op_sel_hi:[1,0]
	v_pk_mul_f32 v[102:103], v[102:103], v[142:143] op_sel_hi:[1,0]
	s_waitcnt vmcnt(0)
	v_fmamk_f32 v142, v204, 0x39800000, v246
	v_cmp_gt_f32_e32 vcc, s95, v142
	v_mul_f32_e32 v143, 0x4b800000, v142
	s_nop 0
	v_cndmask_b32_e32 v142, v142, v143, vcc
	v_rsq_f32_e32 v142, v142
	s_nop 0
	v_mul_f32_e32 v143, 0x45800000, v142
	v_cndmask_b32_e32 v142, v142, v143, vcc
	v_pk_mul_f32 v[150:151], v[94:95], v[142:143] op_sel_hi:[1,0]
	v_pk_mul_f32 v[152:153], v[98:99], v[142:143] op_sel_hi:[1,0]
	v_pk_mul_f32 v[100:101], v[100:101], v[142:143] op_sel_hi:[1,0]
	v_pk_mul_f32 v[92:93], v[92:93], v[142:143] op_sel_hi:[1,0]
	v_pk_mul_f32 v[90:91], v[90:91], v[142:143] op_sel_hi:[1,0]
	v_pk_mul_f32 v[86:87], v[86:87], v[142:143] op_sel_hi:[1,0]
	v_pk_mul_f32 v[96:97], v[96:97], v[142:143] op_sel_hi:[1,0]
	v_pk_mul_f32 v[88:89], v[88:89], v[142:143] op_sel_hi:[1,0]
	s_waitcnt vmcnt(0)
	v_fmamk_f32 v94, v203, 0x39800000, v246
	v_cmp_gt_f32_e32 vcc, s95, v94
	v_mul_f32_e32 v95, 0x4b800000, v94
	s_nop 0
	v_cndmask_b32_e32 v94, v94, v95, vcc
	v_rsq_f32_e32 v94, v94
	s_nop 0
	v_mul_f32_e32 v95, 0x45800000, v94
	v_cndmask_b32_e32 v94, v94, v95, vcc
	v_pk_mul_f32 v[164:165], v[80:81], v[94:95] op_sel_hi:[1,0]
	v_pk_mul_f32 v[80:81], v[74:75], v[94:95] op_sel_hi:[1,0]
	v_pk_mul_f32 v[166:167], v[84:85], v[94:95] op_sel_hi:[1,0]
	v_pk_mul_f32 v[170:171], v[82:83], v[94:95] op_sel_hi:[1,0]
	v_pk_mul_f32 v[168:169], v[78:79], v[94:95] op_sel_hi:[1,0]
	v_pk_mul_f32 v[78:79], v[76:77], v[94:95] op_sel_hi:[1,0]
	v_pk_mul_f32 v[72:73], v[72:73], v[94:95] op_sel_hi:[1,0]
	v_pk_mul_f32 v[70:71], v[70:71], v[94:95] op_sel_hi:[1,0]
	s_waitcnt vmcnt(0)
	v_fmamk_f32 v74, v202, 0x39800000, v246
	v_cmp_gt_f32_e32 vcc, s95, v74
	v_mul_f32_e32 v75, 0x4b800000, v74
	s_nop 0
	v_cndmask_b32_e32 v74, v74, v75, vcc
	v_rsq_f32_e32 v74, v74
	s_nop 0
	v_mul_f32_e32 v75, 0x45800000, v74
	v_cndmask_b32_e32 v98, v74, v75, vcc
	v_pk_mul_f32 v[76:77], v[68:69], v[98:99] op_sel_hi:[1,0]
	v_pk_mul_f32 v[176:177], v[66:67], v[98:99] op_sel_hi:[1,0]
	v_pk_mul_f32 v[74:75], v[64:65], v[98:99] op_sel_hi:[1,0]
	v_pk_mul_f32 v[174:175], v[62:63], v[98:99] op_sel_hi:[1,0]
	v_pk_mul_f32 v[84:85], v[60:61], v[98:99] op_sel_hi:[1,0]
	v_pk_mul_f32 v[94:95], v[58:59], v[98:99] op_sel_hi:[1,0]
	v_pk_mul_f32 v[82:83], v[56:57], v[98:99] op_sel_hi:[1,0]
	v_pk_mul_f32 v[98:99], v[54:55], v[98:99] op_sel_hi:[1,0]
	s_waitcnt vmcnt(0)
	v_fmamk_f32 v54, v201, 0x39800000, v246
	v_cmp_gt_f32_e32 vcc, s95, v54
	v_mul_f32_e32 v55, 0x4b800000, v54
	s_nop 0
	v_cndmask_b32_e32 v54, v54, v55, vcc
	v_rsq_f32_e32 v54, v54
	s_nop 0
	v_mul_f32_e32 v55, 0x45800000, v54
	v_cndmask_b32_e32 v54, v54, v55, vcc
	v_pk_mul_f32 v[146:147], v[38:39], v[54:55] op_sel_hi:[1,0]
	v_pk_mul_f32 v[180:181], v[52:53], v[54:55] op_sel_hi:[1,0]
	v_pk_mul_f32 v[184:185], v[50:51], v[54:55] op_sel_hi:[1,0]
	v_pk_mul_f32 v[144:145], v[44:45], v[54:55] op_sel_hi:[1,0]
	v_pk_mul_f32 v[148:149], v[42:43], v[54:55] op_sel_hi:[1,0]
	v_pk_mul_f32 v[182:183], v[46:47], v[54:55] op_sel_hi:[1,0]
	v_pk_mul_f32 v[178:179], v[48:49], v[54:55] op_sel_hi:[1,0]
	v_pk_mul_f32 v[142:143], v[40:41], v[54:55] op_sel_hi:[1,0]
	s_waitcnt vmcnt(0)
	v_fmamk_f32 v38, v200, 0x39800000, v246
	v_cmp_gt_f32_e32 vcc, s95, v38
	v_mul_f32_e32 v39, 0x4b800000, v38
	s_nop 0
	v_cndmask_b32_e32 v38, v38, v39, vcc
	v_rsq_f32_e32 v38, v38
	s_nop 0
	v_mul_f32_e32 v39, 0x45800000, v38
	v_cndmask_b32_e32 v38, v38, v39, vcc
	v_pk_mul_f32 v[160:161], v[22:23], v[38:39] op_sel_hi:[1,0]
	v_pk_mul_f32 v[188:189], v[36:37], v[38:39] op_sel_hi:[1,0]
	v_pk_mul_f32 v[192:193], v[34:35], v[38:39] op_sel_hi:[1,0]
	v_pk_mul_f32 v[158:159], v[28:29], v[38:39] op_sel_hi:[1,0]
	v_pk_mul_f32 v[162:163], v[26:27], v[38:39] op_sel_hi:[1,0]
	v_pk_mul_f32 v[186:187], v[32:33], v[38:39] op_sel_hi:[1,0]
	v_pk_mul_f32 v[190:191], v[30:31], v[38:39] op_sel_hi:[1,0]
	v_pk_mul_f32 v[156:157], v[24:25], v[38:39] op_sel_hi:[1,0]
	v_mul_f32_e32 v24, v95, v95
	v_mul_f32_e32 v25, v85, v85
	v_mul_f32_e32 v26, v185, v185
	v_mul_f32_e32 v27, v181, v181
	v_mul_f32_e32 v28, v149, v149
	v_mul_f32_e32 v29, v145, v145
	v_mul_f32_e32 v30, v193, v193
	v_mul_f32_e32 v31, v189, v189
	v_mul_f32_e32 v32, v163, v163
	v_mul_f32_e32 v33, v159, v159
	v_fmac_f32_e32 v24, v94, v94
	v_fmac_f32_e32 v25, v84, v84
	v_fmac_f32_e32 v26, v184, v184
	v_fmac_f32_e32 v27, v180, v180
	v_fmac_f32_e32 v28, v148, v148
	v_fmac_f32_e32 v29, v144, v144
	v_fmac_f32_e32 v30, v192, v192
	v_fmac_f32_e32 v31, v188, v188
	v_fmac_f32_e32 v32, v162, v162
	v_fmac_f32_e32 v33, v158, v158
	v_add_f32_e32 v24, v24, v25
	v_mul_f32_e32 v25, v99, v99
	v_add_f32_e32 v26, v26, v27
	v_mul_f32_e32 v27, v183, v183
	v_add_f32_e32 v28, v28, v29
	v_mul_f32_e32 v29, v147, v147
	v_add_f32_e32 v30, v30, v31
	v_mul_f32_e32 v31, v191, v191
	v_add_f32_e32 v32, v32, v33
	v_mul_f32_e32 v33, v161, v161
	v_fmac_f32_e32 v25, v98, v98
	v_fmac_f32_e32 v27, v182, v182
	v_fmac_f32_e32 v29, v146, v146
	v_fmac_f32_e32 v31, v190, v190
	v_fmac_f32_e32 v33, v160, v160
	v_add_f32_e32 v24, v25, v24
	v_mul_f32_e32 v25, v83, v83
	v_add_f32_e32 v26, v27, v26
	v_mul_f32_e32 v27, v179, v179
	v_add_f32_e32 v28, v29, v28
	v_mul_f32_e32 v29, v143, v143
	v_add_f32_e32 v30, v31, v30
	v_mul_f32_e32 v31, v187, v187
	v_add_f32_e32 v32, v33, v32
	v_mul_f32_e32 v33, v157, v157
	v_fmac_f32_e32 v25, v82, v82
	v_fmac_f32_e32 v27, v178, v178
	v_fmac_f32_e32 v29, v142, v142
	v_fmac_f32_e32 v31, v186, v186
	v_fmac_f32_e32 v33, v156, v156
	v_add_f32_e32 v24, v25, v24
	v_add_f32_e32 v26, v27, v26
	v_add_f32_e32 v28, v29, v28
	v_add_f32_e32 v30, v31, v30
	v_add_f32_e32 v32, v33, v32
	ds_swizzle_b32 v25, v24 offset:swizzle(SWAP,16)
	ds_swizzle_b32 v27, v26 offset:swizzle(SWAP,16)
	ds_swizzle_b32 v29, v28 offset:swizzle(SWAP,16)
	ds_swizzle_b32 v31, v30 offset:swizzle(SWAP,16)
	ds_swizzle_b32 v33, v32 offset:swizzle(SWAP,16)
	s_waitcnt lgkmcnt(4)
	v_add_f32_e32 v24, v24, v25
	s_waitcnt lgkmcnt(3)
	v_add_f32_e32 v26, v26, v27
	s_waitcnt lgkmcnt(2)
	v_add_f32_e32 v28, v28, v29
	s_waitcnt lgkmcnt(1)
	v_add_f32_e32 v30, v30, v31
	s_waitcnt lgkmcnt(0)
	v_add_f32_e32 v32, v32, v33
	v_mov_b32_e32 v25, v24
	v_mov_b32_e32 v27, v26
	v_mov_b32_e32 v29, v28
	v_mov_b32_e32 v31, v30
	v_mov_b32_e32 v33, v32
	v_permlane32_swap_b32_e32 v24, v25
	s_waitcnt vmcnt(0)
	v_fmamk_f32 v22, v199, 0x39800000, v246
	v_cmp_gt_f32_e32 vcc, s95, v22
	v_mul_f32_e32 v23, 0x4b800000, v22
	v_permlane32_swap_b32_e32 v26, v27
	v_cndmask_b32_e32 v22, v22, v23, vcc
	v_rsq_f32_e32 v22, v22
	v_permlane32_swap_b32_e32 v28, v29
	v_permlane32_swap_b32_e32 v30, v31
	v_mul_f32_e32 v23, 0x45800000, v22
	v_cndmask_b32_e32 v22, v22, v23, vcc
	v_pk_mul_f32 v[202:203], v[20:21], v[22:23] op_sel_hi:[1,0]
	v_pk_mul_f32 v[204:205], v[18:19], v[22:23] op_sel_hi:[1,0]
	v_pk_mul_f32 v[194:195], v[12:13], v[22:23] op_sel_hi:[1,0]
	v_pk_mul_f32 v[196:197], v[10:11], v[22:23] op_sel_hi:[1,0]
	v_pk_mul_f32 v[206:207], v[16:17], v[22:23] op_sel_hi:[1,0]
	v_pk_mul_f32 v[208:209], v[14:15], v[22:23] op_sel_hi:[1,0]
	v_pk_mul_f32 v[198:199], v[8:9], v[22:23] op_sel_hi:[1,0]
	v_pk_mul_f32 v[200:201], v[6:7], v[22:23] op_sel_hi:[1,0]
	v_mul_f32_e32 v6, v131, v131
	v_mul_f32_e32 v7, v133, v133
	v_mul_f32_e32 v8, v123, v123
	v_mul_f32_e32 v9, v125, v125
	v_mul_f32_e32 v10, v115, v115
	v_mul_f32_e32 v11, v117, v117
	v_mul_f32_e32 v12, v107, v107
	v_mul_f32_e32 v13, v109, v109
	v_mul_f32_e32 v14, v153, v153
	v_mul_f32_e32 v15, v101, v101
	v_mul_f32_e32 v16, v91, v91
	v_mul_f32_e32 v17, v93, v93
	v_mul_f32_e32 v18, v171, v171
	v_mul_f32_e32 v19, v167, v167
	v_mul_f32_e32 v20, v81, v81
	v_mul_f32_e32 v21, v79, v79
	v_mul_f32_e32 v22, v177, v177
	v_mul_f32_e32 v23, v77, v77
	v_mul_f32_e32 v34, v205, v205
	v_mul_f32_e32 v35, v203, v203
	v_mul_f32_e32 v36, v197, v197
	v_mul_f32_e32 v37, v195, v195
	v_fmac_f32_e32 v6, v130, v130
	v_fmac_f32_e32 v7, v132, v132
	v_fmac_f32_e32 v8, v122, v122
	v_fmac_f32_e32 v9, v124, v124
	v_fmac_f32_e32 v10, v114, v114
	v_fmac_f32_e32 v11, v116, v116
	v_fmac_f32_e32 v12, v106, v106
	v_fmac_f32_e32 v13, v108, v108
	v_fmac_f32_e32 v14, v152, v152
	v_fmac_f32_e32 v15, v100, v100
	v_fmac_f32_e32 v16, v90, v90
	v_fmac_f32_e32 v17, v92, v92
	v_fmac_f32_e32 v18, v170, v170
	v_fmac_f32_e32 v19, v166, v166
	v_fmac_f32_e32 v20, v80, v80
	v_fmac_f32_e32 v21, v78, v78
	v_fmac_f32_e32 v22, v176, v176
	v_fmac_f32_e32 v23, v76, v76
	v_fmac_f32_e32 v34, v204, v204
	v_fmac_f32_e32 v35, v202, v202
	v_fmac_f32_e32 v36, v196, v196
	v_fmac_f32_e32 v37, v194, v194
	v_add_f32_e32 v6, v6, v7
	v_mul_f32_e32 v7, v127, v127
	v_add_f32_e32 v8, v8, v9
	v_mul_f32_e32 v9, v119, v119
	v_add_f32_e32 v10, v10, v11
	v_mul_f32_e32 v11, v111, v111
	v_add_f32_e32 v12, v12, v13
	v_mul_f32_e32 v13, v103, v103
	v_add_f32_e32 v14, v14, v15
	v_mul_f32_e32 v15, v151, v151
	v_add_f32_e32 v16, v16, v17
	v_mul_f32_e32 v17, v87, v87
	v_add_f32_e32 v18, v18, v19
	v_mul_f32_e32 v19, v169, v169
	v_add_f32_e32 v20, v20, v21
	v_mul_f32_e32 v21, v71, v71
	v_add_f32_e32 v22, v22, v23
	v_mul_f32_e32 v23, v175, v175
	v_add_f32_e32 v34, v34, v35
	v_mul_f32_e32 v35, v209, v209
	v_add_f32_e32 v36, v36, v37
	v_mul_f32_e32 v37, v201, v201
	v_fmac_f32_e32 v7, v126, v126
	v_fmac_f32_e32 v9, v118, v118
	v_fmac_f32_e32 v11, v110, v110
	v_fmac_f32_e32 v13, v102, v102
	v_fmac_f32_e32 v15, v150, v150
	v_fmac_f32_e32 v17, v86, v86
	v_fmac_f32_e32 v19, v168, v168
	v_fmac_f32_e32 v21, v70, v70
	v_fmac_f32_e32 v23, v174, v174
	v_fmac_f32_e32 v35, v208, v208
	v_fmac_f32_e32 v37, v200, v200
	v_add_f32_e32 v6, v7, v6
	v_mul_f32_e32 v7, v129, v129
	v_add_f32_e32 v8, v9, v8
	v_mul_f32_e32 v9, v121, v121
	v_add_f32_e32 v10, v11, v10
	v_mul_f32_e32 v11, v113, v113
	v_add_f32_e32 v12, v13, v12
	v_mul_f32_e32 v13, v105, v105
	v_add_f32_e32 v14, v15, v14
	v_mul_f32_e32 v15, v97, v97
	v_add_f32_e32 v16, v17, v16
	v_mul_f32_e32 v17, v89, v89
	v_add_f32_e32 v18, v19, v18
	v_mul_f32_e32 v19, v165, v165
	v_add_f32_e32 v20, v21, v20
	v_mul_f32_e32 v21, v73, v73
	v_add_f32_e32 v22, v23, v22
	v_mul_f32_e32 v23, v75, v75
	v_add_f32_e32 v34, v35, v34
	v_mul_f32_e32 v35, v207, v207
	v_add_f32_e32 v36, v37, v36
	v_mul_f32_e32 v37, v199, v199
	v_fmac_f32_e32 v7, v128, v128
	v_fmac_f32_e32 v9, v120, v120
	v_fmac_f32_e32 v11, v112, v112
	v_fmac_f32_e32 v13, v104, v104
	v_fmac_f32_e32 v15, v96, v96
	v_fmac_f32_e32 v17, v88, v88
	v_fmac_f32_e32 v19, v164, v164
	v_fmac_f32_e32 v21, v72, v72
	v_fmac_f32_e32 v23, v74, v74
	v_fmac_f32_e32 v35, v206, v206
	v_fmac_f32_e32 v37, v198, v198
	v_add_f32_e32 v6, v7, v6
	v_add_f32_e32 v8, v9, v8
	v_add_f32_e32 v10, v11, v10
	v_add_f32_e32 v12, v13, v12
	v_add_f32_e32 v14, v15, v14
	v_add_f32_e32 v16, v17, v16
	v_add_f32_e32 v18, v19, v18
	v_add_f32_e32 v20, v21, v20
	v_add_f32_e32 v22, v23, v22
	v_add_f32_e32 v34, v35, v34
	v_add_f32_e32 v36, v37, v36
	ds_swizzle_b32 v7, v6 offset:swizzle(SWAP,16)
	ds_swizzle_b32 v9, v8 offset:swizzle(SWAP,16)
	ds_swizzle_b32 v11, v10 offset:swizzle(SWAP,16)
	ds_swizzle_b32 v13, v12 offset:swizzle(SWAP,16)
	ds_swizzle_b32 v15, v14 offset:swizzle(SWAP,16)
	ds_swizzle_b32 v17, v16 offset:swizzle(SWAP,16)
	ds_swizzle_b32 v19, v18 offset:swizzle(SWAP,16)
	ds_swizzle_b32 v21, v20 offset:swizzle(SWAP,16)
	ds_swizzle_b32 v23, v22 offset:swizzle(SWAP,16)
	ds_swizzle_b32 v35, v34 offset:swizzle(SWAP,16)
	ds_swizzle_b32 v37, v36 offset:swizzle(SWAP,16)
	s_waitcnt lgkmcnt(10)
	v_add_f32_e32 v6, v6, v7
	s_waitcnt lgkmcnt(9)
	v_add_f32_e32 v8, v8, v9
	s_waitcnt lgkmcnt(8)
	v_add_f32_e32 v10, v10, v11
	s_waitcnt lgkmcnt(7)
	v_add_f32_e32 v12, v12, v13
	s_waitcnt lgkmcnt(6)
	v_add_f32_e32 v14, v14, v15
	s_waitcnt lgkmcnt(5)
	v_add_f32_e32 v16, v16, v17
	s_waitcnt lgkmcnt(4)
	v_add_f32_e32 v18, v18, v19
	s_waitcnt lgkmcnt(3)
	v_add_f32_e32 v20, v20, v21
	s_waitcnt lgkmcnt(2)
	v_add_f32_e32 v22, v22, v23
	s_waitcnt lgkmcnt(1)
	v_add_f32_e32 v34, v34, v35
	s_waitcnt lgkmcnt(0)
	v_add_f32_e32 v36, v36, v37
	v_mov_b32_e32 v7, v6
	v_mov_b32_e32 v9, v8
	v_mov_b32_e32 v11, v10
	v_mov_b32_e32 v13, v12
	v_mov_b32_e32 v15, v14
	v_mov_b32_e32 v17, v16
	v_mov_b32_e32 v19, v18
	v_mov_b32_e32 v21, v20
	v_mov_b32_e32 v23, v22
	v_mov_b32_e32 v35, v34
	v_mov_b32_e32 v37, v36
	v_permlane32_swap_b32_e32 v6, v7
	v_permlane32_swap_b32_e32 v8, v9
	v_permlane32_swap_b32_e32 v10, v11
	v_permlane32_swap_b32_e32 v12, v13
	v_permlane32_swap_b32_e32 v14, v15
	v_permlane32_swap_b32_e32 v16, v17
	v_permlane32_swap_b32_e32 v18, v19
	v_permlane32_swap_b32_e32 v20, v21
	v_permlane32_swap_b32_e32 v22, v23
	v_permlane32_swap_b32_e32 v32, v33
	v_permlane32_swap_b32_e32 v34, v35
	v_permlane32_swap_b32_e32 v36, v37
	v_cmp_eq_u32_e32 vcc, 0, v210
	s_and_saveexec_b64 s[30:31], vcc
	s_cbranch_execz .LBB0_349
	s_and_b64 s[52:53], s[28:29], exec
	s_mov_b32 s1, 0x31000
	s_cselect_b32 s1, s1, 0x20800
	s_add_u32 s1, s24, s1
	s_addc_u32 s2, s25, 0
	s_add_u32 s52, s1, s6
	v_add_f32_e32 v8, v8, v9
	v_add_f32_e32 v9, v6, v7
	s_addc_u32 s53, s2, s7
	v_add_f32_e32 v12, v12, v13
	v_add_f32_e32 v10, v10, v11
	v_lshl_add_u64 v[6:7], v[140:141], 2, s[52:53]
	v_add_f32_e32 v8, v9, v8
	v_add_f32_e32 v16, v16, v17
	v_add_f32_e32 v14, v14, v15
	global_atomic_add_f32 v[6:7], v8, off
	v_add_f32_e32 v8, v10, v12
	v_add_f32_e32 v20, v20, v21
	v_add_f32_e32 v18, v18, v19
	global_atomic_add_f32 v[6:7], v8, off offset:64
	v_add_f32_e32 v8, v14, v16
	v_add_f32_e32 v24, v24, v25
	v_add_f32_e32 v22, v22, v23
	global_atomic_add_f32 v[6:7], v8, off offset:128
	v_add_f32_e32 v8, v18, v20
	v_add_f32_e32 v28, v28, v29
	v_add_f32_e32 v26, v26, v27
	global_atomic_add_f32 v[6:7], v8, off offset:192
	v_add_f32_e32 v8, v22, v24
	v_add_f32_e32 v32, v32, v33
	v_add_f32_e32 v30, v30, v31
	global_atomic_add_f32 v[6:7], v8, off offset:512
	v_add_f32_e32 v8, v26, v28
	v_add_f32_e32 v36, v36, v37
	v_add_f32_e32 v34, v34, v35
	global_atomic_add_f32 v[6:7], v8, off offset:576
	v_add_f32_e32 v8, v30, v32
	global_atomic_add_f32 v[6:7], v8, off offset:640
	v_add_f32_e32 v8, v34, v36
	global_atomic_add_f32 v[6:7], v8, off offset:704

.LBB0_454:
	s_add_u32 s66, s62, 0xffffff80
	s_addc_u32 s67, s63, -1
	s_cmp_eq_u32 s64, 12
	s_cselect_b32 s38, s21, s62
	s_cselect_b32 s39, s3, s63
	s_cselect_b32 s41, s23, s61
	s_cselect_b32 s40, s31, s33
	s_add_u32 s34, s38, 0x80
	s_addc_u32 s35, s39, 0
	s_add_u32 s36, s40, 0x80
	s_addc_u32 s37, s41, 0
	s_add_i32 s65, 0, 0x10000
	s_add_i32 s68, 0, 0x14000
	v_add_u32_e32 v152, s65, v1
	v_add_u32_e32 v168, s68, v1
	ds_read_b128 v[140:143], v152
	ds_read_b128 v[144:147], v152 offset:1024
	ds_read_b128 v[148:151], v152 offset:2048
	ds_read_b128 v[152:155], v152 offset:3072
	ds_read_b128 v[156:159], v168
	ds_read_b128 v[160:163], v168 offset:1024
	ds_read_b128 v[164:167], v168 offset:2048
	ds_read_b128 v[168:171], v168 offset:3072
	s_add_u32 s66, s66, 0x40000
	s_addc_u32 s67, s67, 0
	v_lshl_add_u64 v[204:205], s[66:67], 0, v[2:3]
	s_add_i32 m0, s29, 0xc000
	ds_read_b128 v[172:175], v5
	ds_read_b128 v[176:179], v5 offset:1024
	ds_read_b128 v[180:183], v5 offset:2048
	ds_read_b128 v[184:187], v5 offset:3072
	ds_read_b128 v[188:191], v5 offset:4096
	ds_read_b128 v[192:195], v5 offset:5120
	ds_read_b128 v[196:199], v5 offset:6144
	ds_read_b128 v[200:203], v5 offset:7168
	global_load_lds_dwordx4 v[204:205], off
	v_lshl_add_u64 v[204:205], s[66:67], 0, v[136:137]
	s_add_i32 m0, s29, 0xe000
	s_nop 0
	global_load_lds_dwordx4 v[204:205], off
	s_waitcnt vmcnt(8)
	s_waitcnt lgkmcnt(0)
	s_barrier
	s_setprio 1
	v_mfma_f32_16x16x32_bf16 v[130:133], v[140:143], v[172:175], v[130:133]
	v_mfma_f32_16x16x32_bf16 v[126:129], v[148:151], v[172:175], v[126:129]
	v_mfma_f32_16x16x32_bf16 v[114:117], v[140:143], v[180:183], v[114:117]
	v_mfma_f32_16x16x32_bf16 v[110:113], v[148:151], v[180:183], v[110:113]
	v_mfma_f32_16x16x32_bf16 v[98:101], v[140:143], v[188:191], v[98:101]
	v_mfma_f32_16x16x32_bf16 v[94:97], v[148:151], v[188:191], v[94:97]
	v_mfma_f32_16x16x32_bf16 v[82:85], v[140:143], v[196:199], v[82:85]
	v_mfma_f32_16x16x32_bf16 v[78:81], v[148:151], v[196:199], v[78:81]
	v_mfma_f32_16x16x32_bf16 v[130:133], v[144:147], v[176:179], v[130:133]
	v_mfma_f32_16x16x32_bf16 v[126:129], v[152:155], v[176:179], v[126:129]
	v_mfma_f32_16x16x32_bf16 v[114:117], v[144:147], v[184:187], v[114:117]
	v_mfma_f32_16x16x32_bf16 v[110:113], v[152:155], v[184:187], v[110:113]
	v_mfma_f32_16x16x32_bf16 v[98:101], v[144:147], v[192:195], v[98:101]
	v_mfma_f32_16x16x32_bf16 v[94:97], v[152:155], v[192:195], v[94:97]
	v_mfma_f32_16x16x32_bf16 v[82:85], v[144:147], v[200:203], v[82:85]
	v_mfma_f32_16x16x32_bf16 v[78:81], v[152:155], v[200:203], v[78:81]
	s_setprio 0
	s_setprio 1
	v_mfma_f32_16x16x32_bf16 v[122:125], v[156:159], v[172:175], v[122:125]
	v_mfma_f32_16x16x32_bf16 v[118:121], v[164:167], v[172:175], v[118:121]
	v_mfma_f32_16x16x32_bf16 v[106:109], v[156:159], v[180:183], v[106:109]
	v_mfma_f32_16x16x32_bf16 v[102:105], v[164:167], v[180:183], v[102:105]
	v_mfma_f32_16x16x32_bf16 v[90:93], v[156:159], v[188:191], v[90:93]
	v_mfma_f32_16x16x32_bf16 v[86:89], v[164:167], v[188:191], v[86:89]
	v_mfma_f32_16x16x32_bf16 v[74:77], v[156:159], v[196:199], v[74:77]
	v_mfma_f32_16x16x32_bf16 v[70:73], v[164:167], v[196:199], v[70:73]
	v_mfma_f32_16x16x32_bf16 v[122:125], v[160:163], v[176:179], v[122:125]
	v_mfma_f32_16x16x32_bf16 v[118:121], v[168:171], v[176:179], v[118:121]
	v_mfma_f32_16x16x32_bf16 v[106:109], v[160:163], v[184:187], v[106:109]
	v_mfma_f32_16x16x32_bf16 v[102:105], v[168:171], v[184:187], v[102:105]
	v_mfma_f32_16x16x32_bf16 v[90:93], v[160:163], v[192:195], v[90:93]
	v_mfma_f32_16x16x32_bf16 v[86:89], v[168:171], v[192:195], v[86:89]
	v_mfma_f32_16x16x32_bf16 v[74:77], v[160:163], v[200:203], v[74:77]
	v_mfma_f32_16x16x32_bf16 v[70:73], v[168:171], v[200:203], v[70:73]
	s_setprio 0
	s_barrier
	s_add_i32 s65, s65, s46
	v_lshl_add_u64 v[204:205], s[40:41], 0, v[134:135]
	s_mov_b32 m0, s65
	ds_read_b128 v[172:175], v5 offset:16384
	ds_read_b128 v[176:179], v5 offset:17408
	ds_read_b128 v[180:183], v5 offset:18432
	ds_read_b128 v[184:187], v5 offset:19456
	ds_read_b128 v[188:191], v5 offset:20480
	ds_read_b128 v[192:195], v5 offset:21504
	ds_read_b128 v[196:199], v5 offset:22528
	ds_read_b128 v[200:203], v5 offset:23552
	global_load_lds_dwordx4 v[204:205], off
	s_add_i32 m0, s65, 0x2000
	v_lshl_add_u64 v[204:205], s[40:41], 0, v[138:139]
	s_add_u32 s40, s40, 0x40000
	s_addc_u32 s41, s41, 0
	s_add_i32 s65, s68, s46
	global_load_lds_dwordx4 v[204:205], off
	v_lshl_add_u64 v[204:205], s[40:41], 0, v[134:135]
	s_mov_b32 m0, s65
	s_nop 0
	global_load_lds_dwordx4 v[204:205], off
	v_lshl_add_u64 v[204:205], s[40:41], 0, v[138:139]
	s_add_i32 m0, s65, 0x2000
	s_nop 0
	global_load_lds_dwordx4 v[204:205], off
	v_lshl_add_u64 v[204:205], s[38:39], 0, v[2:3]
	s_mov_b32 m0, s29
	s_nop 0
	global_load_lds_dwordx4 v[204:205], off
	v_lshl_add_u64 v[204:205], s[38:39], 0, v[136:137]
	s_mov_b32 m0, s51
	s_nop 0
	global_load_lds_dwordx4 v[204:205], off
	s_waitcnt vmcnt(8)
	s_waitcnt lgkmcnt(0)
	s_barrier
	s_setprio 1
	v_mfma_f32_16x16x32_bf16 v[66:69], v[140:143], v[172:175], v[66:69]
	v_mfma_f32_16x16x32_bf16 v[62:65], v[148:151], v[172:175], v[62:65]
	v_mfma_f32_16x16x32_bf16 v[50:53], v[140:143], v[180:183], v[50:53]
	v_mfma_f32_16x16x32_bf16 v[46:49], v[148:151], v[180:183], v[46:49]
	v_mfma_f32_16x16x32_bf16 v[34:37], v[140:143], v[188:191], v[34:37]
	v_mfma_f32_16x16x32_bf16 v[30:33], v[148:151], v[188:191], v[30:33]
	v_mfma_f32_16x16x32_bf16 v[18:21], v[140:143], v[196:199], v[18:21]
	v_mfma_f32_16x16x32_bf16 v[14:17], v[148:151], v[196:199], v[14:17]
	v_mfma_f32_16x16x32_bf16 v[66:69], v[144:147], v[176:179], v[66:69]
	v_mfma_f32_16x16x32_bf16 v[62:65], v[152:155], v[176:179], v[62:65]
	v_mfma_f32_16x16x32_bf16 v[50:53], v[144:147], v[184:187], v[50:53]
	v_mfma_f32_16x16x32_bf16 v[46:49], v[152:155], v[184:187], v[46:49]
	v_mfma_f32_16x16x32_bf16 v[34:37], v[144:147], v[192:195], v[34:37]
	v_mfma_f32_16x16x32_bf16 v[30:33], v[152:155], v[192:195], v[30:33]
	v_mfma_f32_16x16x32_bf16 v[18:21], v[144:147], v[200:203], v[18:21]
	v_mfma_f32_16x16x32_bf16 v[14:17], v[152:155], v[200:203], v[14:17]
	s_setprio 0
	s_setprio 1
	v_mfma_f32_16x16x32_bf16 v[58:61], v[156:159], v[172:175], v[58:61]
	v_mfma_f32_16x16x32_bf16 v[54:57], v[164:167], v[172:175], v[54:57]
	v_mfma_f32_16x16x32_bf16 v[42:45], v[156:159], v[180:183], v[42:45]
	v_mfma_f32_16x16x32_bf16 v[38:41], v[164:167], v[180:183], v[38:41]
	v_mfma_f32_16x16x32_bf16 v[26:29], v[156:159], v[188:191], v[26:29]
	v_mfma_f32_16x16x32_bf16 v[22:25], v[164:167], v[188:191], v[22:25]
	v_mfma_f32_16x16x32_bf16 v[10:13], v[156:159], v[196:199], v[10:13]
	v_mfma_f32_16x16x32_bf16 v[6:9], v[164:167], v[196:199], v[6:9]
	v_mfma_f32_16x16x32_bf16 v[58:61], v[160:163], v[176:179], v[58:61]
	v_mfma_f32_16x16x32_bf16 v[54:57], v[168:171], v[176:179], v[54:57]
	v_mfma_f32_16x16x32_bf16 v[42:45], v[160:163], v[184:187], v[42:45]
	v_mfma_f32_16x16x32_bf16 v[38:41], v[168:171], v[184:187], v[38:41]
	v_mfma_f32_16x16x32_bf16 v[26:29], v[160:163], v[192:195], v[26:29]
	v_mfma_f32_16x16x32_bf16 v[22:25], v[168:171], v[192:195], v[22:25]
	v_mfma_f32_16x16x32_bf16 v[10:13], v[160:163], v[200:203], v[10:13]
	v_mfma_f32_16x16x32_bf16 v[6:9], v[168:171], v[200:203], v[6:9]
	s_setprio 0
	s_barrier
	s_add_i32 s40, 0, 0x18000
	s_add_i32 s41, 0, 0x1c000
	v_add_u32_e32 v152, s40, v1
	v_add_u32_e32 v168, s41, v1
	ds_read_b128 v[140:143], v152
	ds_read_b128 v[144:147], v152 offset:1024
	ds_read_b128 v[148:151], v152 offset:2048
	ds_read_b128 v[152:155], v152 offset:3072
	ds_read_b128 v[156:159], v168
	ds_read_b128 v[160:163], v168 offset:1024
	ds_read_b128 v[164:167], v168 offset:2048
	ds_read_b128 v[168:171], v168 offset:3072
	s_add_u32 s38, s38, 0x40000
	s_addc_u32 s39, s39, 0
	s_mov_b32 m0, s52
	v_lshl_add_u64 v[204:205], s[38:39], 0, v[2:3]
	ds_read_b128 v[172:175], v5 offset:32768
	ds_read_b128 v[176:179], v5 offset:33792
	ds_read_b128 v[180:183], v5 offset:34816
	ds_read_b128 v[184:187], v5 offset:35840
	ds_read_b128 v[188:191], v5 offset:36864
	ds_read_b128 v[192:195], v5 offset:37888
	ds_read_b128 v[196:199], v5 offset:38912
	ds_read_b128 v[200:203], v5 offset:39936
	global_load_lds_dwordx4 v[204:205], off
	v_lshl_add_u64 v[204:205], s[38:39], 0, v[136:137]
	s_mov_b32 m0, s53
	s_nop 0
	global_load_lds_dwordx4 v[204:205], off
	s_waitcnt vmcnt(8)
	s_waitcnt lgkmcnt(0)
	s_barrier
	s_setprio 1
	v_mfma_f32_16x16x32_bf16 v[130:133], v[140:143], v[172:175], v[130:133]
	v_mfma_f32_16x16x32_bf16 v[126:129], v[148:151], v[172:175], v[126:129]
	v_mfma_f32_16x16x32_bf16 v[114:117], v[140:143], v[180:183], v[114:117]
	v_mfma_f32_16x16x32_bf16 v[110:113], v[148:151], v[180:183], v[110:113]
	v_mfma_f32_16x16x32_bf16 v[98:101], v[140:143], v[188:191], v[98:101]
	v_mfma_f32_16x16x32_bf16 v[94:97], v[148:151], v[188:191], v[94:97]
	v_mfma_f32_16x16x32_bf16 v[82:85], v[140:143], v[196:199], v[82:85]
	v_mfma_f32_16x16x32_bf16 v[78:81], v[148:151], v[196:199], v[78:81]
	v_mfma_f32_16x16x32_bf16 v[130:133], v[144:147], v[176:179], v[130:133]
	v_mfma_f32_16x16x32_bf16 v[126:129], v[152:155], v[176:179], v[126:129]
	v_mfma_f32_16x16x32_bf16 v[114:117], v[144:147], v[184:187], v[114:117]
	v_mfma_f32_16x16x32_bf16 v[110:113], v[152:155], v[184:187], v[110:113]
	v_mfma_f32_16x16x32_bf16 v[98:101], v[144:147], v[192:195], v[98:101]
	v_mfma_f32_16x16x32_bf16 v[94:97], v[152:155], v[192:195], v[94:97]
	v_mfma_f32_16x16x32_bf16 v[82:85], v[144:147], v[200:203], v[82:85]
	v_mfma_f32_16x16x32_bf16 v[78:81], v[152:155], v[200:203], v[78:81]
	s_setprio 0
	s_setprio 1
	v_mfma_f32_16x16x32_bf16 v[122:125], v[156:159], v[172:175], v[122:125]
	v_mfma_f32_16x16x32_bf16 v[118:121], v[164:167], v[172:175], v[118:121]
	v_mfma_f32_16x16x32_bf16 v[106:109], v[156:159], v[180:183], v[106:109]
	v_mfma_f32_16x16x32_bf16 v[102:105], v[164:167], v[180:183], v[102:105]
	v_mfma_f32_16x16x32_bf16 v[90:93], v[156:159], v[188:191], v[90:93]
	v_mfma_f32_16x16x32_bf16 v[86:89], v[164:167], v[188:191], v[86:89]
	v_mfma_f32_16x16x32_bf16 v[74:77], v[156:159], v[196:199], v[74:77]
	v_mfma_f32_16x16x32_bf16 v[70:73], v[164:167], v[196:199], v[70:73]
	v_mfma_f32_16x16x32_bf16 v[122:125], v[160:163], v[176:179], v[122:125]
	v_mfma_f32_16x16x32_bf16 v[118:121], v[168:171], v[176:179], v[118:121]
	v_mfma_f32_16x16x32_bf16 v[106:109], v[160:163], v[184:187], v[106:109]
	v_mfma_f32_16x16x32_bf16 v[102:105], v[168:171], v[184:187], v[102:105]
	v_mfma_f32_16x16x32_bf16 v[90:93], v[160:163], v[192:195], v[90:93]
	v_mfma_f32_16x16x32_bf16 v[86:89], v[168:171], v[192:195], v[86:89]
	v_mfma_f32_16x16x32_bf16 v[74:77], v[160:163], v[200:203], v[74:77]
	v_mfma_f32_16x16x32_bf16 v[70:73], v[168:171], v[200:203], v[70:73]
	s_setprio 0
	s_barrier
	s_add_i32 s38, s40, s46
	v_lshl_add_u64 v[204:205], s[36:37], 0, v[134:135]
	s_mov_b32 m0, s38
	ds_read_b128 v[172:175], v5 offset:49152
	ds_read_b128 v[176:179], v5 offset:50176
	ds_read_b128 v[180:183], v5 offset:51200
	ds_read_b128 v[184:187], v5 offset:52224
	ds_read_b128 v[188:191], v5 offset:53248
	ds_read_b128 v[192:195], v5 offset:54272
	ds_read_b128 v[196:199], v5 offset:55296
	ds_read_b128 v[200:203], v5 offset:56320
	global_load_lds_dwordx4 v[204:205], off
	s_add_i32 m0, s38, 0x2000
	v_lshl_add_u64 v[204:205], s[36:37], 0, v[138:139]
	s_add_u32 s36, s36, 0x40000
	s_addc_u32 s37, s37, 0
	s_add_i32 s38, s41, s46
	global_load_lds_dwordx4 v[204:205], off
	v_lshl_add_u64 v[204:205], s[36:37], 0, v[134:135]
	s_mov_b32 m0, s38
	s_nop 0
	global_load_lds_dwordx4 v[204:205], off
	v_lshl_add_u64 v[204:205], s[36:37], 0, v[138:139]
	s_add_i32 m0, s38, 0x2000
	s_nop 0
	global_load_lds_dwordx4 v[204:205], off
	v_lshl_add_u64 v[204:205], s[34:35], 0, v[2:3]
	s_mov_b32 m0, s56
	s_nop 0
	global_load_lds_dwordx4 v[204:205], off
	v_lshl_add_u64 v[204:205], s[34:35], 0, v[136:137]
	s_mov_b32 m0, s57
	s_nop 0
	global_load_lds_dwordx4 v[204:205], off
	s_waitcnt vmcnt(8)
	s_waitcnt lgkmcnt(0)
	s_barrier
	s_setprio 1
	v_mfma_f32_16x16x32_bf16 v[66:69], v[140:143], v[172:175], v[66:69]
	v_mfma_f32_16x16x32_bf16 v[62:65], v[148:151], v[172:175], v[62:65]
	v_mfma_f32_16x16x32_bf16 v[50:53], v[140:143], v[180:183], v[50:53]
	v_mfma_f32_16x16x32_bf16 v[46:49], v[148:151], v[180:183], v[46:49]
	v_mfma_f32_16x16x32_bf16 v[34:37], v[140:143], v[188:191], v[34:37]
	v_mfma_f32_16x16x32_bf16 v[30:33], v[148:151], v[188:191], v[30:33]
	v_mfma_f32_16x16x32_bf16 v[18:21], v[140:143], v[196:199], v[18:21]
	v_mfma_f32_16x16x32_bf16 v[14:17], v[148:151], v[196:199], v[14:17]
	v_mfma_f32_16x16x32_bf16 v[66:69], v[144:147], v[176:179], v[66:69]
	v_mfma_f32_16x16x32_bf16 v[62:65], v[152:155], v[176:179], v[62:65]
	v_mfma_f32_16x16x32_bf16 v[50:53], v[144:147], v[184:187], v[50:53]
	v_mfma_f32_16x16x32_bf16 v[46:49], v[152:155], v[184:187], v[46:49]
	v_mfma_f32_16x16x32_bf16 v[34:37], v[144:147], v[192:195], v[34:37]
	v_mfma_f32_16x16x32_bf16 v[30:33], v[152:155], v[192:195], v[30:33]
	v_mfma_f32_16x16x32_bf16 v[18:21], v[144:147], v[200:203], v[18:21]
	v_mfma_f32_16x16x32_bf16 v[14:17], v[152:155], v[200:203], v[14:17]
	s_setprio 0
	s_setprio 1
	v_mfma_f32_16x16x32_bf16 v[58:61], v[156:159], v[172:175], v[58:61]
	v_mfma_f32_16x16x32_bf16 v[54:57], v[164:167], v[172:175], v[54:57]
	v_mfma_f32_16x16x32_bf16 v[42:45], v[156:159], v[180:183], v[42:45]
	v_mfma_f32_16x16x32_bf16 v[38:41], v[164:167], v[180:183], v[38:41]
	v_mfma_f32_16x16x32_bf16 v[26:29], v[156:159], v[188:191], v[26:29]
	v_mfma_f32_16x16x32_bf16 v[22:25], v[164:167], v[188:191], v[22:25]
	v_mfma_f32_16x16x32_bf16 v[10:13], v[156:159], v[196:199], v[10:13]
	v_mfma_f32_16x16x32_bf16 v[6:9], v[164:167], v[196:199], v[6:9]
	v_mfma_f32_16x16x32_bf16 v[58:61], v[160:163], v[176:179], v[58:61]
	v_mfma_f32_16x16x32_bf16 v[54:57], v[168:171], v[176:179], v[54:57]
	v_mfma_f32_16x16x32_bf16 v[42:45], v[160:163], v[184:187], v[42:45]
	v_mfma_f32_16x16x32_bf16 v[38:41], v[168:171], v[184:187], v[38:41]
	v_mfma_f32_16x16x32_bf16 v[26:29], v[160:163], v[192:195], v[26:29]
	v_mfma_f32_16x16x32_bf16 v[22:25], v[168:171], v[192:195], v[22:25]
	v_mfma_f32_16x16x32_bf16 v[10:13], v[160:163], v[200:203], v[10:13]
	v_mfma_f32_16x16x32_bf16 v[6:9], v[168:171], v[200:203], v[6:9]
	s_setprio 0
	s_barrier
	s_add_i32 s64, s64, 2
	s_add_u32 s33, s33, 0x100
	s_addc_u32 s61, s61, 0
	s_add_u32 s62, s62, 0x100
	s_addc_u32 s63, s63, 0
	s_cmp_gt_u32 s64, 13
	s_cbranch_scc0 .LBB0_454
	s_and_b64 vcc, exec, s[8:9]
	s_cbranch_vccz .LBB0_457
	s_barrier

.LBB0_480:
	s_add_u32 s58, s54, 0xffffff80
	s_addc_u32 s59, s55, -1
	s_cmp_eq_u32 s56, 4
	s_cselect_b32 s30, s25, s54
	s_cselect_b32 s31, s15, s55
	s_cselect_b32 s35, s17, s53
	s_cselect_b32 s34, s33, s52
	s_add_u32 s26, s30, 0x80
	s_addc_u32 s27, s31, 0
	s_add_u32 s28, s34, 0x80
	s_addc_u32 s29, s35, 0
	s_add_i32 s57, 0, 0x10000
	s_add_i32 s60, 0, 0x14000
	v_add_u32_e32 v152, s57, v1
	v_add_u32_e32 v168, s60, v1
	ds_read_b128 v[140:143], v152
	ds_read_b128 v[144:147], v152 offset:1024
	ds_read_b128 v[148:151], v152 offset:2048
	ds_read_b128 v[152:155], v152 offset:3072
	ds_read_b128 v[156:159], v168
	ds_read_b128 v[160:163], v168 offset:1024
	ds_read_b128 v[164:167], v168 offset:2048
	ds_read_b128 v[168:171], v168 offset:3072
	s_add_u32 s58, s58, 0x20000
	s_addc_u32 s59, s59, 0
	v_lshl_add_u64 v[204:205], s[58:59], 0, v[2:3]
	s_add_i32 m0, s43, 0xc000
	ds_read_b128 v[172:175], v5
	ds_read_b128 v[176:179], v5 offset:1024
	ds_read_b128 v[180:183], v5 offset:2048
	ds_read_b128 v[184:187], v5 offset:3072
	ds_read_b128 v[188:191], v5 offset:4096
	ds_read_b128 v[192:195], v5 offset:5120
	ds_read_b128 v[196:199], v5 offset:6144
	ds_read_b128 v[200:203], v5 offset:7168
	global_load_lds_dwordx4 v[204:205], off
	v_lshl_add_u64 v[204:205], s[58:59], 0, v[136:137]
	s_add_i32 m0, s43, 0xe000
	s_nop 0
	global_load_lds_dwordx4 v[204:205], off
	s_waitcnt vmcnt(8)
	s_waitcnt lgkmcnt(0)
	s_barrier
	s_setprio 1
	v_mfma_f32_16x16x32_bf16 v[130:133], v[140:143], v[172:175], v[130:133]
	v_mfma_f32_16x16x32_bf16 v[126:129], v[148:151], v[172:175], v[126:129]
	v_mfma_f32_16x16x32_bf16 v[114:117], v[140:143], v[180:183], v[114:117]
	v_mfma_f32_16x16x32_bf16 v[110:113], v[148:151], v[180:183], v[110:113]
	v_mfma_f32_16x16x32_bf16 v[98:101], v[140:143], v[188:191], v[98:101]
	v_mfma_f32_16x16x32_bf16 v[94:97], v[148:151], v[188:191], v[94:97]
	v_mfma_f32_16x16x32_bf16 v[82:85], v[140:143], v[196:199], v[82:85]
	v_mfma_f32_16x16x32_bf16 v[78:81], v[148:151], v[196:199], v[78:81]
	v_mfma_f32_16x16x32_bf16 v[130:133], v[144:147], v[176:179], v[130:133]
	v_mfma_f32_16x16x32_bf16 v[126:129], v[152:155], v[176:179], v[126:129]
	v_mfma_f32_16x16x32_bf16 v[114:117], v[144:147], v[184:187], v[114:117]
	v_mfma_f32_16x16x32_bf16 v[110:113], v[152:155], v[184:187], v[110:113]
	v_mfma_f32_16x16x32_bf16 v[98:101], v[144:147], v[192:195], v[98:101]
	v_mfma_f32_16x16x32_bf16 v[94:97], v[152:155], v[192:195], v[94:97]
	v_mfma_f32_16x16x32_bf16 v[82:85], v[144:147], v[200:203], v[82:85]
	v_mfma_f32_16x16x32_bf16 v[78:81], v[152:155], v[200:203], v[78:81]
	s_setprio 0
	s_setprio 1
	v_mfma_f32_16x16x32_bf16 v[122:125], v[156:159], v[172:175], v[122:125]
	v_mfma_f32_16x16x32_bf16 v[118:121], v[164:167], v[172:175], v[118:121]
	v_mfma_f32_16x16x32_bf16 v[106:109], v[156:159], v[180:183], v[106:109]
	v_mfma_f32_16x16x32_bf16 v[102:105], v[164:167], v[180:183], v[102:105]
	v_mfma_f32_16x16x32_bf16 v[90:93], v[156:159], v[188:191], v[90:93]
	v_mfma_f32_16x16x32_bf16 v[86:89], v[164:167], v[188:191], v[86:89]
	v_mfma_f32_16x16x32_bf16 v[74:77], v[156:159], v[196:199], v[74:77]
	v_mfma_f32_16x16x32_bf16 v[70:73], v[164:167], v[196:199], v[70:73]
	v_mfma_f32_16x16x32_bf16 v[122:125], v[160:163], v[176:179], v[122:125]
	v_mfma_f32_16x16x32_bf16 v[118:121], v[168:171], v[176:179], v[118:121]
	v_mfma_f32_16x16x32_bf16 v[106:109], v[160:163], v[184:187], v[106:109]
	v_mfma_f32_16x16x32_bf16 v[102:105], v[168:171], v[184:187], v[102:105]
	v_mfma_f32_16x16x32_bf16 v[90:93], v[160:163], v[192:195], v[90:93]
	v_mfma_f32_16x16x32_bf16 v[86:89], v[168:171], v[192:195], v[86:89]
	v_mfma_f32_16x16x32_bf16 v[74:77], v[160:163], v[200:203], v[74:77]
	v_mfma_f32_16x16x32_bf16 v[70:73], v[168:171], v[200:203], v[70:73]
	s_setprio 0
	s_barrier
	s_add_i32 s57, s57, s42
	v_lshl_add_u64 v[204:205], s[34:35], 0, v[134:135]
	s_mov_b32 m0, s57
	ds_read_b128 v[172:175], v5 offset:16384
	ds_read_b128 v[176:179], v5 offset:17408
	ds_read_b128 v[180:183], v5 offset:18432
	ds_read_b128 v[184:187], v5 offset:19456
	ds_read_b128 v[188:191], v5 offset:20480
	ds_read_b128 v[192:195], v5 offset:21504
	ds_read_b128 v[196:199], v5 offset:22528
	ds_read_b128 v[200:203], v5 offset:23552
	global_load_lds_dwordx4 v[204:205], off
	s_add_i32 m0, s57, 0x2000
	v_lshl_add_u64 v[204:205], s[34:35], 0, v[138:139]
	s_add_u32 s34, s34, 0x20000
	s_addc_u32 s35, s35, 0
	s_add_i32 s57, s60, s42
	global_load_lds_dwordx4 v[204:205], off
	v_lshl_add_u64 v[204:205], s[34:35], 0, v[134:135]
	s_mov_b32 m0, s57
	s_nop 0
	global_load_lds_dwordx4 v[204:205], off
	v_lshl_add_u64 v[204:205], s[34:35], 0, v[138:139]
	s_add_i32 m0, s57, 0x2000
	s_nop 0
	global_load_lds_dwordx4 v[204:205], off
	v_lshl_add_u64 v[204:205], s[30:31], 0, v[2:3]
	s_mov_b32 m0, s43
	s_nop 0
	global_load_lds_dwordx4 v[204:205], off
	v_lshl_add_u64 v[204:205], s[30:31], 0, v[136:137]
	s_mov_b32 m0, s44
	s_nop 0
	global_load_lds_dwordx4 v[204:205], off
	s_waitcnt vmcnt(8)
	s_waitcnt lgkmcnt(0)
	s_barrier
	s_setprio 1
	v_mfma_f32_16x16x32_bf16 v[66:69], v[140:143], v[172:175], v[66:69]
	v_mfma_f32_16x16x32_bf16 v[62:65], v[148:151], v[172:175], v[62:65]
	v_mfma_f32_16x16x32_bf16 v[50:53], v[140:143], v[180:183], v[50:53]
	v_mfma_f32_16x16x32_bf16 v[46:49], v[148:151], v[180:183], v[46:49]
	v_mfma_f32_16x16x32_bf16 v[34:37], v[140:143], v[188:191], v[34:37]
	v_mfma_f32_16x16x32_bf16 v[30:33], v[148:151], v[188:191], v[30:33]
	v_mfma_f32_16x16x32_bf16 v[18:21], v[140:143], v[196:199], v[18:21]
	v_mfma_f32_16x16x32_bf16 v[14:17], v[148:151], v[196:199], v[14:17]
	v_mfma_f32_16x16x32_bf16 v[66:69], v[144:147], v[176:179], v[66:69]
	v_mfma_f32_16x16x32_bf16 v[62:65], v[152:155], v[176:179], v[62:65]
	v_mfma_f32_16x16x32_bf16 v[50:53], v[144:147], v[184:187], v[50:53]
	v_mfma_f32_16x16x32_bf16 v[46:49], v[152:155], v[184:187], v[46:49]
	v_mfma_f32_16x16x32_bf16 v[34:37], v[144:147], v[192:195], v[34:37]
	v_mfma_f32_16x16x32_bf16 v[30:33], v[152:155], v[192:195], v[30:33]
	v_mfma_f32_16x16x32_bf16 v[18:21], v[144:147], v[200:203], v[18:21]
	v_mfma_f32_16x16x32_bf16 v[14:17], v[152:155], v[200:203], v[14:17]
	s_setprio 0
	s_setprio 1
	v_mfma_f32_16x16x32_bf16 v[58:61], v[156:159], v[172:175], v[58:61]
	v_mfma_f32_16x16x32_bf16 v[54:57], v[164:167], v[172:175], v[54:57]
	v_mfma_f32_16x16x32_bf16 v[42:45], v[156:159], v[180:183], v[42:45]
	v_mfma_f32_16x16x32_bf16 v[38:41], v[164:167], v[180:183], v[38:41]
	v_mfma_f32_16x16x32_bf16 v[26:29], v[156:159], v[188:191], v[26:29]
	v_mfma_f32_16x16x32_bf16 v[22:25], v[164:167], v[188:191], v[22:25]
	v_mfma_f32_16x16x32_bf16 v[10:13], v[156:159], v[196:199], v[10:13]
	v_mfma_f32_16x16x32_bf16 v[6:9], v[164:167], v[196:199], v[6:9]
	v_mfma_f32_16x16x32_bf16 v[58:61], v[160:163], v[176:179], v[58:61]
	v_mfma_f32_16x16x32_bf16 v[54:57], v[168:171], v[176:179], v[54:57]
	v_mfma_f32_16x16x32_bf16 v[42:45], v[160:163], v[184:187], v[42:45]
	v_mfma_f32_16x16x32_bf16 v[38:41], v[168:171], v[184:187], v[38:41]
	v_mfma_f32_16x16x32_bf16 v[26:29], v[160:163], v[192:195], v[26:29]
	v_mfma_f32_16x16x32_bf16 v[22:25], v[168:171], v[192:195], v[22:25]
	v_mfma_f32_16x16x32_bf16 v[10:13], v[160:163], v[200:203], v[10:13]
	v_mfma_f32_16x16x32_bf16 v[6:9], v[168:171], v[200:203], v[6:9]
	s_setprio 0
	s_barrier
	s_add_i32 s34, 0, 0x18000
	s_add_i32 s35, 0, 0x1c000
	v_add_u32_e32 v152, s34, v1
	v_add_u32_e32 v168, s35, v1
	ds_read_b128 v[140:143], v152
	ds_read_b128 v[144:147], v152 offset:1024
	ds_read_b128 v[148:151], v152 offset:2048
	ds_read_b128 v[152:155], v152 offset:3072
	ds_read_b128 v[156:159], v168
	ds_read_b128 v[160:163], v168 offset:1024
	ds_read_b128 v[164:167], v168 offset:2048
	ds_read_b128 v[168:171], v168 offset:3072
	s_add_u32 s30, s30, 0x20000
	s_addc_u32 s31, s31, 0
	s_mov_b32 m0, s45
	v_lshl_add_u64 v[204:205], s[30:31], 0, v[2:3]
	ds_read_b128 v[172:175], v5 offset:32768
	ds_read_b128 v[176:179], v5 offset:33792
	ds_read_b128 v[180:183], v5 offset:34816
	ds_read_b128 v[184:187], v5 offset:35840
	ds_read_b128 v[188:191], v5 offset:36864
	ds_read_b128 v[192:195], v5 offset:37888
	ds_read_b128 v[196:199], v5 offset:38912
	ds_read_b128 v[200:203], v5 offset:39936
	global_load_lds_dwordx4 v[204:205], off
	v_lshl_add_u64 v[204:205], s[30:31], 0, v[136:137]
	s_mov_b32 m0, s46
	s_nop 0
	global_load_lds_dwordx4 v[204:205], off
	s_waitcnt vmcnt(8)
	s_waitcnt lgkmcnt(0)
	s_barrier
	s_setprio 1
	v_mfma_f32_16x16x32_bf16 v[130:133], v[140:143], v[172:175], v[130:133]
	v_mfma_f32_16x16x32_bf16 v[126:129], v[148:151], v[172:175], v[126:129]
	v_mfma_f32_16x16x32_bf16 v[114:117], v[140:143], v[180:183], v[114:117]
	v_mfma_f32_16x16x32_bf16 v[110:113], v[148:151], v[180:183], v[110:113]
	v_mfma_f32_16x16x32_bf16 v[98:101], v[140:143], v[188:191], v[98:101]
	v_mfma_f32_16x16x32_bf16 v[94:97], v[148:151], v[188:191], v[94:97]
	v_mfma_f32_16x16x32_bf16 v[82:85], v[140:143], v[196:199], v[82:85]
	v_mfma_f32_16x16x32_bf16 v[78:81], v[148:151], v[196:199], v[78:81]
	v_mfma_f32_16x16x32_bf16 v[130:133], v[144:147], v[176:179], v[130:133]
	v_mfma_f32_16x16x32_bf16 v[126:129], v[152:155], v[176:179], v[126:129]
	v_mfma_f32_16x16x32_bf16 v[114:117], v[144:147], v[184:187], v[114:117]
	v_mfma_f32_16x16x32_bf16 v[110:113], v[152:155], v[184:187], v[110:113]
	v_mfma_f32_16x16x32_bf16 v[98:101], v[144:147], v[192:195], v[98:101]
	v_mfma_f32_16x16x32_bf16 v[94:97], v[152:155], v[192:195], v[94:97]
	v_mfma_f32_16x16x32_bf16 v[82:85], v[144:147], v[200:203], v[82:85]
	v_mfma_f32_16x16x32_bf16 v[78:81], v[152:155], v[200:203], v[78:81]
	s_setprio 0
	s_setprio 1
	v_mfma_f32_16x16x32_bf16 v[122:125], v[156:159], v[172:175], v[122:125]
	v_mfma_f32_16x16x32_bf16 v[118:121], v[164:167], v[172:175], v[118:121]
	v_mfma_f32_16x16x32_bf16 v[106:109], v[156:159], v[180:183], v[106:109]
	v_mfma_f32_16x16x32_bf16 v[102:105], v[164:167], v[180:183], v[102:105]
	v_mfma_f32_16x16x32_bf16 v[90:93], v[156:159], v[188:191], v[90:93]
	v_mfma_f32_16x16x32_bf16 v[86:89], v[164:167], v[188:191], v[86:89]
	v_mfma_f32_16x16x32_bf16 v[74:77], v[156:159], v[196:199], v[74:77]
	v_mfma_f32_16x16x32_bf16 v[70:73], v[164:167], v[196:199], v[70:73]
	v_mfma_f32_16x16x32_bf16 v[122:125], v[160:163], v[176:179], v[122:125]
	v_mfma_f32_16x16x32_bf16 v[118:121], v[168:171], v[176:179], v[118:121]
	v_mfma_f32_16x16x32_bf16 v[106:109], v[160:163], v[184:187], v[106:109]
	v_mfma_f32_16x16x32_bf16 v[102:105], v[168:171], v[184:187], v[102:105]
	v_mfma_f32_16x16x32_bf16 v[90:93], v[160:163], v[192:195], v[90:93]
	v_mfma_f32_16x16x32_bf16 v[86:89], v[168:171], v[192:195], v[86:89]
	v_mfma_f32_16x16x32_bf16 v[74:77], v[160:163], v[200:203], v[74:77]
	v_mfma_f32_16x16x32_bf16 v[70:73], v[168:171], v[200:203], v[70:73]
	s_setprio 0
	s_barrier
	s_add_i32 s30, s34, s42
	v_lshl_add_u64 v[204:205], s[28:29], 0, v[134:135]
	s_mov_b32 m0, s30
	ds_read_b128 v[172:175], v5 offset:49152
	ds_read_b128 v[176:179], v5 offset:50176
	ds_read_b128 v[180:183], v5 offset:51200
	ds_read_b128 v[184:187], v5 offset:52224
	ds_read_b128 v[188:191], v5 offset:53248
	ds_read_b128 v[192:195], v5 offset:54272
	ds_read_b128 v[196:199], v5 offset:55296
	ds_read_b128 v[200:203], v5 offset:56320
	global_load_lds_dwordx4 v[204:205], off
	s_add_i32 m0, s30, 0x2000
	v_lshl_add_u64 v[204:205], s[28:29], 0, v[138:139]
	s_add_u32 s28, s28, 0x20000
	s_addc_u32 s29, s29, 0
	s_add_i32 s30, s35, s42
	global_load_lds_dwordx4 v[204:205], off
	v_lshl_add_u64 v[204:205], s[28:29], 0, v[134:135]
	s_mov_b32 m0, s30
	s_nop 0
	global_load_lds_dwordx4 v[204:205], off
	v_lshl_add_u64 v[204:205], s[28:29], 0, v[138:139]
	s_add_i32 m0, s30, 0x2000
	s_nop 0
	global_load_lds_dwordx4 v[204:205], off
	v_lshl_add_u64 v[204:205], s[26:27], 0, v[2:3]
	s_mov_b32 m0, s49
	s_nop 0
	global_load_lds_dwordx4 v[204:205], off
	v_lshl_add_u64 v[204:205], s[26:27], 0, v[136:137]
	s_mov_b32 m0, s50
	s_nop 0
	global_load_lds_dwordx4 v[204:205], off
	s_waitcnt vmcnt(8)
	s_waitcnt lgkmcnt(0)
	s_barrier
	s_setprio 1
	v_mfma_f32_16x16x32_bf16 v[66:69], v[140:143], v[172:175], v[66:69]
	v_mfma_f32_16x16x32_bf16 v[62:65], v[148:151], v[172:175], v[62:65]
	v_mfma_f32_16x16x32_bf16 v[50:53], v[140:143], v[180:183], v[50:53]
	v_mfma_f32_16x16x32_bf16 v[46:49], v[148:151], v[180:183], v[46:49]
	v_mfma_f32_16x16x32_bf16 v[34:37], v[140:143], v[188:191], v[34:37]
	v_mfma_f32_16x16x32_bf16 v[30:33], v[148:151], v[188:191], v[30:33]
	v_mfma_f32_16x16x32_bf16 v[18:21], v[140:143], v[196:199], v[18:21]
	v_mfma_f32_16x16x32_bf16 v[14:17], v[148:151], v[196:199], v[14:17]
	v_mfma_f32_16x16x32_bf16 v[66:69], v[144:147], v[176:179], v[66:69]
	v_mfma_f32_16x16x32_bf16 v[62:65], v[152:155], v[176:179], v[62:65]
	v_mfma_f32_16x16x32_bf16 v[50:53], v[144:147], v[184:187], v[50:53]
	v_mfma_f32_16x16x32_bf16 v[46:49], v[152:155], v[184:187], v[46:49]
	v_mfma_f32_16x16x32_bf16 v[34:37], v[144:147], v[192:195], v[34:37]
	v_mfma_f32_16x16x32_bf16 v[30:33], v[152:155], v[192:195], v[30:33]
	v_mfma_f32_16x16x32_bf16 v[18:21], v[144:147], v[200:203], v[18:21]
	v_mfma_f32_16x16x32_bf16 v[14:17], v[152:155], v[200:203], v[14:17]
	s_setprio 0
	s_setprio 1
	v_mfma_f32_16x16x32_bf16 v[58:61], v[156:159], v[172:175], v[58:61]
	v_mfma_f32_16x16x32_bf16 v[54:57], v[164:167], v[172:175], v[54:57]
	v_mfma_f32_16x16x32_bf16 v[42:45], v[156:159], v[180:183], v[42:45]
	v_mfma_f32_16x16x32_bf16 v[38:41], v[164:167], v[180:183], v[38:41]
	v_mfma_f32_16x16x32_bf16 v[26:29], v[156:159], v[188:191], v[26:29]
	v_mfma_f32_16x16x32_bf16 v[22:25], v[164:167], v[188:191], v[22:25]
	v_mfma_f32_16x16x32_bf16 v[10:13], v[156:159], v[196:199], v[10:13]
	v_mfma_f32_16x16x32_bf16 v[6:9], v[164:167], v[196:199], v[6:9]
	v_mfma_f32_16x16x32_bf16 v[58:61], v[160:163], v[176:179], v[58:61]
	v_mfma_f32_16x16x32_bf16 v[54:57], v[168:171], v[176:179], v[54:57]
	v_mfma_f32_16x16x32_bf16 v[42:45], v[160:163], v[184:187], v[42:45]
	v_mfma_f32_16x16x32_bf16 v[38:41], v[168:171], v[184:187], v[38:41]
	v_mfma_f32_16x16x32_bf16 v[26:29], v[160:163], v[192:195], v[26:29]
	v_mfma_f32_16x16x32_bf16 v[22:25], v[168:171], v[192:195], v[22:25]
	v_mfma_f32_16x16x32_bf16 v[10:13], v[160:163], v[200:203], v[10:13]
	v_mfma_f32_16x16x32_bf16 v[6:9], v[168:171], v[200:203], v[6:9]
	s_setprio 0
	s_barrier
	s_add_i32 s56, s56, 2
	s_add_u32 s52, s52, 0x100
	s_addc_u32 s53, s53, 0
	s_add_u32 s54, s54, 0x100
	s_addc_u32 s55, s55, 0
	s_cmp_gt_u32 s56, 5
	s_cbranch_scc0 .LBB0_480
	s_and_b64 vcc, exec, s[8:9]
	s_cbranch_vccz .LBB0_483
	s_barrier

.LBB0_536:
	s_add_u32 s48, s45, 0xffffff80
	s_addc_u32 s49, s46, -1
	s_cmp_eq_u32 s47, 4
	s_cselect_b32 s22, s41, s45
	s_cselect_b32 s23, s7, s46
	s_cselect_b32 s25, s9, s44
	s_cselect_b32 s24, s42, s43
	s_add_u32 s18, s22, 0x80
	s_addc_u32 s19, s23, 0
	s_add_u32 s20, s24, 0x80
	s_addc_u32 s21, s25, 0
	s_add_i32 s50, 0, 0x10000
	s_add_i32 s51, 0, 0x14000
	v_add_u32_e32 v152, s50, v1
	v_add_u32_e32 v168, s51, v1
	ds_read_b128 v[140:143], v152
	ds_read_b128 v[144:147], v152 offset:1024
	ds_read_b128 v[148:151], v152 offset:2048
	ds_read_b128 v[152:155], v152 offset:3072
	ds_read_b128 v[156:159], v168
	ds_read_b128 v[160:163], v168 offset:1024
	ds_read_b128 v[164:167], v168 offset:2048
	ds_read_b128 v[168:171], v168 offset:3072
	s_add_u32 s48, s48, 0x20000
	s_addc_u32 s49, s49, 0
	v_lshl_add_u64 v[204:205], s[48:49], 0, v[2:3]
	s_add_i32 m0, s15, 0xc000
	ds_read_b128 v[172:175], v5
	ds_read_b128 v[176:179], v5 offset:1024
	ds_read_b128 v[180:183], v5 offset:2048
	ds_read_b128 v[184:187], v5 offset:3072
	ds_read_b128 v[188:191], v5 offset:4096
	ds_read_b128 v[192:195], v5 offset:5120
	ds_read_b128 v[196:199], v5 offset:6144
	ds_read_b128 v[200:203], v5 offset:7168
	global_load_lds_dwordx4 v[204:205], off
	v_lshl_add_u64 v[204:205], s[48:49], 0, v[136:137]
	s_add_i32 m0, s15, 0xe000
	s_nop 0
	global_load_lds_dwordx4 v[204:205], off
	s_waitcnt vmcnt(8)
	s_waitcnt lgkmcnt(0)
	s_barrier
	s_setprio 1
	v_mfma_f32_16x16x32_bf16 v[130:133], v[140:143], v[172:175], v[130:133]
	v_mfma_f32_16x16x32_bf16 v[126:129], v[148:151], v[172:175], v[126:129]
	v_mfma_f32_16x16x32_bf16 v[122:125], v[140:143], v[180:183], v[122:125]
	v_mfma_f32_16x16x32_bf16 v[114:117], v[148:151], v[180:183], v[114:117]
	v_mfma_f32_16x16x32_bf16 v[106:109], v[140:143], v[188:191], v[106:109]
	v_mfma_f32_16x16x32_bf16 v[98:101], v[148:151], v[188:191], v[98:101]
	v_mfma_f32_16x16x32_bf16 v[90:93], v[140:143], v[196:199], v[90:93]
	v_mfma_f32_16x16x32_bf16 v[82:85], v[148:151], v[196:199], v[82:85]
	v_mfma_f32_16x16x32_bf16 v[130:133], v[144:147], v[176:179], v[130:133]
	v_mfma_f32_16x16x32_bf16 v[126:129], v[152:155], v[176:179], v[126:129]
	v_mfma_f32_16x16x32_bf16 v[122:125], v[144:147], v[184:187], v[122:125]
	v_mfma_f32_16x16x32_bf16 v[114:117], v[152:155], v[184:187], v[114:117]
	v_mfma_f32_16x16x32_bf16 v[106:109], v[144:147], v[192:195], v[106:109]
	v_mfma_f32_16x16x32_bf16 v[98:101], v[152:155], v[192:195], v[98:101]
	v_mfma_f32_16x16x32_bf16 v[90:93], v[144:147], v[200:203], v[90:93]
	v_mfma_f32_16x16x32_bf16 v[82:85], v[152:155], v[200:203], v[82:85]
	s_setprio 0
	s_setprio 1
	v_mfma_f32_16x16x32_bf16 v[118:121], v[156:159], v[172:175], v[118:121]
	v_mfma_f32_16x16x32_bf16 v[110:113], v[164:167], v[172:175], v[110:113]
	v_mfma_f32_16x16x32_bf16 v[102:105], v[156:159], v[180:183], v[102:105]
	v_mfma_f32_16x16x32_bf16 v[94:97], v[164:167], v[180:183], v[94:97]
	v_mfma_f32_16x16x32_bf16 v[86:89], v[156:159], v[188:191], v[86:89]
	v_mfma_f32_16x16x32_bf16 v[78:81], v[164:167], v[188:191], v[78:81]
	v_mfma_f32_16x16x32_bf16 v[74:77], v[156:159], v[196:199], v[74:77]
	v_mfma_f32_16x16x32_bf16 v[70:73], v[164:167], v[196:199], v[70:73]
	v_mfma_f32_16x16x32_bf16 v[118:121], v[160:163], v[176:179], v[118:121]
	v_mfma_f32_16x16x32_bf16 v[110:113], v[168:171], v[176:179], v[110:113]
	v_mfma_f32_16x16x32_bf16 v[102:105], v[160:163], v[184:187], v[102:105]
	v_mfma_f32_16x16x32_bf16 v[94:97], v[168:171], v[184:187], v[94:97]
	v_mfma_f32_16x16x32_bf16 v[86:89], v[160:163], v[192:195], v[86:89]
	v_mfma_f32_16x16x32_bf16 v[78:81], v[168:171], v[192:195], v[78:81]
	v_mfma_f32_16x16x32_bf16 v[74:77], v[160:163], v[200:203], v[74:77]
	v_mfma_f32_16x16x32_bf16 v[70:73], v[168:171], v[200:203], v[70:73]
	s_setprio 0
	s_barrier
	s_add_i32 s48, s50, s29
	v_lshl_add_u64 v[204:205], s[24:25], 0, v[134:135]
	s_mov_b32 m0, s48
	ds_read_b128 v[172:175], v5 offset:16384
	ds_read_b128 v[176:179], v5 offset:17408
	ds_read_b128 v[180:183], v5 offset:18432
	ds_read_b128 v[184:187], v5 offset:19456
	ds_read_b128 v[188:191], v5 offset:20480
	ds_read_b128 v[192:195], v5 offset:21504
	ds_read_b128 v[196:199], v5 offset:22528
	ds_read_b128 v[200:203], v5 offset:23552
	global_load_lds_dwordx4 v[204:205], off
	s_add_i32 m0, s48, 0x2000
	v_lshl_add_u64 v[204:205], s[24:25], 0, v[138:139]
	s_add_u32 s24, s24, 0x20000
	s_addc_u32 s25, s25, 0
	s_add_i32 s48, s51, s29
	global_load_lds_dwordx4 v[204:205], off
	v_lshl_add_u64 v[204:205], s[24:25], 0, v[134:135]
	s_mov_b32 m0, s48
	s_nop 0
	global_load_lds_dwordx4 v[204:205], off
	v_lshl_add_u64 v[204:205], s[24:25], 0, v[138:139]
	s_add_i32 m0, s48, 0x2000
	s_nop 0
	global_load_lds_dwordx4 v[204:205], off
	v_lshl_add_u64 v[204:205], s[22:23], 0, v[2:3]
	s_mov_b32 m0, s15
	s_nop 0
	global_load_lds_dwordx4 v[204:205], off
	v_lshl_add_u64 v[204:205], s[22:23], 0, v[136:137]
	s_mov_b32 m0, s17
	s_nop 0
	global_load_lds_dwordx4 v[204:205], off
	s_waitcnt vmcnt(8)
	s_waitcnt lgkmcnt(0)
	s_barrier
	s_setprio 1
	v_mfma_f32_16x16x32_bf16 v[66:69], v[140:143], v[172:175], v[66:69]
	v_mfma_f32_16x16x32_bf16 v[62:65], v[148:151], v[172:175], v[62:65]
	v_mfma_f32_16x16x32_bf16 v[58:61], v[140:143], v[180:183], v[58:61]
	v_mfma_f32_16x16x32_bf16 v[50:53], v[148:151], v[180:183], v[50:53]
	v_mfma_f32_16x16x32_bf16 v[42:45], v[140:143], v[188:191], v[42:45]
	v_mfma_f32_16x16x32_bf16 v[34:37], v[148:151], v[188:191], v[34:37]
	v_mfma_f32_16x16x32_bf16 v[26:29], v[140:143], v[196:199], v[26:29]
	v_mfma_f32_16x16x32_bf16 v[18:21], v[148:151], v[196:199], v[18:21]
	v_mfma_f32_16x16x32_bf16 v[66:69], v[144:147], v[176:179], v[66:69]
	v_mfma_f32_16x16x32_bf16 v[62:65], v[152:155], v[176:179], v[62:65]
	v_mfma_f32_16x16x32_bf16 v[58:61], v[144:147], v[184:187], v[58:61]
	v_mfma_f32_16x16x32_bf16 v[50:53], v[152:155], v[184:187], v[50:53]
	v_mfma_f32_16x16x32_bf16 v[42:45], v[144:147], v[192:195], v[42:45]
	v_mfma_f32_16x16x32_bf16 v[34:37], v[152:155], v[192:195], v[34:37]
	v_mfma_f32_16x16x32_bf16 v[26:29], v[144:147], v[200:203], v[26:29]
	v_mfma_f32_16x16x32_bf16 v[18:21], v[152:155], v[200:203], v[18:21]
	s_setprio 0
	s_setprio 1
	v_mfma_f32_16x16x32_bf16 v[54:57], v[156:159], v[172:175], v[54:57]
	v_mfma_f32_16x16x32_bf16 v[46:49], v[164:167], v[172:175], v[46:49]
	v_mfma_f32_16x16x32_bf16 v[38:41], v[156:159], v[180:183], v[38:41]
	v_mfma_f32_16x16x32_bf16 v[30:33], v[164:167], v[180:183], v[30:33]
	v_mfma_f32_16x16x32_bf16 v[22:25], v[156:159], v[188:191], v[22:25]
	v_mfma_f32_16x16x32_bf16 v[14:17], v[164:167], v[188:191], v[14:17]
	v_mfma_f32_16x16x32_bf16 v[10:13], v[156:159], v[196:199], v[10:13]
	v_mfma_f32_16x16x32_bf16 v[6:9], v[164:167], v[196:199], v[6:9]
	v_mfma_f32_16x16x32_bf16 v[54:57], v[160:163], v[176:179], v[54:57]
	v_mfma_f32_16x16x32_bf16 v[46:49], v[168:171], v[176:179], v[46:49]
	v_mfma_f32_16x16x32_bf16 v[38:41], v[160:163], v[184:187], v[38:41]
	v_mfma_f32_16x16x32_bf16 v[30:33], v[168:171], v[184:187], v[30:33]
	v_mfma_f32_16x16x32_bf16 v[22:25], v[160:163], v[192:195], v[22:25]
	v_mfma_f32_16x16x32_bf16 v[14:17], v[168:171], v[192:195], v[14:17]
	v_mfma_f32_16x16x32_bf16 v[10:13], v[160:163], v[200:203], v[10:13]
	v_mfma_f32_16x16x32_bf16 v[6:9], v[168:171], v[200:203], v[6:9]
	s_setprio 0
	s_barrier
	s_add_i32 s24, 0, 0x18000
	s_add_i32 s25, 0, 0x1c000
	v_add_u32_e32 v152, s24, v1
	v_add_u32_e32 v168, s25, v1
	ds_read_b128 v[140:143], v152
	ds_read_b128 v[144:147], v152 offset:1024
	ds_read_b128 v[148:151], v152 offset:2048
	ds_read_b128 v[152:155], v152 offset:3072
	ds_read_b128 v[156:159], v168
	ds_read_b128 v[160:163], v168 offset:1024
	ds_read_b128 v[164:167], v168 offset:2048
	ds_read_b128 v[168:171], v168 offset:3072
	s_add_u32 s22, s22, 0x20000
	s_addc_u32 s23, s23, 0
	s_mov_b32 m0, s31
	v_lshl_add_u64 v[204:205], s[22:23], 0, v[2:3]
	ds_read_b128 v[172:175], v5 offset:32768
	ds_read_b128 v[176:179], v5 offset:33792
	ds_read_b128 v[180:183], v5 offset:34816
	ds_read_b128 v[184:187], v5 offset:35840
	ds_read_b128 v[188:191], v5 offset:36864
	ds_read_b128 v[192:195], v5 offset:37888
	ds_read_b128 v[196:199], v5 offset:38912
	ds_read_b128 v[200:203], v5 offset:39936
	global_load_lds_dwordx4 v[204:205], off
	v_lshl_add_u64 v[204:205], s[22:23], 0, v[136:137]
	s_mov_b32 m0, s33
	s_nop 0
	global_load_lds_dwordx4 v[204:205], off
	s_waitcnt vmcnt(8)
	s_waitcnt lgkmcnt(0)
	s_barrier
	s_setprio 1
	v_mfma_f32_16x16x32_bf16 v[130:133], v[140:143], v[172:175], v[130:133]
	v_mfma_f32_16x16x32_bf16 v[126:129], v[148:151], v[172:175], v[126:129]
	v_mfma_f32_16x16x32_bf16 v[122:125], v[140:143], v[180:183], v[122:125]
	v_mfma_f32_16x16x32_bf16 v[114:117], v[148:151], v[180:183], v[114:117]
	v_mfma_f32_16x16x32_bf16 v[106:109], v[140:143], v[188:191], v[106:109]
	v_mfma_f32_16x16x32_bf16 v[98:101], v[148:151], v[188:191], v[98:101]
	v_mfma_f32_16x16x32_bf16 v[90:93], v[140:143], v[196:199], v[90:93]
	v_mfma_f32_16x16x32_bf16 v[82:85], v[148:151], v[196:199], v[82:85]
	v_mfma_f32_16x16x32_bf16 v[130:133], v[144:147], v[176:179], v[130:133]
	v_mfma_f32_16x16x32_bf16 v[126:129], v[152:155], v[176:179], v[126:129]
	v_mfma_f32_16x16x32_bf16 v[122:125], v[144:147], v[184:187], v[122:125]
	v_mfma_f32_16x16x32_bf16 v[114:117], v[152:155], v[184:187], v[114:117]
	v_mfma_f32_16x16x32_bf16 v[106:109], v[144:147], v[192:195], v[106:109]
	v_mfma_f32_16x16x32_bf16 v[98:101], v[152:155], v[192:195], v[98:101]
	v_mfma_f32_16x16x32_bf16 v[90:93], v[144:147], v[200:203], v[90:93]
	v_mfma_f32_16x16x32_bf16 v[82:85], v[152:155], v[200:203], v[82:85]
	s_setprio 0
	s_setprio 1
	v_mfma_f32_16x16x32_bf16 v[118:121], v[156:159], v[172:175], v[118:121]
	v_mfma_f32_16x16x32_bf16 v[110:113], v[164:167], v[172:175], v[110:113]
	v_mfma_f32_16x16x32_bf16 v[102:105], v[156:159], v[180:183], v[102:105]
	v_mfma_f32_16x16x32_bf16 v[94:97], v[164:167], v[180:183], v[94:97]
	v_mfma_f32_16x16x32_bf16 v[86:89], v[156:159], v[188:191], v[86:89]
	v_mfma_f32_16x16x32_bf16 v[78:81], v[164:167], v[188:191], v[78:81]
	v_mfma_f32_16x16x32_bf16 v[74:77], v[156:159], v[196:199], v[74:77]
	v_mfma_f32_16x16x32_bf16 v[70:73], v[164:167], v[196:199], v[70:73]
	v_mfma_f32_16x16x32_bf16 v[118:121], v[160:163], v[176:179], v[118:121]
	v_mfma_f32_16x16x32_bf16 v[110:113], v[168:171], v[176:179], v[110:113]
	v_mfma_f32_16x16x32_bf16 v[102:105], v[160:163], v[184:187], v[102:105]
	v_mfma_f32_16x16x32_bf16 v[94:97], v[168:171], v[184:187], v[94:97]
	v_mfma_f32_16x16x32_bf16 v[86:89], v[160:163], v[192:195], v[86:89]
	v_mfma_f32_16x16x32_bf16 v[78:81], v[168:171], v[192:195], v[78:81]
	v_mfma_f32_16x16x32_bf16 v[74:77], v[160:163], v[200:203], v[74:77]
	v_mfma_f32_16x16x32_bf16 v[70:73], v[168:171], v[200:203], v[70:73]
	s_setprio 0
	s_barrier
	s_add_i32 s22, s24, s29
	v_lshl_add_u64 v[204:205], s[20:21], 0, v[134:135]
	s_mov_b32 m0, s22
	ds_read_b128 v[172:175], v5 offset:49152
	ds_read_b128 v[176:179], v5 offset:50176
	ds_read_b128 v[180:183], v5 offset:51200
	ds_read_b128 v[184:187], v5 offset:52224
	ds_read_b128 v[188:191], v5 offset:53248
	ds_read_b128 v[192:195], v5 offset:54272
	ds_read_b128 v[196:199], v5 offset:55296
	ds_read_b128 v[200:203], v5 offset:56320
	global_load_lds_dwordx4 v[204:205], off
	s_add_i32 m0, s22, 0x2000
	v_lshl_add_u64 v[204:205], s[20:21], 0, v[138:139]
	s_add_u32 s20, s20, 0x20000
	s_addc_u32 s21, s21, 0
	s_add_i32 s22, s25, s29
	global_load_lds_dwordx4 v[204:205], off
	v_lshl_add_u64 v[204:205], s[20:21], 0, v[134:135]
	s_mov_b32 m0, s22
	s_nop 0
	global_load_lds_dwordx4 v[204:205], off
	v_lshl_add_u64 v[204:205], s[20:21], 0, v[138:139]
	s_add_i32 m0, s22, 0x2000
	s_nop 0
	global_load_lds_dwordx4 v[204:205], off
	v_lshl_add_u64 v[204:205], s[18:19], 0, v[2:3]
	s_mov_b32 m0, s38
	s_nop 0
	global_load_lds_dwordx4 v[204:205], off
	v_lshl_add_u64 v[204:205], s[18:19], 0, v[136:137]
	s_mov_b32 m0, s39
	s_nop 0
	global_load_lds_dwordx4 v[204:205], off
	s_waitcnt vmcnt(8)
	s_waitcnt lgkmcnt(0)
	s_barrier
	s_setprio 1
	v_mfma_f32_16x16x32_bf16 v[66:69], v[140:143], v[172:175], v[66:69]
	v_mfma_f32_16x16x32_bf16 v[62:65], v[148:151], v[172:175], v[62:65]
	v_mfma_f32_16x16x32_bf16 v[58:61], v[140:143], v[180:183], v[58:61]
	v_mfma_f32_16x16x32_bf16 v[50:53], v[148:151], v[180:183], v[50:53]
	v_mfma_f32_16x16x32_bf16 v[42:45], v[140:143], v[188:191], v[42:45]
	v_mfma_f32_16x16x32_bf16 v[34:37], v[148:151], v[188:191], v[34:37]
	v_mfma_f32_16x16x32_bf16 v[26:29], v[140:143], v[196:199], v[26:29]
	v_mfma_f32_16x16x32_bf16 v[18:21], v[148:151], v[196:199], v[18:21]
	v_mfma_f32_16x16x32_bf16 v[66:69], v[144:147], v[176:179], v[66:69]
	v_mfma_f32_16x16x32_bf16 v[62:65], v[152:155], v[176:179], v[62:65]
	v_mfma_f32_16x16x32_bf16 v[58:61], v[144:147], v[184:187], v[58:61]
	v_mfma_f32_16x16x32_bf16 v[50:53], v[152:155], v[184:187], v[50:53]
	v_mfma_f32_16x16x32_bf16 v[42:45], v[144:147], v[192:195], v[42:45]
	v_mfma_f32_16x16x32_bf16 v[34:37], v[152:155], v[192:195], v[34:37]
	v_mfma_f32_16x16x32_bf16 v[26:29], v[144:147], v[200:203], v[26:29]
	v_mfma_f32_16x16x32_bf16 v[18:21], v[152:155], v[200:203], v[18:21]
	s_setprio 0
	s_setprio 1
	v_mfma_f32_16x16x32_bf16 v[54:57], v[156:159], v[172:175], v[54:57]
	v_mfma_f32_16x16x32_bf16 v[46:49], v[164:167], v[172:175], v[46:49]
	v_mfma_f32_16x16x32_bf16 v[38:41], v[156:159], v[180:183], v[38:41]
	v_mfma_f32_16x16x32_bf16 v[30:33], v[164:167], v[180:183], v[30:33]
	v_mfma_f32_16x16x32_bf16 v[22:25], v[156:159], v[188:191], v[22:25]
	v_mfma_f32_16x16x32_bf16 v[14:17], v[164:167], v[188:191], v[14:17]
	v_mfma_f32_16x16x32_bf16 v[10:13], v[156:159], v[196:199], v[10:13]
	v_mfma_f32_16x16x32_bf16 v[6:9], v[164:167], v[196:199], v[6:9]
	v_mfma_f32_16x16x32_bf16 v[54:57], v[160:163], v[176:179], v[54:57]
	v_mfma_f32_16x16x32_bf16 v[46:49], v[168:171], v[176:179], v[46:49]
	v_mfma_f32_16x16x32_bf16 v[38:41], v[160:163], v[184:187], v[38:41]
	v_mfma_f32_16x16x32_bf16 v[30:33], v[168:171], v[184:187], v[30:33]
	v_mfma_f32_16x16x32_bf16 v[22:25], v[160:163], v[192:195], v[22:25]
	v_mfma_f32_16x16x32_bf16 v[14:17], v[168:171], v[192:195], v[14:17]
	v_mfma_f32_16x16x32_bf16 v[10:13], v[160:163], v[200:203], v[10:13]
	v_mfma_f32_16x16x32_bf16 v[6:9], v[168:171], v[200:203], v[6:9]
	s_setprio 0
	s_barrier
	s_add_i32 s47, s47, 2
	s_add_u32 s43, s43, 0x100
	s_addc_u32 s44, s44, 0
	s_add_u32 s45, s45, 0x100
	s_addc_u32 s46, s46, 0
	s_cmp_gt_u32 s47, 5
	s_cbranch_scc0 .LBB0_536
	s_lshl_b32 s20, s16, 8
	v_mov_b32_e32 v140, v0
	s_mov_b64 s[18:19], s[84:85]
	s_lshl_b32 s7, s14, 8
	s_ashr_i32 s21, s20, 31
	s_add_i32 s7, s7, s34
	s_lshl_b64 s[20:21], s[20:21], 1
	v_and_b32_e32 v142, 15, v140
	s_add_u32 s18, s18, s20
	v_or_b32_e32 v146, s7, v142
	v_lshrrev_b32_e32 v140, 1, v140
	s_addc_u32 s19, s19, s21
	s_ashr_i32 s9, s7, 11
	v_mov_b32_e32 v143, s7
	s_movk_i32 s7, 0x7cf
	v_and_or_b32 v140, v140, 24, s35
	s_mulk_i32 s9, 0x810
	v_bitop3_b32 v142, v142, s7, v143 bitop3:0xc8
	v_lshlrev_b32_e32 v140, 1, v140
	v_mov_b32_e32 v141, v4
	v_add_u32_e32 v142, s9, v142
	v_lshl_add_u64 v[140:141], s[18:19], 0, v[140:141]
	s_mov_b64 s[18:19], 0x2c900000
	v_ashrrev_i32_e32 v143, 31, v142
	v_lshl_add_u64 v[140:141], v[140:141], 0, s[18:19]
	v_lshlrev_b64 v[144:145], 13, v[142:143]
	v_lshl_add_u64 v[144:145], v[140:141], 0, v[144:145]
	v_cvt_pk_bf16_f32 v130, v130, v131
	v_cvt_pk_bf16_f32 v131, v132, v133
	v_cvt_pk_bf16_f32 v132, v126, v127
	v_cvt_pk_bf16_f32 v133, v128, v129
	global_store_dwordx4 v[144:145], v[130:133], off nt
	v_cvt_pk_bf16_f32 v118, v118, v119
	v_cvt_pk_bf16_f32 v119, v120, v121
	v_cvt_pk_bf16_f32 v120, v110, v111
	v_add_u32_e32 v110, 16, v142
	v_ashrrev_i32_e32 v111, 31, v110
	v_lshlrev_b64 v[110:111], 13, v[110:111]
	v_cvt_pk_bf16_f32 v121, v112, v113
	global_store_dwordx4 v[144:145], v[118:121], off offset:256 nt
	s_movk_i32 s7, 0x810
	s_and_b64 vcc, exec, s[0:1]
	v_lshl_add_u64 v[118:119], v[140:141], 0, v[110:111]
	v_cvt_pk_bf16_f32 v110, v122, v123
	v_cvt_pk_bf16_f32 v111, v124, v125
	v_cvt_pk_bf16_f32 v112, v114, v115
	v_cvt_pk_bf16_f32 v113, v116, v117
	global_store_dwordx4 v[118:119], v[110:113], off nt
	v_cvt_pk_bf16_f32 v102, v102, v103
	v_cvt_pk_bf16_f32 v103, v104, v105
	v_cvt_pk_bf16_f32 v104, v94, v95
	v_add_u32_e32 v94, 32, v142
	v_ashrrev_i32_e32 v95, 31, v94
	v_lshlrev_b64 v[94:95], 13, v[94:95]
	v_cvt_pk_bf16_f32 v105, v96, v97
	global_store_dwordx4 v[118:119], v[102:105], off offset:256 nt
	s_mov_b32 s16, s8
	s_mov_b32 s14, s6
	v_lshl_add_u64 v[102:103], v[140:141], 0, v[94:95]
	v_cvt_pk_bf16_f32 v94, v106, v107
	v_cvt_pk_bf16_f32 v95, v108, v109
	v_cvt_pk_bf16_f32 v96, v98, v99
	v_cvt_pk_bf16_f32 v97, v100, v101
	global_store_dwordx4 v[102:103], v[94:97], off nt
	v_cvt_pk_bf16_f32 v86, v86, v87
	v_cvt_pk_bf16_f32 v87, v88, v89
	v_cvt_pk_bf16_f32 v88, v78, v79
	v_add_u32_e32 v78, 48, v142
	v_ashrrev_i32_e32 v79, 31, v78
	v_lshlrev_b64 v[78:79], 13, v[78:79]
	v_cvt_pk_bf16_f32 v89, v80, v81
	global_store_dwordx4 v[102:103], v[86:89], off offset:256 nt
	s_mov_b64 s[20:21], s[10:11]
	s_mov_b64 s[18:19], s[12:13]
	v_lshl_add_u64 v[86:87], v[140:141], 0, v[78:79]
	v_cvt_pk_bf16_f32 v78, v90, v91
	v_cvt_pk_bf16_f32 v79, v92, v93
	v_cvt_pk_bf16_f32 v80, v82, v83
	v_cvt_pk_bf16_f32 v81, v84, v85
	global_store_dwordx4 v[86:87], v[78:81], off nt
	v_cvt_pk_bf16_f32 v74, v74, v75
	v_cvt_pk_bf16_f32 v75, v76, v77
	v_cvt_pk_bf16_f32 v76, v70, v71
	v_add_u32_e32 v70, 0x80, v146
	v_ashrrev_i32_e32 v71, 11, v70
	v_and_b32_e32 v70, 0x7cf, v70
	v_mad_i32_i24 v70, v71, s7, v70
	v_ashrrev_i32_e32 v71, 31, v70
	v_cvt_pk_bf16_f32 v77, v72, v73
	v_lshlrev_b64 v[72:73], 13, v[70:71]
	global_store_dwordx4 v[86:87], v[74:77], off offset:256 nt
	v_lshl_add_u64 v[72:73], v[140:141], 0, v[72:73]
	v_cvt_pk_bf16_f32 v66, v66, v67
	v_cvt_pk_bf16_f32 v67, v68, v69
	v_cvt_pk_bf16_f32 v68, v62, v63
	v_cvt_pk_bf16_f32 v69, v64, v65
	global_store_dwordx4 v[72:73], v[66:69], off nt
	v_cvt_pk_bf16_f32 v54, v54, v55
	v_cvt_pk_bf16_f32 v55, v56, v57
	v_cvt_pk_bf16_f32 v56, v46, v47
	v_add_u32_e32 v46, 16, v70
	v_ashrrev_i32_e32 v47, 31, v46
	v_lshlrev_b64 v[46:47], 13, v[46:47]
	v_cvt_pk_bf16_f32 v57, v48, v49
	global_store_dwordx4 v[72:73], v[54:57], off offset:256 nt
	s_mov_b32 s51, 0x40c000
	s_mov_b32 s47, 0x120000
	v_lshl_add_u64 v[54:55], v[140:141], 0, v[46:47]
	v_cvt_pk_bf16_f32 v46, v58, v59
	v_cvt_pk_bf16_f32 v47, v60, v61
	v_cvt_pk_bf16_f32 v48, v50, v51
	v_cvt_pk_bf16_f32 v49, v52, v53
	global_store_dwordx4 v[54:55], v[46:49], off nt
	v_cvt_pk_bf16_f32 v38, v38, v39
	v_cvt_pk_bf16_f32 v39, v40, v41
	v_cvt_pk_bf16_f32 v40, v30, v31
	v_add_u32_e32 v30, 32, v70
	v_ashrrev_i32_e32 v31, 31, v30
	v_lshlrev_b64 v[30:31], 13, v[30:31]
	v_cvt_pk_bf16_f32 v41, v32, v33
	global_store_dwordx4 v[54:55], v[38:41], off offset:256 nt
	s_mov_b64 s[48:49], 0x7ffff
	s_nop 0
	v_lshl_add_u64 v[38:39], v[140:141], 0, v[30:31]
	v_cvt_pk_bf16_f32 v30, v42, v43
	v_cvt_pk_bf16_f32 v31, v44, v45
	v_cvt_pk_bf16_f32 v32, v34, v35
	v_cvt_pk_bf16_f32 v33, v36, v37
	global_store_dwordx4 v[38:39], v[30:33], off nt
	v_cvt_pk_bf16_f32 v22, v22, v23
	v_cvt_pk_bf16_f32 v23, v24, v25
	v_cvt_pk_bf16_f32 v24, v14, v15
	v_add_u32_e32 v14, 48, v70
	v_ashrrev_i32_e32 v15, 31, v14
	v_lshlrev_b64 v[14:15], 13, v[14:15]
	v_cvt_pk_bf16_f32 v25, v16, v17
	global_store_dwordx4 v[38:39], v[22:25], off offset:256 nt
	s_nop 1
	v_lshl_add_u64 v[22:23], v[140:141], 0, v[14:15]
	v_cvt_pk_bf16_f32 v14, v26, v27
	v_cvt_pk_bf16_f32 v15, v28, v29
	v_cvt_pk_bf16_f32 v16, v18, v19
	v_cvt_pk_bf16_f32 v17, v20, v21
	global_store_dwordx4 v[22:23], v[14:17], off nt
	v_cvt_pk_bf16_f32 v10, v10, v11
	v_cvt_pk_bf16_f32 v11, v12, v13
	v_cvt_pk_bf16_f32 v12, v6, v7
	v_cvt_pk_bf16_f32 v13, v8, v9
	global_store_dwordx4 v[22:23], v[10:13], off offset:256 nt
	s_cbranch_vccz .LBB0_529
	s_waitcnt vmcnt(0)
	s_cmpk_gt_u32 s28, 0xff
	s_cbranch_scc1 .LBB0_540
	s_barrier

.LBB0_924:
	s_add_u32 s48, s45, 0xffffff80
	s_addc_u32 s49, s46, -1
	s_cmp_eq_u32 s47, 60
	s_cselect_b32 s22, s9, s45
	s_cselect_b32 s23, s7, s46
	s_cselect_b32 s25, s11, s44
	s_cselect_b32 s24, s13, s33
	s_add_u32 s18, s22, 0x80
	s_addc_u32 s19, s23, 0
	s_add_u32 s20, s24, 0x80
	s_addc_u32 s21, s25, 0
	s_add_i32 s50, 0, 0x10000
	s_add_i32 s51, 0, 0x14000
	v_add_u32_e32 v90, s50, v1
	v_add_u32_e32 v162, s51, v1
	ds_read_b128 v[78:81], v90
	ds_read_b128 v[82:85], v90 offset:1024
	ds_read_b128 v[86:89], v90 offset:2048
	ds_read_b128 v[90:93], v90 offset:3072
	ds_read_b128 v[142:145], v162
	ds_read_b128 v[146:149], v162 offset:1024
	ds_read_b128 v[158:161], v162 offset:2048
	ds_read_b128 v[162:165], v162 offset:3072
	s_add_u32 s48, s48, 0x100000
	s_addc_u32 s49, s49, 0
	v_lshl_add_u64 v[198:199], s[48:49], 0, v[2:3]
	s_add_i32 m0, s35, 0xc000
	ds_read_b128 v[166:169], v5
	ds_read_b128 v[170:173], v5 offset:1024
	ds_read_b128 v[174:177], v5 offset:2048
	ds_read_b128 v[178:181], v5 offset:3072
	ds_read_b128 v[182:185], v5 offset:4096
	ds_read_b128 v[186:189], v5 offset:5120
	ds_read_b128 v[190:193], v5 offset:6144
	ds_read_b128 v[194:197], v5 offset:7168
	global_load_lds_dwordx4 v[198:199], off
	v_lshl_add_u64 v[198:199], s[48:49], 0, v[218:219]
	s_add_i32 m0, s35, 0xe000
	s_nop 0
	global_load_lds_dwordx4 v[198:199], off
	s_waitcnt vmcnt(8)
	s_waitcnt lgkmcnt(0)
	s_barrier
	s_setprio 1
	v_mfma_f32_16x16x32_bf16 v[154:157], v[78:81], v[166:169], v[154:157]
	v_mfma_f32_16x16x32_bf16 v[150:153], v[86:89], v[166:169], v[150:153]
	v_mfma_f32_16x16x32_bf16 v[134:137], v[78:81], v[174:177], v[134:137]
	v_mfma_f32_16x16x32_bf16 v[126:129], v[86:89], v[174:177], v[126:129]
	v_mfma_f32_16x16x32_bf16 v[118:121], v[78:81], v[182:185], v[118:121]
	v_mfma_f32_16x16x32_bf16 v[110:113], v[86:89], v[182:185], v[110:113]
	v_mfma_f32_16x16x32_bf16 v[102:105], v[78:81], v[190:193], v[102:105]
	v_mfma_f32_16x16x32_bf16 v[94:97], v[86:89], v[190:193], v[94:97]
	v_mfma_f32_16x16x32_bf16 v[154:157], v[82:85], v[170:173], v[154:157]
	v_mfma_f32_16x16x32_bf16 v[150:153], v[90:93], v[170:173], v[150:153]
	v_mfma_f32_16x16x32_bf16 v[134:137], v[82:85], v[178:181], v[134:137]
	v_mfma_f32_16x16x32_bf16 v[126:129], v[90:93], v[178:181], v[126:129]
	v_mfma_f32_16x16x32_bf16 v[118:121], v[82:85], v[186:189], v[118:121]
	v_mfma_f32_16x16x32_bf16 v[110:113], v[90:93], v[186:189], v[110:113]
	v_mfma_f32_16x16x32_bf16 v[102:105], v[82:85], v[194:197], v[102:105]
	v_mfma_f32_16x16x32_bf16 v[94:97], v[90:93], v[194:197], v[94:97]
	s_setprio 0
	s_setprio 1
	v_mfma_f32_16x16x32_bf16 v[138:141], v[142:145], v[166:169], v[138:141]
	v_mfma_f32_16x16x32_bf16 v[130:133], v[158:161], v[166:169], v[130:133]
	v_mfma_f32_16x16x32_bf16 v[122:125], v[142:145], v[174:177], v[122:125]
	v_mfma_f32_16x16x32_bf16 v[114:117], v[158:161], v[174:177], v[114:117]
	v_mfma_f32_16x16x32_bf16 v[106:109], v[142:145], v[182:185], v[106:109]
	v_mfma_f32_16x16x32_bf16 v[98:101], v[158:161], v[182:185], v[98:101]
	v_mfma_f32_16x16x32_bf16 v[74:77], v[142:145], v[190:193], v[74:77]
	v_mfma_f32_16x16x32_bf16 v[70:73], v[158:161], v[190:193], v[70:73]
	v_mfma_f32_16x16x32_bf16 v[138:141], v[146:149], v[170:173], v[138:141]
	v_mfma_f32_16x16x32_bf16 v[130:133], v[162:165], v[170:173], v[130:133]
	v_mfma_f32_16x16x32_bf16 v[122:125], v[146:149], v[178:181], v[122:125]
	v_mfma_f32_16x16x32_bf16 v[114:117], v[162:165], v[178:181], v[114:117]
	v_mfma_f32_16x16x32_bf16 v[106:109], v[146:149], v[186:189], v[106:109]
	v_mfma_f32_16x16x32_bf16 v[98:101], v[162:165], v[186:189], v[98:101]
	v_mfma_f32_16x16x32_bf16 v[74:77], v[146:149], v[194:197], v[74:77]
	v_mfma_f32_16x16x32_bf16 v[70:73], v[162:165], v[194:197], v[70:73]
	s_setprio 0
	s_barrier
	s_add_i32 s48, s50, s29
	v_lshl_add_u64 v[198:199], s[24:25], 0, v[216:217]
	s_mov_b32 m0, s48
	ds_read_b128 v[166:169], v5 offset:16384
	ds_read_b128 v[170:173], v5 offset:17408
	ds_read_b128 v[174:177], v5 offset:18432
	ds_read_b128 v[178:181], v5 offset:19456
	ds_read_b128 v[182:185], v5 offset:20480
	ds_read_b128 v[186:189], v5 offset:21504
	ds_read_b128 v[190:193], v5 offset:22528
	ds_read_b128 v[194:197], v5 offset:23552
	global_load_lds_dwordx4 v[198:199], off
	s_add_i32 m0, s48, 0x2000
	v_lshl_add_u64 v[198:199], s[24:25], 0, v[220:221]
	s_add_u32 s24, s24, 0x100000
	s_addc_u32 s25, s25, 0
	s_add_i32 s48, s51, s29
	global_load_lds_dwordx4 v[198:199], off
	v_lshl_add_u64 v[198:199], s[24:25], 0, v[216:217]
	s_mov_b32 m0, s48
	s_nop 0
	global_load_lds_dwordx4 v[198:199], off
	v_lshl_add_u64 v[198:199], s[24:25], 0, v[220:221]
	s_add_i32 m0, s48, 0x2000
	s_nop 0
	global_load_lds_dwordx4 v[198:199], off
	v_lshl_add_u64 v[198:199], s[22:23], 0, v[2:3]
	s_mov_b32 m0, s35
	s_nop 0
	global_load_lds_dwordx4 v[198:199], off
	v_lshl_add_u64 v[198:199], s[22:23], 0, v[218:219]
	s_mov_b32 m0, s36
	s_nop 0
	global_load_lds_dwordx4 v[198:199], off
	s_waitcnt vmcnt(8)
	s_waitcnt lgkmcnt(0)
	s_barrier
	s_setprio 1
	v_mfma_f32_16x16x32_bf16 v[66:69], v[78:81], v[166:169], v[66:69]
	v_mfma_f32_16x16x32_bf16 v[62:65], v[86:89], v[166:169], v[62:65]
	v_mfma_f32_16x16x32_bf16 v[54:57], v[78:81], v[174:177], v[54:57]
	v_mfma_f32_16x16x32_bf16 v[46:49], v[86:89], v[174:177], v[46:49]
	v_mfma_f32_16x16x32_bf16 v[38:41], v[78:81], v[182:185], v[38:41]
	v_mfma_f32_16x16x32_bf16 v[30:33], v[86:89], v[182:185], v[30:33]
	v_mfma_f32_16x16x32_bf16 v[22:25], v[78:81], v[190:193], v[22:25]
	v_mfma_f32_16x16x32_bf16 v[14:17], v[86:89], v[190:193], v[14:17]
	v_mfma_f32_16x16x32_bf16 v[66:69], v[82:85], v[170:173], v[66:69]
	v_mfma_f32_16x16x32_bf16 v[62:65], v[90:93], v[170:173], v[62:65]
	v_mfma_f32_16x16x32_bf16 v[54:57], v[82:85], v[178:181], v[54:57]
	v_mfma_f32_16x16x32_bf16 v[46:49], v[90:93], v[178:181], v[46:49]
	v_mfma_f32_16x16x32_bf16 v[38:41], v[82:85], v[186:189], v[38:41]
	v_mfma_f32_16x16x32_bf16 v[30:33], v[90:93], v[186:189], v[30:33]
	v_mfma_f32_16x16x32_bf16 v[22:25], v[82:85], v[194:197], v[22:25]
	v_mfma_f32_16x16x32_bf16 v[14:17], v[90:93], v[194:197], v[14:17]
	s_setprio 0
	s_setprio 1
	v_mfma_f32_16x16x32_bf16 v[58:61], v[142:145], v[166:169], v[58:61]
	v_mfma_f32_16x16x32_bf16 v[50:53], v[158:161], v[166:169], v[50:53]
	v_mfma_f32_16x16x32_bf16 v[42:45], v[142:145], v[174:177], v[42:45]
	v_mfma_f32_16x16x32_bf16 v[34:37], v[158:161], v[174:177], v[34:37]
	v_mfma_f32_16x16x32_bf16 v[26:29], v[142:145], v[182:185], v[26:29]
	v_mfma_f32_16x16x32_bf16 v[18:21], v[158:161], v[182:185], v[18:21]
	v_mfma_f32_16x16x32_bf16 v[10:13], v[142:145], v[190:193], v[10:13]
	v_mfma_f32_16x16x32_bf16 v[6:9], v[158:161], v[190:193], v[6:9]
	v_mfma_f32_16x16x32_bf16 v[58:61], v[146:149], v[170:173], v[58:61]
	v_mfma_f32_16x16x32_bf16 v[50:53], v[162:165], v[170:173], v[50:53]
	v_mfma_f32_16x16x32_bf16 v[42:45], v[146:149], v[178:181], v[42:45]
	v_mfma_f32_16x16x32_bf16 v[34:37], v[162:165], v[178:181], v[34:37]
	v_mfma_f32_16x16x32_bf16 v[26:29], v[146:149], v[186:189], v[26:29]
	v_mfma_f32_16x16x32_bf16 v[18:21], v[162:165], v[186:189], v[18:21]
	v_mfma_f32_16x16x32_bf16 v[10:13], v[146:149], v[194:197], v[10:13]
	v_mfma_f32_16x16x32_bf16 v[6:9], v[162:165], v[194:197], v[6:9]
	s_setprio 0
	s_barrier
	s_add_i32 s24, 0, 0x18000
	s_add_i32 s25, 0, 0x1c000
	v_add_u32_e32 v90, s24, v1
	v_add_u32_e32 v162, s25, v1
	ds_read_b128 v[78:81], v90
	ds_read_b128 v[82:85], v90 offset:1024
	ds_read_b128 v[86:89], v90 offset:2048
	ds_read_b128 v[90:93], v90 offset:3072
	ds_read_b128 v[142:145], v162
	ds_read_b128 v[146:149], v162 offset:1024
	ds_read_b128 v[158:161], v162 offset:2048
	ds_read_b128 v[162:165], v162 offset:3072
	s_add_u32 s22, s22, 0x100000
	s_addc_u32 s23, s23, 0
	s_mov_b32 m0, s37
	v_lshl_add_u64 v[198:199], s[22:23], 0, v[2:3]
	ds_read_b128 v[166:169], v5 offset:32768
	ds_read_b128 v[170:173], v5 offset:33792
	ds_read_b128 v[174:177], v5 offset:34816
	ds_read_b128 v[178:181], v5 offset:35840
	ds_read_b128 v[182:185], v5 offset:36864
	ds_read_b128 v[186:189], v5 offset:37888
	ds_read_b128 v[190:193], v5 offset:38912
	ds_read_b128 v[194:197], v5 offset:39936
	global_load_lds_dwordx4 v[198:199], off
	v_lshl_add_u64 v[198:199], s[22:23], 0, v[218:219]
	s_mov_b32 m0, s38
	s_nop 0
	global_load_lds_dwordx4 v[198:199], off
	s_waitcnt vmcnt(8)
	s_waitcnt lgkmcnt(0)
	s_barrier
	s_setprio 1
	v_mfma_f32_16x16x32_bf16 v[154:157], v[78:81], v[166:169], v[154:157]
	v_mfma_f32_16x16x32_bf16 v[150:153], v[86:89], v[166:169], v[150:153]
	v_mfma_f32_16x16x32_bf16 v[134:137], v[78:81], v[174:177], v[134:137]
	v_mfma_f32_16x16x32_bf16 v[126:129], v[86:89], v[174:177], v[126:129]
	v_mfma_f32_16x16x32_bf16 v[118:121], v[78:81], v[182:185], v[118:121]
	v_mfma_f32_16x16x32_bf16 v[110:113], v[86:89], v[182:185], v[110:113]
	v_mfma_f32_16x16x32_bf16 v[102:105], v[78:81], v[190:193], v[102:105]
	v_mfma_f32_16x16x32_bf16 v[94:97], v[86:89], v[190:193], v[94:97]
	v_mfma_f32_16x16x32_bf16 v[154:157], v[82:85], v[170:173], v[154:157]
	v_mfma_f32_16x16x32_bf16 v[150:153], v[90:93], v[170:173], v[150:153]
	v_mfma_f32_16x16x32_bf16 v[134:137], v[82:85], v[178:181], v[134:137]
	v_mfma_f32_16x16x32_bf16 v[126:129], v[90:93], v[178:181], v[126:129]
	v_mfma_f32_16x16x32_bf16 v[118:121], v[82:85], v[186:189], v[118:121]
	v_mfma_f32_16x16x32_bf16 v[110:113], v[90:93], v[186:189], v[110:113]
	v_mfma_f32_16x16x32_bf16 v[102:105], v[82:85], v[194:197], v[102:105]
	v_mfma_f32_16x16x32_bf16 v[94:97], v[90:93], v[194:197], v[94:97]
	s_setprio 0
	s_setprio 1
	v_mfma_f32_16x16x32_bf16 v[138:141], v[142:145], v[166:169], v[138:141]
	v_mfma_f32_16x16x32_bf16 v[130:133], v[158:161], v[166:169], v[130:133]
	v_mfma_f32_16x16x32_bf16 v[122:125], v[142:145], v[174:177], v[122:125]
	v_mfma_f32_16x16x32_bf16 v[114:117], v[158:161], v[174:177], v[114:117]
	v_mfma_f32_16x16x32_bf16 v[106:109], v[142:145], v[182:185], v[106:109]
	v_mfma_f32_16x16x32_bf16 v[98:101], v[158:161], v[182:185], v[98:101]
	v_mfma_f32_16x16x32_bf16 v[74:77], v[142:145], v[190:193], v[74:77]
	v_mfma_f32_16x16x32_bf16 v[70:73], v[158:161], v[190:193], v[70:73]
	v_mfma_f32_16x16x32_bf16 v[138:141], v[146:149], v[170:173], v[138:141]
	v_mfma_f32_16x16x32_bf16 v[130:133], v[162:165], v[170:173], v[130:133]
	v_mfma_f32_16x16x32_bf16 v[122:125], v[146:149], v[178:181], v[122:125]
	v_mfma_f32_16x16x32_bf16 v[114:117], v[162:165], v[178:181], v[114:117]
	v_mfma_f32_16x16x32_bf16 v[106:109], v[146:149], v[186:189], v[106:109]
	v_mfma_f32_16x16x32_bf16 v[98:101], v[162:165], v[186:189], v[98:101]
	v_mfma_f32_16x16x32_bf16 v[74:77], v[146:149], v[194:197], v[74:77]
	v_mfma_f32_16x16x32_bf16 v[70:73], v[162:165], v[194:197], v[70:73]
	s_setprio 0
	s_barrier
	s_add_i32 s22, s24, s29
	v_lshl_add_u64 v[198:199], s[20:21], 0, v[216:217]
	s_mov_b32 m0, s22
	ds_read_b128 v[166:169], v5 offset:49152
	ds_read_b128 v[170:173], v5 offset:50176
	ds_read_b128 v[174:177], v5 offset:51200
	ds_read_b128 v[178:181], v5 offset:52224
	ds_read_b128 v[182:185], v5 offset:53248
	ds_read_b128 v[186:189], v5 offset:54272
	ds_read_b128 v[190:193], v5 offset:55296
	ds_read_b128 v[194:197], v5 offset:56320
	global_load_lds_dwordx4 v[198:199], off
	s_add_i32 m0, s22, 0x2000
	v_lshl_add_u64 v[198:199], s[20:21], 0, v[220:221]
	s_add_u32 s20, s20, 0x100000
	s_addc_u32 s21, s21, 0
	s_add_i32 s22, s25, s29
	global_load_lds_dwordx4 v[198:199], off
	v_lshl_add_u64 v[198:199], s[20:21], 0, v[216:217]
	s_mov_b32 m0, s22
	s_nop 0
	global_load_lds_dwordx4 v[198:199], off
	v_lshl_add_u64 v[198:199], s[20:21], 0, v[220:221]
	s_add_i32 m0, s22, 0x2000
	s_nop 0
	global_load_lds_dwordx4 v[198:199], off
	v_lshl_add_u64 v[198:199], s[18:19], 0, v[2:3]
	s_mov_b32 m0, s41
	s_nop 0
	global_load_lds_dwordx4 v[198:199], off
	v_lshl_add_u64 v[198:199], s[18:19], 0, v[218:219]
	s_mov_b32 m0, s42
	s_nop 0
	global_load_lds_dwordx4 v[198:199], off
	s_waitcnt vmcnt(8)
	s_waitcnt lgkmcnt(0)
	s_barrier
	s_setprio 1
	v_mfma_f32_16x16x32_bf16 v[66:69], v[78:81], v[166:169], v[66:69]
	v_mfma_f32_16x16x32_bf16 v[62:65], v[86:89], v[166:169], v[62:65]
	v_mfma_f32_16x16x32_bf16 v[54:57], v[78:81], v[174:177], v[54:57]
	v_mfma_f32_16x16x32_bf16 v[46:49], v[86:89], v[174:177], v[46:49]
	v_mfma_f32_16x16x32_bf16 v[38:41], v[78:81], v[182:185], v[38:41]
	v_mfma_f32_16x16x32_bf16 v[30:33], v[86:89], v[182:185], v[30:33]
	v_mfma_f32_16x16x32_bf16 v[22:25], v[78:81], v[190:193], v[22:25]
	v_mfma_f32_16x16x32_bf16 v[14:17], v[86:89], v[190:193], v[14:17]
	v_mfma_f32_16x16x32_bf16 v[66:69], v[82:85], v[170:173], v[66:69]
	v_mfma_f32_16x16x32_bf16 v[62:65], v[90:93], v[170:173], v[62:65]
	v_mfma_f32_16x16x32_bf16 v[54:57], v[82:85], v[178:181], v[54:57]
	v_mfma_f32_16x16x32_bf16 v[46:49], v[90:93], v[178:181], v[46:49]
	v_mfma_f32_16x16x32_bf16 v[38:41], v[82:85], v[186:189], v[38:41]
	v_mfma_f32_16x16x32_bf16 v[30:33], v[90:93], v[186:189], v[30:33]
	v_mfma_f32_16x16x32_bf16 v[22:25], v[82:85], v[194:197], v[22:25]
	v_mfma_f32_16x16x32_bf16 v[14:17], v[90:93], v[194:197], v[14:17]
	s_setprio 0
	s_setprio 1
	v_mfma_f32_16x16x32_bf16 v[58:61], v[142:145], v[166:169], v[58:61]
	v_mfma_f32_16x16x32_bf16 v[50:53], v[158:161], v[166:169], v[50:53]
	v_mfma_f32_16x16x32_bf16 v[42:45], v[142:145], v[174:177], v[42:45]
	v_mfma_f32_16x16x32_bf16 v[34:37], v[158:161], v[174:177], v[34:37]
	v_mfma_f32_16x16x32_bf16 v[26:29], v[142:145], v[182:185], v[26:29]
	v_mfma_f32_16x16x32_bf16 v[18:21], v[158:161], v[182:185], v[18:21]
	v_mfma_f32_16x16x32_bf16 v[10:13], v[142:145], v[190:193], v[10:13]
	v_mfma_f32_16x16x32_bf16 v[6:9], v[158:161], v[190:193], v[6:9]
	v_mfma_f32_16x16x32_bf16 v[58:61], v[146:149], v[170:173], v[58:61]
	v_mfma_f32_16x16x32_bf16 v[50:53], v[162:165], v[170:173], v[50:53]
	v_mfma_f32_16x16x32_bf16 v[42:45], v[146:149], v[178:181], v[42:45]
	v_mfma_f32_16x16x32_bf16 v[34:37], v[162:165], v[178:181], v[34:37]
	v_mfma_f32_16x16x32_bf16 v[26:29], v[146:149], v[186:189], v[26:29]
	v_mfma_f32_16x16x32_bf16 v[18:21], v[162:165], v[186:189], v[18:21]
	v_mfma_f32_16x16x32_bf16 v[10:13], v[146:149], v[194:197], v[10:13]
	v_mfma_f32_16x16x32_bf16 v[6:9], v[162:165], v[194:197], v[6:9]
	s_setprio 0
	s_barrier
	s_add_i32 s47, s47, 2
	s_add_u32 s33, s33, 0x100
	s_addc_u32 s44, s44, 0
	s_add_u32 s45, s45, 0x100
	s_addc_u32 s46, s46, 0
	s_cmp_gt_u32 s47, 61
	s_cbranch_scc0 .LBB0_924
	v_mov_b32_e32 v142, v0
	s_mov_b64 s[20:21], s[84:85]
	s_add_u32 s7, s20, 0x4179c000
	v_readlane_b32 s18, v254, 26
	s_addc_u32 s9, s21, 0
	v_readlane_b32 s19, v254, 27
	v_readlane_b32 s44, v253, 35
	s_and_b64 s[18:19], s[18:19], exec
	v_readlane_b32 s45, v253, 36
	v_bfe_u32 v144, v142, 4, 2
	s_cselect_b32 s23, s9, s45
	s_cselect_b32 s22, s7, s44
	s_cselect_b32 s19, s83, s9
	s_cselect_b32 s18, s82, s7
	s_lshl_b32 s7, s8, 8
	s_lshl_b32 s6, s6, 8
	v_lshl_or_b32 v78, v144, 3, s7
	s_add_i32 s6, s6, s39
	v_or_b32_e32 v226, s40, v78
	v_ashrrev_i32_e32 v227, 31, v226
	v_readlane_b32 s8, v254, 9
	v_and_or_b32 v230, v142, 15, s6
	v_lshlrev_b64 v[244:245], 2, v[226:227]
	v_readlane_b32 s9, v254, 10
	v_lshl_add_u64 v[142:143], v[226:227], 1, s[20:21]
	s_mov_b64 s[6:7], 0x10f80000
	v_ashrrev_i32_e32 v231, 31, v230
	v_or_b32_e32 v240, 16, v230
	v_lshl_add_u64 v[82:83], s[8:9], 0, v[244:245]
	v_lshl_add_u64 v[228:229], s[22:23], 0, v[244:245]
	v_lshl_add_u64 v[224:225], v[142:143], 0, s[6:7]
	v_lshl_add_u64 v[142:143], v[230:231], 2, s[20:21]
	s_mov_b64 s[8:9], 0x18400
	v_lshlrev_b64 v[248:249], 14, v[230:231]
	v_ashrrev_i32_e32 v241, 31, v240
	v_or_b32_e32 v236, 32, v230
	v_or_b32_e32 v232, 48, v230
	v_lshl_add_u64 v[222:223], v[142:143], 0, s[8:9]
	v_lshl_add_u64 v[142:143], v[228:229], 0, v[248:249]
	v_lshlrev_b64 v[242:243], 14, v[240:241]
	v_ashrrev_i32_e32 v237, 31, v236
	v_ashrrev_i32_e32 v233, 31, v232
	global_load_dwordx4 v[86:89], v[82:83], off offset:16
	global_load_dwordx4 v[90:93], v[82:83], off
	global_load_dwordx4 v[78:81], v[82:83], off offset:528
	s_nop 0
	global_load_dwordx4 v[82:85], v[82:83], off offset:512
	s_nop 0
	global_load_dwordx4 v[206:209], v[142:143], off offset:16
	global_load_dwordx4 v[210:213], v[142:143], off
	global_load_dwordx4 v[198:201], v[142:143], off offset:528
	global_load_dwordx4 v[202:205], v[142:143], off offset:512
	v_lshl_add_u64 v[142:143], v[228:229], 0, v[242:243]
	v_lshlrev_b64 v[238:239], 14, v[236:237]
	v_lshlrev_b64 v[234:235], 14, v[232:233]
	global_load_dwordx4 v[190:193], v[142:143], off offset:16
	global_load_dwordx4 v[194:197], v[142:143], off
	global_load_dwordx4 v[182:185], v[142:143], off offset:528
	global_load_dwordx4 v[186:189], v[142:143], off offset:512
	v_lshl_add_u64 v[142:143], v[228:229], 0, v[238:239]
	v_lshl_add_u64 v[146:147], v[228:229], 0, v[234:235]
	v_cmp_eq_u32_e64 s[6:7], 0, v144
	global_load_dwordx4 v[174:177], v[142:143], off offset:16
	global_load_dwordx4 v[178:181], v[142:143], off
	global_load_dwordx4 v[166:169], v[142:143], off offset:528
	global_load_dwordx4 v[170:173], v[142:143], off offset:512
	global_load_dwordx4 v[158:161], v[146:147], off offset:16
	global_load_dwordx4 v[162:165], v[146:147], off
	s_nop 0
	global_load_dwordx4 v[142:145], v[146:147], off offset:528
	s_nop 0
	global_load_dwordx4 v[146:149], v[146:147], off offset:512
	v_lshl_add_u64 v[248:249], s[18:19], 0, v[248:249]
	v_lshl_add_u64 v[244:245], v[248:249], 0, v[244:245]
	s_mov_b64 s[20:21], -1
	s_andn2_b64 vcc, exec, s[60:61]
	v_readlane_b32 s46, v253, 37
	v_readlane_b32 s47, v253, 38
	v_readlane_b32 s48, v253, 39
	v_readlane_b32 s49, v253, 40
	v_readlane_b32 s50, v253, 41
	v_readlane_b32 s51, v253, 42
	v_readlane_b32 s52, v253, 43
	v_readlane_b32 s53, v253, 44
	v_readlane_b32 s54, v253, 45
	v_readlane_b32 s55, v253, 46
	v_readlane_b32 s56, v253, 47
	v_readlane_b32 s57, v253, 48
	v_readlane_b32 s58, v253, 49
	v_readlane_b32 s59, v253, 50
	s_waitcnt vmcnt(0)
	v_pk_add_f32 v[206:207], v[150:151], v[206:207]
	v_cndmask_b32_e64 v150, 0, 1, s[60:61]
	v_pk_add_f32 v[212:213], v[156:157], v[212:213]
	v_pk_add_f32 v[210:211], v[154:155], v[210:211]
	v_pk_add_f32 v[208:209], v[152:153], v[208:209]
	v_cmp_ne_u32_e64 s[8:9], 1, v150
	v_pk_add_f32 v[150:151], v[138:139], v[202:203]
	v_pk_add_f32 v[154:155], v[130:131], v[198:199]
	global_store_dwordx4 v[244:245], v[210:213], off
	global_store_dwordx4 v[244:245], v[206:209], off offset:16
	s_cbranch_vccnz .LBB0_929
	v_mul_f32_e32 v138, v211, v211
	v_mul_f32_e32 v139, v213, v213
	v_fmac_f32_e32 v138, v210, v210
	v_fmac_f32_e32 v139, v212, v212
	v_add_f32_e32 v138, v138, v139
	v_mul_f32_e32 v139, v207, v207
	v_fmac_f32_e32 v139, v206, v206
	v_add_f32_e32 v138, v138, v139
	v_mul_f32_e32 v139, v209, v209
	v_lshlrev_b64 v[130:131], 12, v[230:231]
	v_fmac_f32_e32 v139, v208, v208
	v_pk_mul_f32 v[152:153], v[90:91], v[210:211]
	v_pk_mul_f32 v[156:157], v[88:89], v[208:209]
	v_lshl_add_u64 v[130:131], v[130:131], 1, v[224:225]
	v_add_f32_e32 v231, v139, v138
	v_pk_mul_f32 v[138:139], v[92:93], v[212:213]
	v_pk_mul_f32 v[198:199], v[86:87], v[206:207]
	v_cvt_pk_bf16_f32 v206, v152, v153
	v_cvt_pk_bf16_f32 v207, v138, v139
	v_pk_add_f32 v[152:153], v[140:141], v[204:205]
	v_cvt_pk_bf16_f32 v208, v198, v199
	v_cvt_pk_bf16_f32 v209, v156, v157
	v_pk_add_f32 v[156:157], v[132:133], v[200:201]
	global_store_dwordx4 v[130:131], v[206:209], off
	global_store_dwordx4 v[244:245], v[150:153], off offset:512
	global_store_dwordx4 v[244:245], v[154:157], off offset:528
	v_pk_mul_f32 v[202:203], v[80:81], v[156:157]
	v_pk_mul_f32 v[138:139], v[84:85], v[152:153]
	v_mul_f32_e32 v157, v157, v157
	v_fmac_f32_e32 v157, v156, v156
	v_mul_f32_e32 v156, v151, v151
	v_mul_f32_e32 v153, v153, v153
	v_fmac_f32_e32 v156, v150, v150
	v_fmac_f32_e32 v153, v152, v152
	v_add_f32_e32 v152, v156, v153
	v_mul_f32_e32 v153, v155, v155
	v_fmac_f32_e32 v153, v154, v154
	v_add_f32_e32 v152, v152, v153
	v_add_f32_e32 v152, v157, v152
	v_add_f32_e32 v152, v231, v152
	ds_swizzle_b32 v153, v152 offset:swizzle(SWAP,16)
	v_pk_mul_f32 v[208:209], v[78:79], v[154:155]
	v_pk_mul_f32 v[198:199], v[82:83], v[150:151]
	s_nop 0
	v_cvt_pk_bf16_f32 v206, v198, v199
	v_cvt_pk_bf16_f32 v207, v138, v139
	v_cvt_pk_bf16_f32 v208, v208, v209
	v_cvt_pk_bf16_f32 v209, v202, v203
	global_store_dwordx4 v[130:131], v[206:209], off offset:256
	s_waitcnt lgkmcnt(0)
	v_add_f32_e32 v130, v152, v153
	v_mov_b32_e32 v131, v130
	s_nop 1
	v_permlane32_swap_b32_e32 v130, v131
	s_and_saveexec_b64 s[20:21], s[6:7]
	s_cbranch_execz .LBB0_928
	v_add_f32_e32 v130, v130, v131
	global_atomic_add_f32 v[222:223], v130, off
